# GEMM K loops: duplicate s_waitcnt lgkmcnt(0) behind the hand-off barrier removed (32 sites)
# speedup vs baseline: 1.0090x; 1.0012x over previous
;     __device__ __forceinline__ const char* a_ptr(const Unit& u) const { return (const char*)(u.sel ? A1 : A0) + ((size_t)u.pm * BM * lda + (size_t)(u.pn >> a_grp_shift) * a_grp_cols) * 2; }
;     __device__ __forceinline__ const char* b_ptr(const Unit& u) const { return (const char*)(u.sel ? B1 : B0) + (size_t)u.pn * BM * ldb * 2; }
;     __device__ bool next(int i, Unit& u) const { if (!S.next(i >> 1, u)) return false; u.sel = i & 1; return true; }
; #define PG8_STAGE(bufoff, gbase, voff) do { _Pragma("unroll") for (int _i = 0; _i < 2; ++_i) \
;         __builtin_amdgcn_global_load_lds((const unsigned*)((const char*)(gbase) + (voff)[_i]), (LAS unsigned*)(lds + (bufoff) + ldsw + _i * 8192), 16, 0, 0); } while (0)
; #define PG8_LDA(dst, b, h) do { _Pragma("unroll") for (int m = 0; m < 4; ++m) _Pragma("unroll") for (int k = 0; k < 2; ++k) dst[m][k] = *(const LAS bf16x8*)(lds + PG8_SA(b, h) + aoff + m * 2048 + k * 1024); } while (0)
; #define PG8_LDB(dst, b, h) do { _Pragma("unroll") for (int n = 0; n < 2; ++n) _Pragma("unroll") for (int k = 0; k < 2; ++k) dst[n][k] = *(const LAS bf16x8*)(lds + PG8_SB(b, h) + boff + n * 2048 + k * 1024); } while (0)
; template <class Epi, class Sched, bool ALIGN_EPI>
; __device__ __forceinline__ void gemm_phase(LAS unsigned char* lds, const Gemm g, const Sched& S, const Epi& E) {
;     ...
;         const bool has_next = S.next(ui + 1, nxt);
;         const char* nA = has_next ? g.a_ptr(nxt) : cA; const char* nB = has_next ? g.b_ptr(nxt) : cB;
;         for (int t = 0; t < nt; t += 2) {
;             const bool last = (t == nt - 2);
;             const char* a1 = cA + (size_t)(t + 1) * kstep;
;             const char* a2 = last ? nA : cA + (size_t)(t + 2) * kstep; const char* b2 = last ? nB : cB + (size_t)(t + 2) * kstep;
;             const char* a3 = a2 + kstep; const char* b3 = b2 + kstep;
;             PG8_LDB(B0, 0, 0); PG8_LDB(B1, 0, 1); PG8_SCHED; PG8_LDA(At, 0, 0); PG8_STAGE(PG8_SA(1, 1), a1 + hstepA, voffA);
;             PG8_WAIT_V(8); PG8_WAIT_L(0); PG8_BAR; PG8_MMA(0, 0, At, B0); PG8_MMA(0, 1, At, B1); PG8_BAR; PG8_SCHED;
;             PG8_LDA(At, 0, 1); PG8_STAGE(PG8_SB(0, 0), b2, voffB); PG8_STAGE(PG8_SB(0, 1), b2 + hstepB, voffB); PG8_STAGE(PG8_SA(0, 0), a2, voffA);
;             PG8_WAIT_V(8); PG8_WAIT_L(0); PG8_BAR; PG8_MMA(1, 0, At, B0); PG8_MMA(1, 1, At, B1); PG8_BAR; PG8_SCHED;
.LBB0_157:
	ds_read_b128 v[128:131], v145
	ds_read_b128 v[156:159], v145 offset:1024
	ds_read_b128 v[166:169], v145 offset:2048
	ds_read_b128 v[170:173], v145 offset:3072
	ds_read_b128 v[174:177], v163
	ds_read_b128 v[178:181], v163 offset:1024
	ds_read_b128 v[182:185], v163 offset:2048
	ds_read_b128 v[186:189], v163 offset:3072
	s_add_i32 s55, s26, 2
	s_add_u32 s40, s12, 0x80
	s_addc_u32 s27, s13, 0
	s_cmp_eq_u32 s68, s26
	s_cselect_b32 s26, s7, s40
	s_cselect_b32 s27, s5, s27
	s_cselect_b32 s41, s11, s50
	s_cselect_b32 s40, s30, s31
	v_lshl_add_u64 v[224:225], s[12:13], 0, v[148:149]
	s_add_i32 m0, s65, 0xc000
	ds_read_b128 v[190:193], v164
	ds_read_b128 v[194:197], v164 offset:1024
	ds_read_b128 v[198:201], v164 offset:2048
	ds_read_b128 v[202:205], v164 offset:3072
	ds_read_b128 v[206:209], v164 offset:4096
	ds_read_b128 v[210:213], v164 offset:5120
	ds_read_b128 v[214:217], v164 offset:6144
	ds_read_b128 v[220:223], v164 offset:7168
	global_load_lds_dwordx4 v[224:225], off
	v_lshl_add_u64 v[224:225], s[12:13], 0, v[150:151]
	s_add_i32 m0, s65, 0xe000
	s_nop 0
	global_load_lds_dwordx4 v[224:225], off
	s_waitcnt vmcnt(8)
	s_waitcnt lgkmcnt(0)
	s_barrier
	s_setprio 1
	v_mfma_f32_16x16x32_bf16 v[124:127], v[128:131], v[190:193], v[124:127]
	v_mfma_f32_16x16x32_bf16 v[120:123], v[166:169], v[190:193], v[120:123]
	v_mfma_f32_16x16x32_bf16 v[108:111], v[128:131], v[198:201], v[108:111]
	v_mfma_f32_16x16x32_bf16 v[104:107], v[166:169], v[198:201], v[104:107]
	v_mfma_f32_16x16x32_bf16 v[92:95], v[128:131], v[206:209], v[92:95]
	v_mfma_f32_16x16x32_bf16 v[88:91], v[166:169], v[206:209], v[88:91]
	v_mfma_f32_16x16x32_bf16 v[76:79], v[128:131], v[214:217], v[76:79]
	v_mfma_f32_16x16x32_bf16 v[72:75], v[166:169], v[214:217], v[72:75]
	v_mfma_f32_16x16x32_bf16 v[124:127], v[156:159], v[194:197], v[124:127]
	v_mfma_f32_16x16x32_bf16 v[120:123], v[170:173], v[194:197], v[120:123]
	v_mfma_f32_16x16x32_bf16 v[108:111], v[156:159], v[202:205], v[108:111]
	v_mfma_f32_16x16x32_bf16 v[104:107], v[170:173], v[202:205], v[104:107]
	v_mfma_f32_16x16x32_bf16 v[92:95], v[156:159], v[210:213], v[92:95]
	v_mfma_f32_16x16x32_bf16 v[88:91], v[170:173], v[210:213], v[88:91]
	v_mfma_f32_16x16x32_bf16 v[76:79], v[156:159], v[220:223], v[76:79]
	v_mfma_f32_16x16x32_bf16 v[72:75], v[170:173], v[220:223], v[72:75]
	s_setprio 0
	s_setprio 1
	v_mfma_f32_16x16x32_bf16 v[116:119], v[174:177], v[190:193], v[116:119]
	v_mfma_f32_16x16x32_bf16 v[112:115], v[182:185], v[190:193], v[112:115]
	v_mfma_f32_16x16x32_bf16 v[100:103], v[174:177], v[198:201], v[100:103]
	v_mfma_f32_16x16x32_bf16 v[96:99], v[182:185], v[198:201], v[96:99]
	v_mfma_f32_16x16x32_bf16 v[84:87], v[174:177], v[206:209], v[84:87]
	v_mfma_f32_16x16x32_bf16 v[80:83], v[182:185], v[206:209], v[80:83]
	v_mfma_f32_16x16x32_bf16 v[68:71], v[174:177], v[214:217], v[68:71]
	v_mfma_f32_16x16x32_bf16 v[64:67], v[182:185], v[214:217], v[64:67]
	v_mfma_f32_16x16x32_bf16 v[116:119], v[178:181], v[194:197], v[116:119]
	v_mfma_f32_16x16x32_bf16 v[112:115], v[186:189], v[194:197], v[112:115]
	v_mfma_f32_16x16x32_bf16 v[100:103], v[178:181], v[202:205], v[100:103]
	v_mfma_f32_16x16x32_bf16 v[96:99], v[186:189], v[202:205], v[96:99]
	v_mfma_f32_16x16x32_bf16 v[84:87], v[178:181], v[210:213], v[84:87]
	v_mfma_f32_16x16x32_bf16 v[80:83], v[186:189], v[210:213], v[80:83]
	v_mfma_f32_16x16x32_bf16 v[68:71], v[178:181], v[220:223], v[68:71]
	v_mfma_f32_16x16x32_bf16 v[64:67], v[186:189], v[220:223], v[64:67]
	s_setprio 0
	s_barrier
	s_add_i32 s42, s52, s64
	v_lshl_add_u64 v[224:225], s[40:41], 0, v[136:137]
	s_mov_b32 m0, s42
	ds_read_b128 v[190:193], v164 offset:16384
	ds_read_b128 v[194:197], v164 offset:17408
	ds_read_b128 v[198:201], v164 offset:18432
	ds_read_b128 v[202:205], v164 offset:19456
	ds_read_b128 v[206:209], v164 offset:20480
	ds_read_b128 v[210:213], v164 offset:21504
	ds_read_b128 v[214:217], v164 offset:22528
	ds_read_b128 v[220:223], v164 offset:23552
	global_load_lds_dwordx4 v[224:225], off
	s_add_i32 m0, s42, 0x2000
	v_lshl_add_u64 v[226:227], s[40:41], 0, v[140:141]
	s_add_u32 s40, s40, s48
	s_addc_u32 s41, s41, s49
	s_add_i32 s42, s53, s64
	global_load_lds_dwordx4 v[226:227], off
	v_lshl_add_u64 v[228:229], s[40:41], 0, v[136:137]
	s_mov_b32 m0, s42
	v_lshl_add_u64 v[230:231], s[40:41], 0, v[140:141]
	global_load_lds_dwordx4 v[228:229], off
	s_add_i32 m0, s42, 0x2000
	v_lshl_add_u64 v[232:233], s[26:27], 0, v[134:135]
	global_load_lds_dwordx4 v[230:231], off
	s_mov_b32 m0, s65
	v_lshl_add_u64 v[234:235], s[26:27], 0, v[138:139]
	global_load_lds_dwordx4 v[232:233], off
	s_mov_b32 m0, s76
	s_nop 0
	global_load_lds_dwordx4 v[234:235], off
	s_waitcnt vmcnt(8)
	s_waitcnt lgkmcnt(0)
	s_barrier
; #define PG8_STAGE(bufoff, gbase, voff) do { _Pragma("unroll") for (int _i = 0; _i < 2; ++_i) \
;         __builtin_amdgcn_global_load_lds((const unsigned*)((const char*)(gbase) + (voff)[_i]), (LAS unsigned*)(lds + (bufoff) + ldsw + _i * 8192), 16, 0, 0); } while (0)
; #define PG8_LDA(dst, b, h) do { _Pragma("unroll") for (int m = 0; m < 4; ++m) _Pragma("unroll") for (int k = 0; k < 2; ++k) dst[m][k] = *(const LAS bf16x8*)(lds + PG8_SA(b, h) + aoff + m * 2048 + k * 1024); } while (0)
; #define PG8_LDB(dst, b, h) do { _Pragma("unroll") for (int n = 0; n < 2; ++n) _Pragma("unroll") for (int k = 0; k < 2; ++k) dst[n][k] = *(const LAS bf16x8*)(lds + PG8_SB(b, h) + boff + n * 2048 + k * 1024); } while (0)
; #define PG8_MMA(ai, bj, At, Bt) do { __builtin_amdgcn_s_setprio(1); _Pragma("unroll") for (int m = 0; m < 4; ++m) _Pragma("unroll") for (int n = 0; n < 2; ++n) _Pragma("unroll") for (int k = 0; k < 2; ++k) \
;         acc[ai][bj][m][n] = __builtin_amdgcn_mfma_f32_16x16x32_bf16(Bt[n][k], At[m][k], acc[ai][bj][m][n], 0, 0, 0); __builtin_amdgcn_s_setprio(0); } while (0)
; #define PG8_WAIT_V(n) asm volatile("s_waitcnt vmcnt(" #n ")" ::: "memory")
; #define PG8_WAIT_L(n) asm volatile("s_waitcnt lgkmcnt(" #n ")" ::: "memory")
; #define PG8_BAR __builtin_amdgcn_s_barrier()
; #define PG8_SCHED __builtin_amdgcn_sched_barrier(0)
; template <class Epi, class Sched, bool ALIGN_EPI>
; __device__ __forceinline__ void gemm_phase(LAS unsigned char* lds, const Gemm g, const Sched& S, const Epi& E) {
;     ...
;             PG8_WAIT_V(8); PG8_WAIT_L(0); PG8_BAR; PG8_MMA(1, 0, At, B0); PG8_MMA(1, 1, At, B1); PG8_BAR; PG8_SCHED;
;             PG8_LDB(B0, 1, 0); PG8_LDB(B1, 1, 1); PG8_SCHED; PG8_LDA(At, 1, 0); PG8_STAGE(PG8_SA(0, 1), a2 + hstepA, voffA);
;             PG8_WAIT_V(8); PG8_WAIT_L(0); PG8_BAR; PG8_MMA(0, 0, At, B0); PG8_MMA(0, 1, At, B1); PG8_BAR; PG8_SCHED;
	s_setprio 1
	v_mfma_f32_16x16x32_bf16 v[60:63], v[128:131], v[190:193], v[60:63]
	v_mfma_f32_16x16x32_bf16 v[56:59], v[166:169], v[190:193], v[56:59]
	v_mfma_f32_16x16x32_bf16 v[44:47], v[128:131], v[198:201], v[44:47]
	v_mfma_f32_16x16x32_bf16 v[40:43], v[166:169], v[198:201], v[40:43]
	v_mfma_f32_16x16x32_bf16 v[28:31], v[128:131], v[206:209], v[28:31]
	v_mfma_f32_16x16x32_bf16 v[24:27], v[166:169], v[206:209], v[24:27]
	v_mfma_f32_16x16x32_bf16 v[12:15], v[128:131], v[214:217], v[12:15]
	v_mfma_f32_16x16x32_bf16 v[8:11], v[166:169], v[214:217], v[8:11]
	v_mfma_f32_16x16x32_bf16 v[60:63], v[156:159], v[194:197], v[60:63]
	v_mfma_f32_16x16x32_bf16 v[56:59], v[170:173], v[194:197], v[56:59]
	v_mfma_f32_16x16x32_bf16 v[44:47], v[156:159], v[202:205], v[44:47]
	v_mfma_f32_16x16x32_bf16 v[40:43], v[170:173], v[202:205], v[40:43]
	v_mfma_f32_16x16x32_bf16 v[28:31], v[156:159], v[210:213], v[28:31]
	v_mfma_f32_16x16x32_bf16 v[24:27], v[170:173], v[210:213], v[24:27]
	v_mfma_f32_16x16x32_bf16 v[12:15], v[156:159], v[220:223], v[12:15]
	v_mfma_f32_16x16x32_bf16 v[8:11], v[170:173], v[220:223], v[8:11]
	s_setprio 0
	s_setprio 1
	v_mfma_f32_16x16x32_bf16 v[52:55], v[174:177], v[190:193], v[52:55]
	v_mfma_f32_16x16x32_bf16 v[48:51], v[182:185], v[190:193], v[48:51]
	v_mfma_f32_16x16x32_bf16 v[36:39], v[174:177], v[198:201], v[36:39]
	v_mfma_f32_16x16x32_bf16 v[32:35], v[182:185], v[198:201], v[32:35]
	v_mfma_f32_16x16x32_bf16 v[20:23], v[174:177], v[206:209], v[20:23]
	v_mfma_f32_16x16x32_bf16 v[16:19], v[182:185], v[206:209], v[16:19]
	v_mfma_f32_16x16x32_bf16 v[4:7], v[174:177], v[214:217], v[4:7]
	v_mfma_f32_16x16x32_bf16 v[0:3], v[182:185], v[214:217], v[0:3]
	v_mfma_f32_16x16x32_bf16 v[52:55], v[178:181], v[194:197], v[52:55]
	v_mfma_f32_16x16x32_bf16 v[48:51], v[186:189], v[194:197], v[48:51]
	v_mfma_f32_16x16x32_bf16 v[36:39], v[178:181], v[202:205], v[36:39]
	v_mfma_f32_16x16x32_bf16 v[32:35], v[186:189], v[202:205], v[32:35]
	v_mfma_f32_16x16x32_bf16 v[20:23], v[178:181], v[210:213], v[20:23]
	v_mfma_f32_16x16x32_bf16 v[16:19], v[186:189], v[210:213], v[16:19]
	v_mfma_f32_16x16x32_bf16 v[4:7], v[178:181], v[220:223], v[4:7]
	v_mfma_f32_16x16x32_bf16 v[0:3], v[186:189], v[220:223], v[0:3]
	s_setprio 0
	s_barrier
	s_add_i32 s40, 0, 0x18000
	v_add_u32_e32 v142, s40, v160
	s_add_i32 s41, 0, 0x1c000
	ds_read_b128 v[128:131], v142
	ds_read_b128 v[156:159], v142 offset:1024
	ds_read_b128 v[166:169], v142 offset:2048
	ds_read_b128 v[170:173], v142 offset:3072
	v_add_u32_e32 v142, s41, v160
	ds_read_b128 v[174:177], v142
	ds_read_b128 v[178:181], v142 offset:1024
	ds_read_b128 v[182:185], v142 offset:2048
	ds_read_b128 v[186:189], v142 offset:3072
	s_add_u32 s26, s26, s46
	s_addc_u32 s27, s27, s47
	s_mov_b32 m0, s77
	v_lshl_add_u64 v[236:237], s[26:27], 0, v[134:135]
	ds_read_b128 v[190:193], v164 offset:32768
	ds_read_b128 v[194:197], v164 offset:33792
	ds_read_b128 v[198:201], v164 offset:34816
	ds_read_b128 v[202:205], v164 offset:35840
	ds_read_b128 v[206:209], v164 offset:36864
	ds_read_b128 v[210:213], v164 offset:37888
	ds_read_b128 v[214:217], v164 offset:38912
	ds_read_b128 v[220:223], v164 offset:39936
	global_load_lds_dwordx4 v[236:237], off
	v_lshl_add_u64 v[236:237], s[26:27], 0, v[138:139]
	s_mov_b32 m0, s82
	s_nop 0
	global_load_lds_dwordx4 v[236:237], off
	s_waitcnt vmcnt(8)
	s_waitcnt lgkmcnt(0)
	s_barrier
	s_setprio 1
	v_mfma_f32_16x16x32_bf16 v[124:127], v[128:131], v[190:193], v[124:127]
	v_mfma_f32_16x16x32_bf16 v[120:123], v[166:169], v[190:193], v[120:123]
	v_mfma_f32_16x16x32_bf16 v[108:111], v[128:131], v[198:201], v[108:111]
	v_mfma_f32_16x16x32_bf16 v[104:107], v[166:169], v[198:201], v[104:107]
	v_mfma_f32_16x16x32_bf16 v[92:95], v[128:131], v[206:209], v[92:95]
	v_mfma_f32_16x16x32_bf16 v[88:91], v[166:169], v[206:209], v[88:91]
	v_mfma_f32_16x16x32_bf16 v[76:79], v[128:131], v[214:217], v[76:79]
	v_mfma_f32_16x16x32_bf16 v[72:75], v[166:169], v[214:217], v[72:75]
	v_mfma_f32_16x16x32_bf16 v[124:127], v[156:159], v[194:197], v[124:127]
	v_mfma_f32_16x16x32_bf16 v[120:123], v[170:173], v[194:197], v[120:123]
	v_mfma_f32_16x16x32_bf16 v[108:111], v[156:159], v[202:205], v[108:111]
	v_mfma_f32_16x16x32_bf16 v[104:107], v[170:173], v[202:205], v[104:107]
	v_mfma_f32_16x16x32_bf16 v[92:95], v[156:159], v[210:213], v[92:95]
	v_mfma_f32_16x16x32_bf16 v[88:91], v[170:173], v[210:213], v[88:91]
	v_mfma_f32_16x16x32_bf16 v[76:79], v[156:159], v[220:223], v[76:79]
	v_mfma_f32_16x16x32_bf16 v[72:75], v[170:173], v[220:223], v[72:75]
	s_setprio 0
	s_setprio 1
	v_mfma_f32_16x16x32_bf16 v[116:119], v[174:177], v[190:193], v[116:119]
	v_mfma_f32_16x16x32_bf16 v[112:115], v[182:185], v[190:193], v[112:115]
	v_mfma_f32_16x16x32_bf16 v[100:103], v[174:177], v[198:201], v[100:103]
	v_mfma_f32_16x16x32_bf16 v[96:99], v[182:185], v[198:201], v[96:99]
	v_mfma_f32_16x16x32_bf16 v[84:87], v[174:177], v[206:209], v[84:87]
	v_mfma_f32_16x16x32_bf16 v[80:83], v[182:185], v[206:209], v[80:83]
	v_mfma_f32_16x16x32_bf16 v[68:71], v[174:177], v[214:217], v[68:71]
	v_mfma_f32_16x16x32_bf16 v[64:67], v[182:185], v[214:217], v[64:67]
	v_mfma_f32_16x16x32_bf16 v[116:119], v[178:181], v[194:197], v[116:119]
	v_mfma_f32_16x16x32_bf16 v[112:115], v[186:189], v[194:197], v[112:115]
	v_mfma_f32_16x16x32_bf16 v[100:103], v[178:181], v[202:205], v[100:103]
	v_mfma_f32_16x16x32_bf16 v[96:99], v[186:189], v[202:205], v[96:99]
	v_mfma_f32_16x16x32_bf16 v[84:87], v[178:181], v[210:213], v[84:87]
	v_mfma_f32_16x16x32_bf16 v[80:83], v[186:189], v[210:213], v[80:83]
	v_mfma_f32_16x16x32_bf16 v[68:71], v[178:181], v[220:223], v[68:71]
	v_mfma_f32_16x16x32_bf16 v[64:67], v[186:189], v[220:223], v[64:67]
	s_setprio 0
	s_barrier
; #define PG8_STAGE(bufoff, gbase, voff) do { _Pragma("unroll") for (int _i = 0; _i < 2; ++_i) \
;         __builtin_amdgcn_global_load_lds((const unsigned*)((const char*)(gbase) + (voff)[_i]), (LAS unsigned*)(lds + (bufoff) + ldsw + _i * 8192), 16, 0, 0); } while (0)
; #define PG8_LDA(dst, b, h) do { _Pragma("unroll") for (int m = 0; m < 4; ++m) _Pragma("unroll") for (int k = 0; k < 2; ++k) dst[m][k] = *(const LAS bf16x8*)(lds + PG8_SA(b, h) + aoff + m * 2048 + k * 1024); } while (0)
; #define PG8_MMA(ai, bj, At, Bt) do { __builtin_amdgcn_s_setprio(1); _Pragma("unroll") for (int m = 0; m < 4; ++m) _Pragma("unroll") for (int n = 0; n < 2; ++n) _Pragma("unroll") for (int k = 0; k < 2; ++k) \
;         acc[ai][bj][m][n] = __builtin_amdgcn_mfma_f32_16x16x32_bf16(Bt[n][k], At[m][k], acc[ai][bj][m][n], 0, 0, 0); __builtin_amdgcn_s_setprio(0); } while (0)
; #define PG8_WAIT_V(n) asm volatile("s_waitcnt vmcnt(" #n ")" ::: "memory")
; #define PG8_WAIT_L(n) asm volatile("s_waitcnt lgkmcnt(" #n ")" ::: "memory")
; #define PG8_BAR __builtin_amdgcn_s_barrier()
; #define PG8_SCHED __builtin_amdgcn_sched_barrier(0)
; template <class Epi, class Sched, bool ALIGN_EPI>
; __device__ __forceinline__ void gemm_phase(LAS unsigned char* lds, const Gemm g, const Sched& S, const Epi& E) {
;     ...
;             PG8_LDA(At, 1, 1); PG8_STAGE(PG8_SB(1, 0), b3, voffB); PG8_STAGE(PG8_SB(1, 1), b3 + hstepB, voffB); PG8_STAGE(PG8_SA(1, 0), a3, voffA);
;             PG8_WAIT_V(8); PG8_WAIT_L(0); PG8_BAR; PG8_MMA(1, 0, At, B0); PG8_MMA(1, 1, At, B1); PG8_BAR; PG8_SCHED;
;         }
	s_add_i32 s26, s40, s64
	v_lshl_add_u64 v[224:225], v[224:225], 0, s[66:67]
	s_mov_b32 m0, s26
	ds_read_b128 v[190:193], v164 offset:49152
	ds_read_b128 v[194:197], v164 offset:50176
	ds_read_b128 v[198:201], v164 offset:51200
	ds_read_b128 v[202:205], v164 offset:52224
	ds_read_b128 v[206:209], v164 offset:53248
	ds_read_b128 v[210:213], v164 offset:54272
	ds_read_b128 v[214:217], v164 offset:55296
	ds_read_b128 v[220:223], v164 offset:56320
	global_load_lds_dwordx4 v[224:225], off
	v_lshl_add_u64 v[224:225], v[226:227], 0, s[66:67]
	s_add_i32 m0, s26, 0x2000
	s_add_i32 s26, s41, s64
	global_load_lds_dwordx4 v[224:225], off
	v_lshl_add_u64 v[224:225], v[228:229], 0, s[66:67]
	s_mov_b32 m0, s26
	s_nop 0
	global_load_lds_dwordx4 v[224:225], off
	v_lshl_add_u64 v[224:225], v[230:231], 0, s[66:67]
	s_add_i32 m0, s26, 0x2000
	s_nop 0
	global_load_lds_dwordx4 v[224:225], off
	v_lshl_add_u64 v[224:225], v[232:233], 0, s[66:67]
	s_mov_b32 m0, s83
	s_nop 0
	global_load_lds_dwordx4 v[224:225], off
	v_lshl_add_u64 v[224:225], v[234:235], 0, s[66:67]
	s_mov_b32 m0, s80
	s_nop 0
	global_load_lds_dwordx4 v[224:225], off
	s_waitcnt vmcnt(8)
	s_waitcnt lgkmcnt(0)
	s_barrier
	s_setprio 1
	v_mfma_f32_16x16x32_bf16 v[60:63], v[128:131], v[190:193], v[60:63]
	v_mfma_f32_16x16x32_bf16 v[56:59], v[166:169], v[190:193], v[56:59]
	v_mfma_f32_16x16x32_bf16 v[44:47], v[128:131], v[198:201], v[44:47]
	v_mfma_f32_16x16x32_bf16 v[40:43], v[166:169], v[198:201], v[40:43]
	v_mfma_f32_16x16x32_bf16 v[28:31], v[128:131], v[206:209], v[28:31]
	v_mfma_f32_16x16x32_bf16 v[24:27], v[166:169], v[206:209], v[24:27]
	v_mfma_f32_16x16x32_bf16 v[12:15], v[128:131], v[214:217], v[12:15]
	v_mfma_f32_16x16x32_bf16 v[8:11], v[166:169], v[214:217], v[8:11]
	v_mfma_f32_16x16x32_bf16 v[60:63], v[156:159], v[194:197], v[60:63]
	v_mfma_f32_16x16x32_bf16 v[56:59], v[170:173], v[194:197], v[56:59]
	v_mfma_f32_16x16x32_bf16 v[44:47], v[156:159], v[202:205], v[44:47]
	v_mfma_f32_16x16x32_bf16 v[40:43], v[170:173], v[202:205], v[40:43]
	v_mfma_f32_16x16x32_bf16 v[28:31], v[156:159], v[210:213], v[28:31]
	v_mfma_f32_16x16x32_bf16 v[24:27], v[170:173], v[210:213], v[24:27]
	v_mfma_f32_16x16x32_bf16 v[12:15], v[156:159], v[220:223], v[12:15]
	v_mfma_f32_16x16x32_bf16 v[8:11], v[170:173], v[220:223], v[8:11]
	s_setprio 0
	s_setprio 1
	v_mfma_f32_16x16x32_bf16 v[52:55], v[174:177], v[190:193], v[52:55]
	v_mfma_f32_16x16x32_bf16 v[48:51], v[182:185], v[190:193], v[48:51]
	v_mfma_f32_16x16x32_bf16 v[36:39], v[174:177], v[198:201], v[36:39]
	v_mfma_f32_16x16x32_bf16 v[32:35], v[182:185], v[198:201], v[32:35]
	v_mfma_f32_16x16x32_bf16 v[20:23], v[174:177], v[206:209], v[20:23]
	v_mfma_f32_16x16x32_bf16 v[16:19], v[182:185], v[206:209], v[16:19]
	v_mfma_f32_16x16x32_bf16 v[4:7], v[174:177], v[214:217], v[4:7]
	v_mfma_f32_16x16x32_bf16 v[0:3], v[182:185], v[214:217], v[0:3]
	v_mfma_f32_16x16x32_bf16 v[52:55], v[178:181], v[194:197], v[52:55]
	v_mfma_f32_16x16x32_bf16 v[48:51], v[186:189], v[194:197], v[48:51]
	v_mfma_f32_16x16x32_bf16 v[36:39], v[178:181], v[202:205], v[36:39]
	v_mfma_f32_16x16x32_bf16 v[32:35], v[186:189], v[202:205], v[32:35]
	v_mfma_f32_16x16x32_bf16 v[20:23], v[178:181], v[210:213], v[20:23]
	v_mfma_f32_16x16x32_bf16 v[16:19], v[186:189], v[210:213], v[16:19]
	v_mfma_f32_16x16x32_bf16 v[4:7], v[178:181], v[220:223], v[4:7]
	v_mfma_f32_16x16x32_bf16 v[0:3], v[186:189], v[220:223], v[0:3]
	s_setprio 0
	s_barrier
	s_add_u32 s31, s31, 0x100
	s_addc_u32 s50, s50, 0
	s_add_u32 s12, s12, 0x100
	s_addc_u32 s13, s13, 0
	s_cmp_ge_i32 s55, s81
	s_mov_b32 s26, s55
	s_cbranch_scc0 .LBB0_157

;     __device__ __forceinline__ const char* a_ptr(const Unit& u) const { return (const char*)(u.sel ? A1 : A0) + ((size_t)u.pm * BM * lda + (size_t)(u.pn >> a_grp_shift) * a_grp_cols) * 2; }
;     __device__ __forceinline__ const char* b_ptr(const Unit& u) const { return (const char*)(u.sel ? B1 : B0) + (size_t)u.pn * BM * ldb * 2; }
;     __device__ bool next(int i, Unit& u) const { if (!S.next(i >> 1, u)) return false; u.sel = i & 1; return true; }
; #define PG8_STAGE(bufoff, gbase, voff) do { _Pragma("unroll") for (int _i = 0; _i < 2; ++_i) \
;         __builtin_amdgcn_global_load_lds((const unsigned*)((const char*)(gbase) + (voff)[_i]), (LAS unsigned*)(lds + (bufoff) + ldsw + _i * 8192), 16, 0, 0); } while (0)
; #define PG8_LDA(dst, b, h) do { _Pragma("unroll") for (int m = 0; m < 4; ++m) _Pragma("unroll") for (int k = 0; k < 2; ++k) dst[m][k] = *(const LAS bf16x8*)(lds + PG8_SA(b, h) + aoff + m * 2048 + k * 1024); } while (0)
; #define PG8_LDB(dst, b, h) do { _Pragma("unroll") for (int n = 0; n < 2; ++n) _Pragma("unroll") for (int k = 0; k < 2; ++k) dst[n][k] = *(const LAS bf16x8*)(lds + PG8_SB(b, h) + boff + n * 2048 + k * 1024); } while (0)
; template <class Epi, class Sched, bool ALIGN_EPI>
; __device__ __forceinline__ void gemm_phase(LAS unsigned char* lds, const Gemm g, const Sched& S, const Epi& E) {
;     ...
;         const bool has_next = S.next(ui + 1, nxt);
;         const char* nA = has_next ? g.a_ptr(nxt) : cA; const char* nB = has_next ? g.b_ptr(nxt) : cB;
;         for (int t = 0; t < nt; t += 2) {
;             const bool last = (t == nt - 2);
;             const char* a1 = cA + (size_t)(t + 1) * kstep;
;             const char* a2 = last ? nA : cA + (size_t)(t + 2) * kstep; const char* b2 = last ? nB : cB + (size_t)(t + 2) * kstep;
;             const char* a3 = a2 + kstep; const char* b3 = b2 + kstep;
;             PG8_LDB(B0, 0, 0); PG8_LDB(B1, 0, 1); PG8_SCHED; PG8_LDA(At, 0, 0); PG8_STAGE(PG8_SA(1, 1), a1 + hstepA, voffA);
;             PG8_WAIT_V(8); PG8_WAIT_L(0); PG8_BAR; PG8_MMA(0, 0, At, B0); PG8_MMA(0, 1, At, B1); PG8_BAR; PG8_SCHED;
;             PG8_LDA(At, 0, 1); PG8_STAGE(PG8_SB(0, 0), b2, voffB); PG8_STAGE(PG8_SB(0, 1), b2 + hstepB, voffB); PG8_STAGE(PG8_SA(0, 0), a2, voffA);
;             PG8_WAIT_V(8); PG8_WAIT_L(0); PG8_BAR; PG8_MMA(1, 0, At, B0); PG8_MMA(1, 1, At, B1); PG8_BAR; PG8_SCHED;
.LBB0_403:
	ds_read_b128 v[128:131], v187
	ds_read_b128 v[132:135], v187 offset:1024
	ds_read_b128 v[136:139], v187 offset:2048
	ds_read_b128 v[140:143], v187 offset:3072
	ds_read_b128 v[144:147], v189
	ds_read_b128 v[148:151], v189 offset:1024
	ds_read_b128 v[152:155], v189 offset:2048
	ds_read_b128 v[156:159], v189 offset:3072
	s_add_i32 s96, s12, 2
	s_add_u32 s84, s8, 0x80
	s_addc_u32 s13, s9, 0
	s_cmp_eq_u32 s75, s12
	s_cselect_b32 s12, s7, s84
	s_cselect_b32 s13, s5, s13
	s_cselect_b32 s85, s55, s95
	s_cselect_b32 s84, s65, s94
	v_lshl_add_u64 v[178:179], s[8:9], 0, v[170:171]
	s_add_i32 m0, s33, 0xc000
	ds_read_b128 v[194:197], v191
	ds_read_b128 v[198:201], v191 offset:1024
	ds_read_b128 v[202:205], v191 offset:2048
	ds_read_b128 v[206:209], v191 offset:3072
	ds_read_b128 v[210:213], v191 offset:4096
	ds_read_b128 v[214:217], v191 offset:5120
	ds_read_b128 v[220:223], v191 offset:6144
	ds_read_b128 v[224:227], v191 offset:7168
	global_load_lds_dwordx4 v[178:179], off
	v_lshl_add_u64 v[178:179], s[8:9], 0, v[172:173]
	s_add_i32 m0, s33, 0xe000
	s_nop 0
	global_load_lds_dwordx4 v[178:179], off
	s_waitcnt vmcnt(8)
	s_waitcnt lgkmcnt(0)
	s_barrier
	s_setprio 1
	v_mfma_f32_16x16x32_bf16 v[124:127], v[128:131], v[194:197], v[124:127]
	v_mfma_f32_16x16x32_bf16 v[120:123], v[136:139], v[194:197], v[120:123]
	v_mfma_f32_16x16x32_bf16 v[108:111], v[128:131], v[202:205], v[108:111]
	v_mfma_f32_16x16x32_bf16 v[104:107], v[136:139], v[202:205], v[104:107]
	v_mfma_f32_16x16x32_bf16 v[92:95], v[128:131], v[210:213], v[92:95]
	v_mfma_f32_16x16x32_bf16 v[88:91], v[136:139], v[210:213], v[88:91]
	v_mfma_f32_16x16x32_bf16 v[76:79], v[128:131], v[220:223], v[76:79]
	v_mfma_f32_16x16x32_bf16 v[72:75], v[136:139], v[220:223], v[72:75]
	v_mfma_f32_16x16x32_bf16 v[124:127], v[132:135], v[198:201], v[124:127]
	v_mfma_f32_16x16x32_bf16 v[120:123], v[140:143], v[198:201], v[120:123]
	v_mfma_f32_16x16x32_bf16 v[108:111], v[132:135], v[206:209], v[108:111]
	v_mfma_f32_16x16x32_bf16 v[104:107], v[140:143], v[206:209], v[104:107]
	v_mfma_f32_16x16x32_bf16 v[92:95], v[132:135], v[214:217], v[92:95]
	v_mfma_f32_16x16x32_bf16 v[88:91], v[140:143], v[214:217], v[88:91]
	v_mfma_f32_16x16x32_bf16 v[76:79], v[132:135], v[224:227], v[76:79]
	v_mfma_f32_16x16x32_bf16 v[72:75], v[140:143], v[224:227], v[72:75]
	s_setprio 0
	s_setprio 1
	v_mfma_f32_16x16x32_bf16 v[116:119], v[144:147], v[194:197], v[116:119]
	v_mfma_f32_16x16x32_bf16 v[112:115], v[152:155], v[194:197], v[112:115]
	v_mfma_f32_16x16x32_bf16 v[100:103], v[144:147], v[202:205], v[100:103]
	v_mfma_f32_16x16x32_bf16 v[96:99], v[152:155], v[202:205], v[96:99]
	v_mfma_f32_16x16x32_bf16 v[84:87], v[144:147], v[210:213], v[84:87]
	v_mfma_f32_16x16x32_bf16 v[80:83], v[152:155], v[210:213], v[80:83]
	v_mfma_f32_16x16x32_bf16 v[68:71], v[144:147], v[220:223], v[68:71]
	v_mfma_f32_16x16x32_bf16 v[64:67], v[152:155], v[220:223], v[64:67]
	v_mfma_f32_16x16x32_bf16 v[116:119], v[148:151], v[198:201], v[116:119]
	v_mfma_f32_16x16x32_bf16 v[112:115], v[156:159], v[198:201], v[112:115]
	v_mfma_f32_16x16x32_bf16 v[100:103], v[148:151], v[206:209], v[100:103]
	v_mfma_f32_16x16x32_bf16 v[96:99], v[156:159], v[206:209], v[96:99]
	v_mfma_f32_16x16x32_bf16 v[84:87], v[148:151], v[214:217], v[84:87]
	v_mfma_f32_16x16x32_bf16 v[80:83], v[156:159], v[214:217], v[80:83]
	v_mfma_f32_16x16x32_bf16 v[68:71], v[148:151], v[224:227], v[68:71]
	v_mfma_f32_16x16x32_bf16 v[64:67], v[156:159], v[224:227], v[64:67]
	s_setprio 0
	s_barrier
	s_add_i32 s86, s81, s29
	v_lshl_add_u64 v[178:179], s[84:85], 0, v[162:163]
	s_mov_b32 m0, s86
	ds_read_b128 v[194:197], v191 offset:16384
	ds_read_b128 v[198:201], v191 offset:17408
	ds_read_b128 v[202:205], v191 offset:18432
	ds_read_b128 v[206:209], v191 offset:19456
	ds_read_b128 v[210:213], v191 offset:20480
	ds_read_b128 v[214:217], v191 offset:21504
	ds_read_b128 v[220:223], v191 offset:22528
	ds_read_b128 v[224:227], v191 offset:23552
	global_load_lds_dwordx4 v[178:179], off
	s_add_i32 m0, s86, 0x2000
	v_lshl_add_u64 v[228:229], s[84:85], 0, v[166:167]
	s_add_u32 s84, s84, s46
	s_addc_u32 s85, s85, s47
	s_add_i32 s86, s82, s29
	global_load_lds_dwordx4 v[228:229], off
	v_lshl_add_u64 v[230:231], s[84:85], 0, v[162:163]
	s_mov_b32 m0, s86
	v_lshl_add_u64 v[232:233], s[84:85], 0, v[166:167]
	global_load_lds_dwordx4 v[230:231], off
	s_add_i32 m0, s86, 0x2000
	v_lshl_add_u64 v[234:235], s[12:13], 0, v[160:161]
	global_load_lds_dwordx4 v[232:233], off
	s_mov_b32 m0, s33
	v_lshl_add_u64 v[236:237], s[12:13], 0, v[164:165]
	global_load_lds_dwordx4 v[234:235], off
	s_mov_b32 m0, s58
	s_nop 0
	global_load_lds_dwordx4 v[236:237], off
	s_waitcnt vmcnt(8)
	s_waitcnt lgkmcnt(0)
	s_barrier
; #define PG8_STAGE(bufoff, gbase, voff) do { _Pragma("unroll") for (int _i = 0; _i < 2; ++_i) \
;         __builtin_amdgcn_global_load_lds((const unsigned*)((const char*)(gbase) + (voff)[_i]), (LAS unsigned*)(lds + (bufoff) + ldsw + _i * 8192), 16, 0, 0); } while (0)
; #define PG8_LDA(dst, b, h) do { _Pragma("unroll") for (int m = 0; m < 4; ++m) _Pragma("unroll") for (int k = 0; k < 2; ++k) dst[m][k] = *(const LAS bf16x8*)(lds + PG8_SA(b, h) + aoff + m * 2048 + k * 1024); } while (0)
; #define PG8_LDB(dst, b, h) do { _Pragma("unroll") for (int n = 0; n < 2; ++n) _Pragma("unroll") for (int k = 0; k < 2; ++k) dst[n][k] = *(const LAS bf16x8*)(lds + PG8_SB(b, h) + boff + n * 2048 + k * 1024); } while (0)
; #define PG8_MMA(ai, bj, At, Bt) do { __builtin_amdgcn_s_setprio(1); _Pragma("unroll") for (int m = 0; m < 4; ++m) _Pragma("unroll") for (int n = 0; n < 2; ++n) _Pragma("unroll") for (int k = 0; k < 2; ++k) \
;         acc[ai][bj][m][n] = __builtin_amdgcn_mfma_f32_16x16x32_bf16(Bt[n][k], At[m][k], acc[ai][bj][m][n], 0, 0, 0); __builtin_amdgcn_s_setprio(0); } while (0)
; #define PG8_WAIT_V(n) asm volatile("s_waitcnt vmcnt(" #n ")" ::: "memory")
; #define PG8_WAIT_L(n) asm volatile("s_waitcnt lgkmcnt(" #n ")" ::: "memory")
; #define PG8_BAR __builtin_amdgcn_s_barrier()
; #define PG8_SCHED __builtin_amdgcn_sched_barrier(0)
; template <class Epi, class Sched, bool ALIGN_EPI>
; __device__ __forceinline__ void gemm_phase(LAS unsigned char* lds, const Gemm g, const Sched& S, const Epi& E) {
;     ...
;             PG8_WAIT_V(8); PG8_WAIT_L(0); PG8_BAR; PG8_MMA(1, 0, At, B0); PG8_MMA(1, 1, At, B1); PG8_BAR; PG8_SCHED;
;             PG8_LDB(B0, 1, 0); PG8_LDB(B1, 1, 1); PG8_SCHED; PG8_LDA(At, 1, 0); PG8_STAGE(PG8_SA(0, 1), a2 + hstepA, voffA);
;             PG8_WAIT_V(8); PG8_WAIT_L(0); PG8_BAR; PG8_MMA(0, 0, At, B0); PG8_MMA(0, 1, At, B1); PG8_BAR; PG8_SCHED;
	s_setprio 1
	v_mfma_f32_16x16x32_bf16 v[60:63], v[128:131], v[194:197], v[60:63]
	v_mfma_f32_16x16x32_bf16 v[56:59], v[136:139], v[194:197], v[56:59]
	v_mfma_f32_16x16x32_bf16 v[44:47], v[128:131], v[202:205], v[44:47]
	v_mfma_f32_16x16x32_bf16 v[40:43], v[136:139], v[202:205], v[40:43]
	v_mfma_f32_16x16x32_bf16 v[28:31], v[128:131], v[210:213], v[28:31]
	v_mfma_f32_16x16x32_bf16 v[24:27], v[136:139], v[210:213], v[24:27]
	v_mfma_f32_16x16x32_bf16 v[12:15], v[128:131], v[220:223], v[12:15]
	v_mfma_f32_16x16x32_bf16 v[8:11], v[136:139], v[220:223], v[8:11]
	v_mfma_f32_16x16x32_bf16 v[60:63], v[132:135], v[198:201], v[60:63]
	v_mfma_f32_16x16x32_bf16 v[56:59], v[140:143], v[198:201], v[56:59]
	v_mfma_f32_16x16x32_bf16 v[44:47], v[132:135], v[206:209], v[44:47]
	v_mfma_f32_16x16x32_bf16 v[40:43], v[140:143], v[206:209], v[40:43]
	v_mfma_f32_16x16x32_bf16 v[28:31], v[132:135], v[214:217], v[28:31]
	v_mfma_f32_16x16x32_bf16 v[24:27], v[140:143], v[214:217], v[24:27]
	v_mfma_f32_16x16x32_bf16 v[12:15], v[132:135], v[224:227], v[12:15]
	v_mfma_f32_16x16x32_bf16 v[8:11], v[140:143], v[224:227], v[8:11]
	s_setprio 0
	s_setprio 1
	v_mfma_f32_16x16x32_bf16 v[52:55], v[144:147], v[194:197], v[52:55]
	v_mfma_f32_16x16x32_bf16 v[48:51], v[152:155], v[194:197], v[48:51]
	v_mfma_f32_16x16x32_bf16 v[36:39], v[144:147], v[202:205], v[36:39]
	v_mfma_f32_16x16x32_bf16 v[32:35], v[152:155], v[202:205], v[32:35]
	v_mfma_f32_16x16x32_bf16 v[20:23], v[144:147], v[210:213], v[20:23]
	v_mfma_f32_16x16x32_bf16 v[16:19], v[152:155], v[210:213], v[16:19]
	v_mfma_f32_16x16x32_bf16 v[4:7], v[144:147], v[220:223], v[4:7]
	v_mfma_f32_16x16x32_bf16 v[0:3], v[152:155], v[220:223], v[0:3]
	v_mfma_f32_16x16x32_bf16 v[52:55], v[148:151], v[198:201], v[52:55]
	v_mfma_f32_16x16x32_bf16 v[48:51], v[156:159], v[198:201], v[48:51]
	v_mfma_f32_16x16x32_bf16 v[36:39], v[148:151], v[206:209], v[36:39]
	v_mfma_f32_16x16x32_bf16 v[32:35], v[156:159], v[206:209], v[32:35]
	v_mfma_f32_16x16x32_bf16 v[20:23], v[148:151], v[214:217], v[20:23]
	v_mfma_f32_16x16x32_bf16 v[16:19], v[156:159], v[214:217], v[16:19]
	v_mfma_f32_16x16x32_bf16 v[4:7], v[148:151], v[224:227], v[4:7]
	v_mfma_f32_16x16x32_bf16 v[0:3], v[156:159], v[224:227], v[0:3]
	s_setprio 0
	s_barrier
	s_add_i32 s84, 0, 0x18000
	s_add_i32 s85, 0, 0x1c000
	v_add_u32_e32 v140, s84, v183
	v_add_u32_e32 v156, s85, v183
	ds_read_b128 v[128:131], v140
	ds_read_b128 v[132:135], v140 offset:1024
	ds_read_b128 v[136:139], v140 offset:2048
	ds_read_b128 v[140:143], v140 offset:3072
	ds_read_b128 v[144:147], v156
	ds_read_b128 v[148:151], v156 offset:1024
	ds_read_b128 v[152:155], v156 offset:2048
	ds_read_b128 v[156:159], v156 offset:3072
	s_add_u32 s12, s12, s34
	s_addc_u32 s13, s13, s35
	s_mov_b32 m0, s59
	v_lshl_add_u64 v[238:239], s[12:13], 0, v[160:161]
	ds_read_b128 v[194:197], v191 offset:32768
	ds_read_b128 v[198:201], v191 offset:33792
	ds_read_b128 v[202:205], v191 offset:34816
	ds_read_b128 v[206:209], v191 offset:35840
	ds_read_b128 v[210:213], v191 offset:36864
	ds_read_b128 v[214:217], v191 offset:37888
	ds_read_b128 v[220:223], v191 offset:38912
	ds_read_b128 v[224:227], v191 offset:39936
	global_load_lds_dwordx4 v[238:239], off
	v_lshl_add_u64 v[238:239], s[12:13], 0, v[164:165]
	s_mov_b32 m0, s62
	s_nop 0
	global_load_lds_dwordx4 v[238:239], off
	s_waitcnt vmcnt(8)
	s_waitcnt lgkmcnt(0)
	s_barrier
	s_setprio 1
	v_mfma_f32_16x16x32_bf16 v[124:127], v[128:131], v[194:197], v[124:127]
	v_mfma_f32_16x16x32_bf16 v[120:123], v[136:139], v[194:197], v[120:123]
	v_mfma_f32_16x16x32_bf16 v[108:111], v[128:131], v[202:205], v[108:111]
	v_mfma_f32_16x16x32_bf16 v[104:107], v[136:139], v[202:205], v[104:107]
	v_mfma_f32_16x16x32_bf16 v[92:95], v[128:131], v[210:213], v[92:95]
	v_mfma_f32_16x16x32_bf16 v[88:91], v[136:139], v[210:213], v[88:91]
	v_mfma_f32_16x16x32_bf16 v[76:79], v[128:131], v[220:223], v[76:79]
	v_mfma_f32_16x16x32_bf16 v[72:75], v[136:139], v[220:223], v[72:75]
	v_mfma_f32_16x16x32_bf16 v[124:127], v[132:135], v[198:201], v[124:127]
	v_mfma_f32_16x16x32_bf16 v[120:123], v[140:143], v[198:201], v[120:123]
	v_mfma_f32_16x16x32_bf16 v[108:111], v[132:135], v[206:209], v[108:111]
	v_mfma_f32_16x16x32_bf16 v[104:107], v[140:143], v[206:209], v[104:107]
	v_mfma_f32_16x16x32_bf16 v[92:95], v[132:135], v[214:217], v[92:95]
	v_mfma_f32_16x16x32_bf16 v[88:91], v[140:143], v[214:217], v[88:91]
	v_mfma_f32_16x16x32_bf16 v[76:79], v[132:135], v[224:227], v[76:79]
	v_mfma_f32_16x16x32_bf16 v[72:75], v[140:143], v[224:227], v[72:75]
	s_setprio 0
	s_setprio 1
	v_mfma_f32_16x16x32_bf16 v[116:119], v[144:147], v[194:197], v[116:119]
	v_mfma_f32_16x16x32_bf16 v[112:115], v[152:155], v[194:197], v[112:115]
	v_mfma_f32_16x16x32_bf16 v[100:103], v[144:147], v[202:205], v[100:103]
	v_mfma_f32_16x16x32_bf16 v[96:99], v[152:155], v[202:205], v[96:99]
	v_mfma_f32_16x16x32_bf16 v[84:87], v[144:147], v[210:213], v[84:87]
	v_mfma_f32_16x16x32_bf16 v[80:83], v[152:155], v[210:213], v[80:83]
	v_mfma_f32_16x16x32_bf16 v[68:71], v[144:147], v[220:223], v[68:71]
	v_mfma_f32_16x16x32_bf16 v[64:67], v[152:155], v[220:223], v[64:67]
	v_mfma_f32_16x16x32_bf16 v[116:119], v[148:151], v[198:201], v[116:119]
	v_mfma_f32_16x16x32_bf16 v[112:115], v[156:159], v[198:201], v[112:115]
	v_mfma_f32_16x16x32_bf16 v[100:103], v[148:151], v[206:209], v[100:103]
	v_mfma_f32_16x16x32_bf16 v[96:99], v[156:159], v[206:209], v[96:99]
	v_mfma_f32_16x16x32_bf16 v[84:87], v[148:151], v[214:217], v[84:87]
	v_mfma_f32_16x16x32_bf16 v[80:83], v[156:159], v[214:217], v[80:83]
	v_mfma_f32_16x16x32_bf16 v[68:71], v[148:151], v[224:227], v[68:71]
	v_mfma_f32_16x16x32_bf16 v[64:67], v[156:159], v[224:227], v[64:67]
	s_setprio 0
	s_barrier
; #define PG8_STAGE(bufoff, gbase, voff) do { _Pragma("unroll") for (int _i = 0; _i < 2; ++_i) \
;         __builtin_amdgcn_global_load_lds((const unsigned*)((const char*)(gbase) + (voff)[_i]), (LAS unsigned*)(lds + (bufoff) + ldsw + _i * 8192), 16, 0, 0); } while (0)
; #define PG8_LDA(dst, b, h) do { _Pragma("unroll") for (int m = 0; m < 4; ++m) _Pragma("unroll") for (int k = 0; k < 2; ++k) dst[m][k] = *(const LAS bf16x8*)(lds + PG8_SA(b, h) + aoff + m * 2048 + k * 1024); } while (0)
; #define PG8_MMA(ai, bj, At, Bt) do { __builtin_amdgcn_s_setprio(1); _Pragma("unroll") for (int m = 0; m < 4; ++m) _Pragma("unroll") for (int n = 0; n < 2; ++n) _Pragma("unroll") for (int k = 0; k < 2; ++k) \
;         acc[ai][bj][m][n] = __builtin_amdgcn_mfma_f32_16x16x32_bf16(Bt[n][k], At[m][k], acc[ai][bj][m][n], 0, 0, 0); __builtin_amdgcn_s_setprio(0); } while (0)
; #define PG8_WAIT_V(n) asm volatile("s_waitcnt vmcnt(" #n ")" ::: "memory")
; #define PG8_WAIT_L(n) asm volatile("s_waitcnt lgkmcnt(" #n ")" ::: "memory")
; #define PG8_BAR __builtin_amdgcn_s_barrier()
; #define PG8_SCHED __builtin_amdgcn_sched_barrier(0)
; template <class Epi, class Sched, bool ALIGN_EPI>
; __device__ __forceinline__ void gemm_phase(LAS unsigned char* lds, const Gemm g, const Sched& S, const Epi& E) {
;     ...
;             PG8_LDA(At, 1, 1); PG8_STAGE(PG8_SB(1, 0), b3, voffB); PG8_STAGE(PG8_SB(1, 1), b3 + hstepB, voffB); PG8_STAGE(PG8_SA(1, 0), a3, voffA);
;             PG8_WAIT_V(8); PG8_WAIT_L(0); PG8_BAR; PG8_MMA(1, 0, At, B0); PG8_MMA(1, 1, At, B1); PG8_BAR; PG8_SCHED;
;         }
	s_add_i32 s12, s84, s29
	v_lshl_add_u64 v[178:179], v[178:179], 0, s[50:51]
	s_mov_b32 m0, s12
	ds_read_b128 v[194:197], v191 offset:49152
	ds_read_b128 v[198:201], v191 offset:50176
	ds_read_b128 v[202:205], v191 offset:51200
	ds_read_b128 v[206:209], v191 offset:52224
	ds_read_b128 v[210:213], v191 offset:53248
	ds_read_b128 v[214:217], v191 offset:54272
	ds_read_b128 v[220:223], v191 offset:55296
	ds_read_b128 v[224:227], v191 offset:56320
	global_load_lds_dwordx4 v[178:179], off
	v_lshl_add_u64 v[178:179], v[228:229], 0, s[50:51]
	s_add_i32 m0, s12, 0x2000
	s_add_i32 s12, s85, s29
	global_load_lds_dwordx4 v[178:179], off
	v_lshl_add_u64 v[178:179], v[230:231], 0, s[50:51]
	s_mov_b32 m0, s12
	s_nop 0
	global_load_lds_dwordx4 v[178:179], off
	v_lshl_add_u64 v[178:179], v[232:233], 0, s[50:51]
	s_add_i32 m0, s12, 0x2000
	s_nop 0
	global_load_lds_dwordx4 v[178:179], off
	v_lshl_add_u64 v[178:179], v[234:235], 0, s[50:51]
	s_mov_b32 m0, s72
	s_nop 0
	global_load_lds_dwordx4 v[178:179], off
	v_lshl_add_u64 v[178:179], v[236:237], 0, s[50:51]
	s_mov_b32 m0, s73
	s_nop 0
	global_load_lds_dwordx4 v[178:179], off
	s_waitcnt vmcnt(8)
	s_waitcnt lgkmcnt(0)
	s_barrier
	s_setprio 1
	v_mfma_f32_16x16x32_bf16 v[60:63], v[128:131], v[194:197], v[60:63]
	v_mfma_f32_16x16x32_bf16 v[56:59], v[136:139], v[194:197], v[56:59]
	v_mfma_f32_16x16x32_bf16 v[44:47], v[128:131], v[202:205], v[44:47]
	v_mfma_f32_16x16x32_bf16 v[40:43], v[136:139], v[202:205], v[40:43]
	v_mfma_f32_16x16x32_bf16 v[28:31], v[128:131], v[210:213], v[28:31]
	v_mfma_f32_16x16x32_bf16 v[24:27], v[136:139], v[210:213], v[24:27]
	v_mfma_f32_16x16x32_bf16 v[12:15], v[128:131], v[220:223], v[12:15]
	v_mfma_f32_16x16x32_bf16 v[8:11], v[136:139], v[220:223], v[8:11]
	v_mfma_f32_16x16x32_bf16 v[60:63], v[132:135], v[198:201], v[60:63]
	v_mfma_f32_16x16x32_bf16 v[56:59], v[140:143], v[198:201], v[56:59]
	v_mfma_f32_16x16x32_bf16 v[44:47], v[132:135], v[206:209], v[44:47]
	v_mfma_f32_16x16x32_bf16 v[40:43], v[140:143], v[206:209], v[40:43]
	v_mfma_f32_16x16x32_bf16 v[28:31], v[132:135], v[214:217], v[28:31]
	v_mfma_f32_16x16x32_bf16 v[24:27], v[140:143], v[214:217], v[24:27]
	v_mfma_f32_16x16x32_bf16 v[12:15], v[132:135], v[224:227], v[12:15]
	v_mfma_f32_16x16x32_bf16 v[8:11], v[140:143], v[224:227], v[8:11]
	s_setprio 0
	s_setprio 1
	v_mfma_f32_16x16x32_bf16 v[52:55], v[144:147], v[194:197], v[52:55]
	v_mfma_f32_16x16x32_bf16 v[48:51], v[152:155], v[194:197], v[48:51]
	v_mfma_f32_16x16x32_bf16 v[36:39], v[144:147], v[202:205], v[36:39]
	v_mfma_f32_16x16x32_bf16 v[32:35], v[152:155], v[202:205], v[32:35]
	v_mfma_f32_16x16x32_bf16 v[20:23], v[144:147], v[210:213], v[20:23]
	v_mfma_f32_16x16x32_bf16 v[16:19], v[152:155], v[210:213], v[16:19]
	v_mfma_f32_16x16x32_bf16 v[4:7], v[144:147], v[220:223], v[4:7]
	v_mfma_f32_16x16x32_bf16 v[0:3], v[152:155], v[220:223], v[0:3]
	v_mfma_f32_16x16x32_bf16 v[52:55], v[148:151], v[198:201], v[52:55]
	v_mfma_f32_16x16x32_bf16 v[48:51], v[156:159], v[198:201], v[48:51]
	v_mfma_f32_16x16x32_bf16 v[36:39], v[148:151], v[206:209], v[36:39]
	v_mfma_f32_16x16x32_bf16 v[32:35], v[156:159], v[206:209], v[32:35]
	v_mfma_f32_16x16x32_bf16 v[20:23], v[148:151], v[214:217], v[20:23]
	v_mfma_f32_16x16x32_bf16 v[16:19], v[156:159], v[214:217], v[16:19]
	v_mfma_f32_16x16x32_bf16 v[4:7], v[148:151], v[224:227], v[4:7]
	v_mfma_f32_16x16x32_bf16 v[0:3], v[156:159], v[224:227], v[0:3]
	s_setprio 0
	s_barrier
	s_add_u32 s94, s94, 0x100
	s_addc_u32 s95, s95, 0
	s_add_u32 s8, s8, 0x100
	s_addc_u32 s9, s9, 0
	s_cmp_ge_i32 s96, s70
	s_mov_b32 s12, s96
	s_cbranch_scc0 .LBB0_403
	v_readlane_b32 s78, v252, 37
	v_readlane_b32 s79, v252, 38

; #define PG8_STAGE(bufoff, gbase, voff) do { _Pragma("unroll") for (int _i = 0; _i < 2; ++_i) \
;         __builtin_amdgcn_global_load_lds((const unsigned*)((const char*)(gbase) + (voff)[_i]), (LAS unsigned*)(lds + (bufoff) + ldsw + _i * 8192), 16, 0, 0); } while (0)
; #define PG8_LDA(dst, b, h) do { _Pragma("unroll") for (int m = 0; m < 4; ++m) _Pragma("unroll") for (int k = 0; k < 2; ++k) dst[m][k] = *(const LAS bf16x8*)(lds + PG8_SA(b, h) + aoff + m * 2048 + k * 1024); } while (0)
; #define PG8_LDB(dst, b, h) do { _Pragma("unroll") for (int n = 0; n < 2; ++n) _Pragma("unroll") for (int k = 0; k < 2; ++k) dst[n][k] = *(const LAS bf16x8*)(lds + PG8_SB(b, h) + boff + n * 2048 + k * 1024); } while (0)
; #define PG8_MMA(ai, bj, At, Bt) do { __builtin_amdgcn_s_setprio(1); _Pragma("unroll") for (int m = 0; m < 4; ++m) _Pragma("unroll") for (int n = 0; n < 2; ++n) _Pragma("unroll") for (int k = 0; k < 2; ++k) \
;         acc[ai][bj][m][n] = __builtin_amdgcn_mfma_f32_16x16x32_bf16(Bt[n][k], At[m][k], acc[ai][bj][m][n], 0, 0, 0); __builtin_amdgcn_s_setprio(0); } while (0)
; #define PG8_WAIT_V(n) asm volatile("s_waitcnt vmcnt(" #n ")" ::: "memory")
; #define PG8_WAIT_L(n) asm volatile("s_waitcnt lgkmcnt(" #n ")" ::: "memory")
; #define PG8_BAR __builtin_amdgcn_s_barrier()
; #define PG8_SCHED __builtin_amdgcn_sched_barrier(0)
; template <class Epi, class Sched, bool ALIGN_EPI>
; __device__ __forceinline__ void gemm_phase(LAS unsigned char* lds, const Gemm g, const Sched& S, const Epi& E) {
;     ...
;         for (int t = 0; t < nt; t += 2) {
;             const bool last = (t == nt - 2);
;             const char* a1 = cA + (size_t)(t + 1) * kstep;
;             const char* a2 = last ? nA : cA + (size_t)(t + 2) * kstep; const char* b2 = last ? nB : cB + (size_t)(t + 2) * kstep;
;             const char* a3 = a2 + kstep; const char* b3 = b2 + kstep;
;             PG8_LDB(B0, 0, 0); PG8_LDB(B1, 0, 1); PG8_SCHED; PG8_LDA(At, 0, 0); PG8_STAGE(PG8_SA(1, 1), a1 + hstepA, voffA);
;             PG8_WAIT_V(8); PG8_WAIT_L(0); PG8_BAR; PG8_MMA(0, 0, At, B0); PG8_MMA(0, 1, At, B1); PG8_BAR; PG8_SCHED;
;             PG8_LDA(At, 0, 1); PG8_STAGE(PG8_SB(0, 0), b2, voffB); PG8_STAGE(PG8_SB(0, 1), b2 + hstepB, voffB); PG8_STAGE(PG8_SA(0, 0), a2, voffA);
;             PG8_WAIT_V(8); PG8_WAIT_L(0); PG8_BAR; PG8_MMA(1, 0, At, B0); PG8_MMA(1, 1, At, B1); PG8_BAR; PG8_SCHED;
.LBB0_462:
	ds_read_b128 v[154:157], v149
	ds_read_b128 v[158:161], v149 offset:1024
	ds_read_b128 v[162:165], v149 offset:2048
	ds_read_b128 v[166:169], v149 offset:3072
	ds_read_b128 v[170:173], v150
	ds_read_b128 v[174:177], v150 offset:1024
	ds_read_b128 v[178:181], v150 offset:2048
	ds_read_b128 v[182:185], v150 offset:3072
	s_add_i32 s82, s64, 2
	s_add_u32 s83, s54, 0x80
	s_addc_u32 s65, s55, 0
	s_cmp_eq_u32 s70, s64
	s_cselect_b32 s64, s49, s83
	s_cselect_b32 s65, s47, s65
	s_cselect_b32 s85, s76, s81
	s_cselect_b32 s84, s77, s80
	v_lshl_add_u64 v[220:221], s[54:55], 0, v[138:139]
	s_add_i32 m0, s58, 0xc000
	ds_read_b128 v[186:189], v151
	ds_read_b128 v[190:193], v151 offset:1024
	ds_read_b128 v[194:197], v151 offset:2048
	ds_read_b128 v[198:201], v151 offset:3072
	ds_read_b128 v[202:205], v151 offset:4096
	ds_read_b128 v[206:209], v151 offset:5120
	ds_read_b128 v[210:213], v151 offset:6144
	ds_read_b128 v[214:217], v151 offset:7168
	global_load_lds_dwordx4 v[220:221], off
	v_lshl_add_u64 v[220:221], s[54:55], 0, v[140:141]
	s_add_i32 m0, s58, 0xe000
	s_nop 0
	global_load_lds_dwordx4 v[220:221], off
	s_waitcnt vmcnt(8)
	s_waitcnt lgkmcnt(0)
	s_barrier
	s_setprio 1
	v_mfma_f32_16x16x32_bf16 v[124:127], v[154:157], v[186:189], v[124:127]
	v_mfma_f32_16x16x32_bf16 v[120:123], v[162:165], v[186:189], v[120:123]
	v_mfma_f32_16x16x32_bf16 v[108:111], v[154:157], v[194:197], v[108:111]
	v_mfma_f32_16x16x32_bf16 v[104:107], v[162:165], v[194:197], v[104:107]
	v_mfma_f32_16x16x32_bf16 v[92:95], v[154:157], v[202:205], v[92:95]
	v_mfma_f32_16x16x32_bf16 v[88:91], v[162:165], v[202:205], v[88:91]
	v_mfma_f32_16x16x32_bf16 v[76:79], v[154:157], v[210:213], v[76:79]
	v_mfma_f32_16x16x32_bf16 v[72:75], v[162:165], v[210:213], v[72:75]
	v_mfma_f32_16x16x32_bf16 v[124:127], v[158:161], v[190:193], v[124:127]
	v_mfma_f32_16x16x32_bf16 v[120:123], v[166:169], v[190:193], v[120:123]
	v_mfma_f32_16x16x32_bf16 v[108:111], v[158:161], v[198:201], v[108:111]
	v_mfma_f32_16x16x32_bf16 v[104:107], v[166:169], v[198:201], v[104:107]
	v_mfma_f32_16x16x32_bf16 v[92:95], v[158:161], v[206:209], v[92:95]
	v_mfma_f32_16x16x32_bf16 v[88:91], v[166:169], v[206:209], v[88:91]
	v_mfma_f32_16x16x32_bf16 v[76:79], v[158:161], v[214:217], v[76:79]
	v_mfma_f32_16x16x32_bf16 v[72:75], v[166:169], v[214:217], v[72:75]
	s_setprio 0
	s_setprio 1
	v_mfma_f32_16x16x32_bf16 v[116:119], v[170:173], v[186:189], v[116:119]
	v_mfma_f32_16x16x32_bf16 v[112:115], v[178:181], v[186:189], v[112:115]
	v_mfma_f32_16x16x32_bf16 v[100:103], v[170:173], v[194:197], v[100:103]
	v_mfma_f32_16x16x32_bf16 v[96:99], v[178:181], v[194:197], v[96:99]
	v_mfma_f32_16x16x32_bf16 v[84:87], v[170:173], v[202:205], v[84:87]
	v_mfma_f32_16x16x32_bf16 v[80:83], v[178:181], v[202:205], v[80:83]
	v_mfma_f32_16x16x32_bf16 v[68:71], v[170:173], v[210:213], v[68:71]
	v_mfma_f32_16x16x32_bf16 v[64:67], v[178:181], v[210:213], v[64:67]
	v_mfma_f32_16x16x32_bf16 v[116:119], v[174:177], v[190:193], v[116:119]
	v_mfma_f32_16x16x32_bf16 v[112:115], v[182:185], v[190:193], v[112:115]
	v_mfma_f32_16x16x32_bf16 v[100:103], v[174:177], v[198:201], v[100:103]
	v_mfma_f32_16x16x32_bf16 v[96:99], v[182:185], v[198:201], v[96:99]
	v_mfma_f32_16x16x32_bf16 v[84:87], v[174:177], v[206:209], v[84:87]
	v_mfma_f32_16x16x32_bf16 v[80:83], v[182:185], v[206:209], v[80:83]
	v_mfma_f32_16x16x32_bf16 v[68:71], v[174:177], v[214:217], v[68:71]
	v_mfma_f32_16x16x32_bf16 v[64:67], v[182:185], v[214:217], v[64:67]
	s_setprio 0
	s_barrier
	s_add_i32 s83, s72, s33
	v_lshl_add_u64 v[220:221], s[84:85], 0, v[130:131]
	s_mov_b32 m0, s83
	ds_read_b128 v[186:189], v151 offset:16384
	ds_read_b128 v[190:193], v151 offset:17408
	ds_read_b128 v[194:197], v151 offset:18432
	ds_read_b128 v[198:201], v151 offset:19456
	ds_read_b128 v[202:205], v151 offset:20480
	ds_read_b128 v[206:209], v151 offset:21504
	ds_read_b128 v[210:213], v151 offset:22528
	ds_read_b128 v[214:217], v151 offset:23552
	global_load_lds_dwordx4 v[220:221], off
	s_add_i32 m0, s83, 0x2000
	v_lshl_add_u64 v[222:223], s[84:85], 0, v[134:135]
	s_add_u32 s84, s84, s12
	s_addc_u32 s85, s85, s13
	s_add_i32 s83, s73, s33
	global_load_lds_dwordx4 v[222:223], off
	v_lshl_add_u64 v[224:225], s[84:85], 0, v[130:131]
	s_mov_b32 m0, s83
	v_lshl_add_u64 v[226:227], s[84:85], 0, v[134:135]
	global_load_lds_dwordx4 v[224:225], off
	s_add_i32 m0, s83, 0x2000
	v_lshl_add_u64 v[228:229], s[64:65], 0, v[128:129]
	global_load_lds_dwordx4 v[226:227], off
	s_mov_b32 m0, s58
	v_lshl_add_u64 v[230:231], s[64:65], 0, v[132:133]
	global_load_lds_dwordx4 v[228:229], off
	s_mov_b32 m0, s59
	s_nop 0
	global_load_lds_dwordx4 v[230:231], off
	s_waitcnt vmcnt(8)
	s_waitcnt lgkmcnt(0)
	s_barrier
; #define PG8_STAGE(bufoff, gbase, voff) do { _Pragma("unroll") for (int _i = 0; _i < 2; ++_i) \
;         __builtin_amdgcn_global_load_lds((const unsigned*)((const char*)(gbase) + (voff)[_i]), (LAS unsigned*)(lds + (bufoff) + ldsw + _i * 8192), 16, 0, 0); } while (0)
; #define PG8_LDA(dst, b, h) do { _Pragma("unroll") for (int m = 0; m < 4; ++m) _Pragma("unroll") for (int k = 0; k < 2; ++k) dst[m][k] = *(const LAS bf16x8*)(lds + PG8_SA(b, h) + aoff + m * 2048 + k * 1024); } while (0)
; #define PG8_LDB(dst, b, h) do { _Pragma("unroll") for (int n = 0; n < 2; ++n) _Pragma("unroll") for (int k = 0; k < 2; ++k) dst[n][k] = *(const LAS bf16x8*)(lds + PG8_SB(b, h) + boff + n * 2048 + k * 1024); } while (0)
; #define PG8_MMA(ai, bj, At, Bt) do { __builtin_amdgcn_s_setprio(1); _Pragma("unroll") for (int m = 0; m < 4; ++m) _Pragma("unroll") for (int n = 0; n < 2; ++n) _Pragma("unroll") for (int k = 0; k < 2; ++k) \
;         acc[ai][bj][m][n] = __builtin_amdgcn_mfma_f32_16x16x32_bf16(Bt[n][k], At[m][k], acc[ai][bj][m][n], 0, 0, 0); __builtin_amdgcn_s_setprio(0); } while (0)
; #define PG8_WAIT_V(n) asm volatile("s_waitcnt vmcnt(" #n ")" ::: "memory")
; #define PG8_WAIT_L(n) asm volatile("s_waitcnt lgkmcnt(" #n ")" ::: "memory")
; #define PG8_BAR __builtin_amdgcn_s_barrier()
; #define PG8_SCHED __builtin_amdgcn_sched_barrier(0)
; template <class Epi, class Sched, bool ALIGN_EPI>
; __device__ __forceinline__ void gemm_phase(LAS unsigned char* lds, const Gemm g, const Sched& S, const Epi& E) {
;     ...
;             PG8_WAIT_V(8); PG8_WAIT_L(0); PG8_BAR; PG8_MMA(1, 0, At, B0); PG8_MMA(1, 1, At, B1); PG8_BAR; PG8_SCHED;
;             PG8_LDB(B0, 1, 0); PG8_LDB(B1, 1, 1); PG8_SCHED; PG8_LDA(At, 1, 0); PG8_STAGE(PG8_SA(0, 1), a2 + hstepA, voffA);
;             PG8_WAIT_V(8); PG8_WAIT_L(0); PG8_BAR; PG8_MMA(0, 0, At, B0); PG8_MMA(0, 1, At, B1); PG8_BAR; PG8_SCHED;
	s_setprio 1
	v_mfma_f32_16x16x32_bf16 v[60:63], v[154:157], v[186:189], v[60:63]
	v_mfma_f32_16x16x32_bf16 v[56:59], v[162:165], v[186:189], v[56:59]
	v_mfma_f32_16x16x32_bf16 v[44:47], v[154:157], v[194:197], v[44:47]
	v_mfma_f32_16x16x32_bf16 v[40:43], v[162:165], v[194:197], v[40:43]
	v_mfma_f32_16x16x32_bf16 v[28:31], v[154:157], v[202:205], v[28:31]
	v_mfma_f32_16x16x32_bf16 v[24:27], v[162:165], v[202:205], v[24:27]
	v_mfma_f32_16x16x32_bf16 v[12:15], v[154:157], v[210:213], v[12:15]
	v_mfma_f32_16x16x32_bf16 v[8:11], v[162:165], v[210:213], v[8:11]
	v_mfma_f32_16x16x32_bf16 v[60:63], v[158:161], v[190:193], v[60:63]
	v_mfma_f32_16x16x32_bf16 v[56:59], v[166:169], v[190:193], v[56:59]
	v_mfma_f32_16x16x32_bf16 v[44:47], v[158:161], v[198:201], v[44:47]
	v_mfma_f32_16x16x32_bf16 v[40:43], v[166:169], v[198:201], v[40:43]
	v_mfma_f32_16x16x32_bf16 v[28:31], v[158:161], v[206:209], v[28:31]
	v_mfma_f32_16x16x32_bf16 v[24:27], v[166:169], v[206:209], v[24:27]
	v_mfma_f32_16x16x32_bf16 v[12:15], v[158:161], v[214:217], v[12:15]
	v_mfma_f32_16x16x32_bf16 v[8:11], v[166:169], v[214:217], v[8:11]
	s_setprio 0
	s_setprio 1
	v_mfma_f32_16x16x32_bf16 v[52:55], v[170:173], v[186:189], v[52:55]
	v_mfma_f32_16x16x32_bf16 v[48:51], v[178:181], v[186:189], v[48:51]
	v_mfma_f32_16x16x32_bf16 v[36:39], v[170:173], v[194:197], v[36:39]
	v_mfma_f32_16x16x32_bf16 v[32:35], v[178:181], v[194:197], v[32:35]
	v_mfma_f32_16x16x32_bf16 v[20:23], v[170:173], v[202:205], v[20:23]
	v_mfma_f32_16x16x32_bf16 v[16:19], v[178:181], v[202:205], v[16:19]
	v_mfma_f32_16x16x32_bf16 v[4:7], v[170:173], v[210:213], v[4:7]
	v_mfma_f32_16x16x32_bf16 v[0:3], v[178:181], v[210:213], v[0:3]
	v_mfma_f32_16x16x32_bf16 v[52:55], v[174:177], v[190:193], v[52:55]
	v_mfma_f32_16x16x32_bf16 v[48:51], v[182:185], v[190:193], v[48:51]
	v_mfma_f32_16x16x32_bf16 v[36:39], v[174:177], v[198:201], v[36:39]
	v_mfma_f32_16x16x32_bf16 v[32:35], v[182:185], v[198:201], v[32:35]
	v_mfma_f32_16x16x32_bf16 v[20:23], v[174:177], v[206:209], v[20:23]
	v_mfma_f32_16x16x32_bf16 v[16:19], v[182:185], v[206:209], v[16:19]
	v_mfma_f32_16x16x32_bf16 v[4:7], v[174:177], v[214:217], v[4:7]
	v_mfma_f32_16x16x32_bf16 v[0:3], v[182:185], v[214:217], v[0:3]
	s_setprio 0
	s_barrier
	s_add_i32 s83, 0, 0x18000
	v_add_u32_e32 v136, s83, v147
	s_add_i32 s84, 0, 0x1c000
	ds_read_b128 v[154:157], v136
	ds_read_b128 v[158:161], v136 offset:1024
	ds_read_b128 v[162:165], v136 offset:2048
	ds_read_b128 v[166:169], v136 offset:3072
	v_add_u32_e32 v136, s84, v147
	ds_read_b128 v[170:173], v136
	ds_read_b128 v[174:177], v136 offset:1024
	ds_read_b128 v[178:181], v136 offset:2048
	ds_read_b128 v[182:185], v136 offset:3072
	s_add_u32 s64, s64, s6
	s_addc_u32 s65, s65, s7
	s_mov_b32 m0, s62
	v_lshl_add_u64 v[232:233], s[64:65], 0, v[128:129]
	ds_read_b128 v[186:189], v151 offset:32768
	ds_read_b128 v[190:193], v151 offset:33792
	ds_read_b128 v[194:197], v151 offset:34816
	ds_read_b128 v[198:201], v151 offset:35840
	ds_read_b128 v[202:205], v151 offset:36864
	ds_read_b128 v[206:209], v151 offset:37888
	ds_read_b128 v[210:213], v151 offset:38912
	ds_read_b128 v[214:217], v151 offset:39936
	global_load_lds_dwordx4 v[232:233], off
	v_lshl_add_u64 v[232:233], s[64:65], 0, v[132:133]
	s_mov_b32 m0, s63
	s_nop 0
	global_load_lds_dwordx4 v[232:233], off
	s_waitcnt vmcnt(8)
	s_waitcnt lgkmcnt(0)
	s_barrier
	s_setprio 1
	v_mfma_f32_16x16x32_bf16 v[124:127], v[154:157], v[186:189], v[124:127]
	v_mfma_f32_16x16x32_bf16 v[120:123], v[162:165], v[186:189], v[120:123]
	v_mfma_f32_16x16x32_bf16 v[108:111], v[154:157], v[194:197], v[108:111]
	v_mfma_f32_16x16x32_bf16 v[104:107], v[162:165], v[194:197], v[104:107]
	v_mfma_f32_16x16x32_bf16 v[92:95], v[154:157], v[202:205], v[92:95]
	v_mfma_f32_16x16x32_bf16 v[88:91], v[162:165], v[202:205], v[88:91]
	v_mfma_f32_16x16x32_bf16 v[76:79], v[154:157], v[210:213], v[76:79]
	v_mfma_f32_16x16x32_bf16 v[72:75], v[162:165], v[210:213], v[72:75]
	v_mfma_f32_16x16x32_bf16 v[124:127], v[158:161], v[190:193], v[124:127]
	v_mfma_f32_16x16x32_bf16 v[120:123], v[166:169], v[190:193], v[120:123]
	v_mfma_f32_16x16x32_bf16 v[108:111], v[158:161], v[198:201], v[108:111]
	v_mfma_f32_16x16x32_bf16 v[104:107], v[166:169], v[198:201], v[104:107]
	v_mfma_f32_16x16x32_bf16 v[92:95], v[158:161], v[206:209], v[92:95]
	v_mfma_f32_16x16x32_bf16 v[88:91], v[166:169], v[206:209], v[88:91]
	v_mfma_f32_16x16x32_bf16 v[76:79], v[158:161], v[214:217], v[76:79]
	v_mfma_f32_16x16x32_bf16 v[72:75], v[166:169], v[214:217], v[72:75]
	s_setprio 0
	s_setprio 1
	v_mfma_f32_16x16x32_bf16 v[116:119], v[170:173], v[186:189], v[116:119]
	v_mfma_f32_16x16x32_bf16 v[112:115], v[178:181], v[186:189], v[112:115]
	v_mfma_f32_16x16x32_bf16 v[100:103], v[170:173], v[194:197], v[100:103]
	v_mfma_f32_16x16x32_bf16 v[96:99], v[178:181], v[194:197], v[96:99]
	v_mfma_f32_16x16x32_bf16 v[84:87], v[170:173], v[202:205], v[84:87]
	v_mfma_f32_16x16x32_bf16 v[80:83], v[178:181], v[202:205], v[80:83]
	v_mfma_f32_16x16x32_bf16 v[68:71], v[170:173], v[210:213], v[68:71]
	v_mfma_f32_16x16x32_bf16 v[64:67], v[178:181], v[210:213], v[64:67]
	v_mfma_f32_16x16x32_bf16 v[116:119], v[174:177], v[190:193], v[116:119]
	v_mfma_f32_16x16x32_bf16 v[112:115], v[182:185], v[190:193], v[112:115]
	v_mfma_f32_16x16x32_bf16 v[100:103], v[174:177], v[198:201], v[100:103]
	v_mfma_f32_16x16x32_bf16 v[96:99], v[182:185], v[198:201], v[96:99]
	v_mfma_f32_16x16x32_bf16 v[84:87], v[174:177], v[206:209], v[84:87]
	v_mfma_f32_16x16x32_bf16 v[80:83], v[182:185], v[206:209], v[80:83]
	v_mfma_f32_16x16x32_bf16 v[68:71], v[174:177], v[214:217], v[68:71]
	v_mfma_f32_16x16x32_bf16 v[64:67], v[182:185], v[214:217], v[64:67]
	s_setprio 0
	s_barrier
; #define PG8_STAGE(bufoff, gbase, voff) do { _Pragma("unroll") for (int _i = 0; _i < 2; ++_i) \
;         __builtin_amdgcn_global_load_lds((const unsigned*)((const char*)(gbase) + (voff)[_i]), (LAS unsigned*)(lds + (bufoff) + ldsw + _i * 8192), 16, 0, 0); } while (0)
; #define PG8_LDA(dst, b, h) do { _Pragma("unroll") for (int m = 0; m < 4; ++m) _Pragma("unroll") for (int k = 0; k < 2; ++k) dst[m][k] = *(const LAS bf16x8*)(lds + PG8_SA(b, h) + aoff + m * 2048 + k * 1024); } while (0)
; #define PG8_MMA(ai, bj, At, Bt) do { __builtin_amdgcn_s_setprio(1); _Pragma("unroll") for (int m = 0; m < 4; ++m) _Pragma("unroll") for (int n = 0; n < 2; ++n) _Pragma("unroll") for (int k = 0; k < 2; ++k) \
;         acc[ai][bj][m][n] = __builtin_amdgcn_mfma_f32_16x16x32_bf16(Bt[n][k], At[m][k], acc[ai][bj][m][n], 0, 0, 0); __builtin_amdgcn_s_setprio(0); } while (0)
; #define PG8_WAIT_V(n) asm volatile("s_waitcnt vmcnt(" #n ")" ::: "memory")
; #define PG8_WAIT_L(n) asm volatile("s_waitcnt lgkmcnt(" #n ")" ::: "memory")
; #define PG8_BAR __builtin_amdgcn_s_barrier()
; #define PG8_SCHED __builtin_amdgcn_sched_barrier(0)
; template <class Epi, class Sched, bool ALIGN_EPI>
; __device__ __forceinline__ void gemm_phase(LAS unsigned char* lds, const Gemm g, const Sched& S, const Epi& E) {
;     ...
;             PG8_LDA(At, 1, 1); PG8_STAGE(PG8_SB(1, 0), b3, voffB); PG8_STAGE(PG8_SB(1, 1), b3 + hstepB, voffB); PG8_STAGE(PG8_SA(1, 0), a3, voffA);
;             PG8_WAIT_V(8); PG8_WAIT_L(0); PG8_BAR; PG8_MMA(1, 0, At, B0); PG8_MMA(1, 1, At, B1); PG8_BAR; PG8_SCHED;
;         }
	s_add_i32 s64, s83, s33
	v_lshl_add_u64 v[220:221], v[220:221], 0, s[40:41]
	s_mov_b32 m0, s64
	ds_read_b128 v[186:189], v151 offset:49152
	ds_read_b128 v[190:193], v151 offset:50176
	ds_read_b128 v[194:197], v151 offset:51200
	ds_read_b128 v[198:201], v151 offset:52224
	ds_read_b128 v[202:205], v151 offset:53248
	ds_read_b128 v[206:209], v151 offset:54272
	ds_read_b128 v[210:213], v151 offset:55296
	ds_read_b128 v[214:217], v151 offset:56320
	global_load_lds_dwordx4 v[220:221], off
	v_lshl_add_u64 v[220:221], v[222:223], 0, s[40:41]
	s_add_i32 m0, s64, 0x2000
	s_add_i32 s64, s84, s33
	global_load_lds_dwordx4 v[220:221], off
	v_lshl_add_u64 v[220:221], v[224:225], 0, s[40:41]
	s_mov_b32 m0, s64
	s_nop 0
	global_load_lds_dwordx4 v[220:221], off
	v_lshl_add_u64 v[220:221], v[226:227], 0, s[40:41]
	s_add_i32 m0, s64, 0x2000
	s_nop 0
	global_load_lds_dwordx4 v[220:221], off
	v_lshl_add_u64 v[220:221], v[228:229], 0, s[40:41]
	s_mov_b32 m0, s67
	s_nop 0
	global_load_lds_dwordx4 v[220:221], off
	v_lshl_add_u64 v[220:221], v[230:231], 0, s[40:41]
	s_mov_b32 m0, s68
	s_nop 0
	global_load_lds_dwordx4 v[220:221], off
	s_waitcnt vmcnt(8)
	s_waitcnt lgkmcnt(0)
	s_barrier
	s_setprio 1
	v_mfma_f32_16x16x32_bf16 v[60:63], v[154:157], v[186:189], v[60:63]
	v_mfma_f32_16x16x32_bf16 v[56:59], v[162:165], v[186:189], v[56:59]
	v_mfma_f32_16x16x32_bf16 v[44:47], v[154:157], v[194:197], v[44:47]
	v_mfma_f32_16x16x32_bf16 v[40:43], v[162:165], v[194:197], v[40:43]
	v_mfma_f32_16x16x32_bf16 v[28:31], v[154:157], v[202:205], v[28:31]
	v_mfma_f32_16x16x32_bf16 v[24:27], v[162:165], v[202:205], v[24:27]
	v_mfma_f32_16x16x32_bf16 v[12:15], v[154:157], v[210:213], v[12:15]
	v_mfma_f32_16x16x32_bf16 v[8:11], v[162:165], v[210:213], v[8:11]
	v_mfma_f32_16x16x32_bf16 v[60:63], v[158:161], v[190:193], v[60:63]
	v_mfma_f32_16x16x32_bf16 v[56:59], v[166:169], v[190:193], v[56:59]
	v_mfma_f32_16x16x32_bf16 v[44:47], v[158:161], v[198:201], v[44:47]
	v_mfma_f32_16x16x32_bf16 v[40:43], v[166:169], v[198:201], v[40:43]
	v_mfma_f32_16x16x32_bf16 v[28:31], v[158:161], v[206:209], v[28:31]
	v_mfma_f32_16x16x32_bf16 v[24:27], v[166:169], v[206:209], v[24:27]
	v_mfma_f32_16x16x32_bf16 v[12:15], v[158:161], v[214:217], v[12:15]
	v_mfma_f32_16x16x32_bf16 v[8:11], v[166:169], v[214:217], v[8:11]
	s_setprio 0
	s_setprio 1
	v_mfma_f32_16x16x32_bf16 v[52:55], v[170:173], v[186:189], v[52:55]
	v_mfma_f32_16x16x32_bf16 v[48:51], v[178:181], v[186:189], v[48:51]
	v_mfma_f32_16x16x32_bf16 v[36:39], v[170:173], v[194:197], v[36:39]
	v_mfma_f32_16x16x32_bf16 v[32:35], v[178:181], v[194:197], v[32:35]
	v_mfma_f32_16x16x32_bf16 v[20:23], v[170:173], v[202:205], v[20:23]
	v_mfma_f32_16x16x32_bf16 v[16:19], v[178:181], v[202:205], v[16:19]
	v_mfma_f32_16x16x32_bf16 v[4:7], v[170:173], v[210:213], v[4:7]
	v_mfma_f32_16x16x32_bf16 v[0:3], v[178:181], v[210:213], v[0:3]
	v_mfma_f32_16x16x32_bf16 v[52:55], v[174:177], v[190:193], v[52:55]
	v_mfma_f32_16x16x32_bf16 v[48:51], v[182:185], v[190:193], v[48:51]
	v_mfma_f32_16x16x32_bf16 v[36:39], v[174:177], v[198:201], v[36:39]
	v_mfma_f32_16x16x32_bf16 v[32:35], v[182:185], v[198:201], v[32:35]
	v_mfma_f32_16x16x32_bf16 v[20:23], v[174:177], v[206:209], v[20:23]
	v_mfma_f32_16x16x32_bf16 v[16:19], v[182:185], v[206:209], v[16:19]
	v_mfma_f32_16x16x32_bf16 v[4:7], v[174:177], v[214:217], v[4:7]
	v_mfma_f32_16x16x32_bf16 v[0:3], v[182:185], v[214:217], v[0:3]
	s_setprio 0
	s_barrier
	s_add_u32 s80, s80, 0x100
	s_addc_u32 s81, s81, 0
	s_add_u32 s54, s54, 0x100
	s_addc_u32 s55, s55, 0
	s_cmp_ge_i32 s82, s69
	s_mov_b32 s64, s82
	s_cbranch_scc0 .LBB0_462

; #define PG8_STAGE(bufoff, gbase, voff) do { _Pragma("unroll") for (int _i = 0; _i < 2; ++_i) \
;         __builtin_amdgcn_global_load_lds((const unsigned*)((const char*)(gbase) + (voff)[_i]), (LAS unsigned*)(lds + (bufoff) + ldsw + _i * 8192), 16, 0, 0); } while (0)
; #define PG8_LDA(dst, b, h) do { _Pragma("unroll") for (int m = 0; m < 4; ++m) _Pragma("unroll") for (int k = 0; k < 2; ++k) dst[m][k] = *(const LAS bf16x8*)(lds + PG8_SA(b, h) + aoff + m * 2048 + k * 1024); } while (0)
; #define PG8_LDB(dst, b, h) do { _Pragma("unroll") for (int n = 0; n < 2; ++n) _Pragma("unroll") for (int k = 0; k < 2; ++k) dst[n][k] = *(const LAS bf16x8*)(lds + PG8_SB(b, h) + boff + n * 2048 + k * 1024); } while (0)
; #define PG8_MMA(ai, bj, At, Bt) do { __builtin_amdgcn_s_setprio(1); _Pragma("unroll") for (int m = 0; m < 4; ++m) _Pragma("unroll") for (int n = 0; n < 2; ++n) _Pragma("unroll") for (int k = 0; k < 2; ++k) \
;         acc[ai][bj][m][n] = __builtin_amdgcn_mfma_f32_16x16x32_bf16(Bt[n][k], At[m][k], acc[ai][bj][m][n], 0, 0, 0); __builtin_amdgcn_s_setprio(0); } while (0)
; #define PG8_WAIT_V(n) asm volatile("s_waitcnt vmcnt(" #n ")" ::: "memory")
; #define PG8_WAIT_L(n) asm volatile("s_waitcnt lgkmcnt(" #n ")" ::: "memory")
; #define PG8_BAR __builtin_amdgcn_s_barrier()
; #define PG8_SCHED __builtin_amdgcn_sched_barrier(0)
; template <class Epi, class Sched, bool ALIGN_EPI>
; __device__ __forceinline__ void gemm_phase(LAS unsigned char* lds, const Gemm g, const Sched& S, const Epi& E) {
;     ...
;         for (int t = 0; t < nt; t += 2) {
;             const bool last = (t == nt - 2);
;             const char* a1 = cA + (size_t)(t + 1) * kstep;
;             const char* a2 = last ? nA : cA + (size_t)(t + 2) * kstep; const char* b2 = last ? nB : cB + (size_t)(t + 2) * kstep;
;             const char* a3 = a2 + kstep; const char* b3 = b2 + kstep;
;             PG8_LDB(B0, 0, 0); PG8_LDB(B1, 0, 1); PG8_SCHED; PG8_LDA(At, 0, 0); PG8_STAGE(PG8_SA(1, 1), a1 + hstepA, voffA);
;             PG8_WAIT_V(8); PG8_WAIT_L(0); PG8_BAR; PG8_MMA(0, 0, At, B0); PG8_MMA(0, 1, At, B1); PG8_BAR; PG8_SCHED;
;             PG8_LDA(At, 0, 1); PG8_STAGE(PG8_SB(0, 0), b2, voffB); PG8_STAGE(PG8_SB(0, 1), b2 + hstepB, voffB); PG8_STAGE(PG8_SA(0, 0), a2, voffA);
;             PG8_WAIT_V(8); PG8_WAIT_L(0); PG8_BAR; PG8_MMA(1, 0, At, B0); PG8_MMA(1, 1, At, B1); PG8_BAR; PG8_SCHED;
.LBB0_540:
	ds_read_b128 v[52:55], v209
	ds_read_b128 v[56:59], v209 offset:1024
	ds_read_b128 v[64:67], v209 offset:2048
	ds_read_b128 v[72:75], v209 offset:3072
	ds_read_b128 v[76:79], v210
	ds_read_b128 v[84:87], v210 offset:1024
	ds_read_b128 v[88:91], v210 offset:2048
	ds_read_b128 v[96:99], v210 offset:3072
	s_add_i32 s77, s54, 2
	s_add_u32 s80, s52, 0x80
	s_addc_u32 s55, s53, 0
	s_cmp_eq_u32 s67, s54
	s_cselect_b32 s54, s43, s80
	s_cselect_b32 s55, s5, s55
	s_cselect_b32 s81, s45, s76
	s_cselect_b32 s80, s73, s75
	v_lshl_add_u64 v[224:225], s[52:53], 0, v[200:201]
	s_add_i32 m0, s51, 0xc000
	ds_read_b128 v[116:119], v211
	ds_read_b128 v[136:139], v211 offset:1024
	ds_read_b128 v[152:155], v211 offset:2048
	ds_read_b128 v[172:175], v211 offset:3072
	ds_read_b128 v[176:179], v211 offset:4096
	ds_read_b128 v[180:183], v211 offset:5120
	ds_read_b128 v[214:217], v211 offset:6144
	ds_read_b128 v[220:223], v211 offset:7168
	global_load_lds_dwordx4 v[224:225], off
	v_lshl_add_u64 v[224:225], s[52:53], 0, v[202:203]
	s_add_i32 m0, s51, 0xe000
	s_nop 0
	global_load_lds_dwordx4 v[224:225], off
	s_waitcnt vmcnt(8)
	s_waitcnt lgkmcnt(0)
	s_barrier
	s_setprio 1
	v_mfma_f32_16x16x32_bf16 v[168:171], v[52:55], v[116:119], v[168:171]
	v_mfma_f32_16x16x32_bf16 v[164:167], v[64:67], v[116:119], v[164:167]
	v_mfma_f32_16x16x32_bf16 v[148:151], v[52:55], v[152:155], v[148:151]
	v_mfma_f32_16x16x32_bf16 v[144:147], v[64:67], v[152:155], v[144:147]
	v_mfma_f32_16x16x32_bf16 v[128:131], v[52:55], v[176:179], v[128:131]
	v_mfma_f32_16x16x32_bf16 v[124:127], v[64:67], v[176:179], v[124:127]
	v_mfma_f32_16x16x32_bf16 v[108:111], v[52:55], v[214:217], v[108:111]
	v_mfma_f32_16x16x32_bf16 v[104:107], v[64:67], v[214:217], v[104:107]
	v_mfma_f32_16x16x32_bf16 v[168:171], v[56:59], v[136:139], v[168:171]
	v_mfma_f32_16x16x32_bf16 v[164:167], v[72:75], v[136:139], v[164:167]
	v_mfma_f32_16x16x32_bf16 v[148:151], v[56:59], v[172:175], v[148:151]
	v_mfma_f32_16x16x32_bf16 v[144:147], v[72:75], v[172:175], v[144:147]
	v_mfma_f32_16x16x32_bf16 v[128:131], v[56:59], v[180:183], v[128:131]
	v_mfma_f32_16x16x32_bf16 v[124:127], v[72:75], v[180:183], v[124:127]
	v_mfma_f32_16x16x32_bf16 v[108:111], v[56:59], v[220:223], v[108:111]
	v_mfma_f32_16x16x32_bf16 v[104:107], v[72:75], v[220:223], v[104:107]
	s_setprio 0
	s_setprio 1
	v_mfma_f32_16x16x32_bf16 v[156:159], v[76:79], v[116:119], v[156:159]
	v_mfma_f32_16x16x32_bf16 v[116:119], v[88:91], v[116:119], v[160:163]
	v_mfma_f32_16x16x32_bf16 v[132:135], v[76:79], v[152:155], v[132:135]
	v_mfma_f32_16x16x32_bf16 v[112:115], v[76:79], v[176:179], v[112:115]
	v_mfma_f32_16x16x32_bf16 v[120:123], v[88:91], v[176:179], v[120:123]
	v_mfma_f32_16x16x32_bf16 v[92:95], v[76:79], v[214:217], v[92:95]
	v_mfma_f32_16x16x32_bf16 v[100:103], v[88:91], v[214:217], v[100:103]
	v_mfma_f32_16x16x32_bf16 v[156:159], v[84:87], v[136:139], v[156:159]
	v_mfma_f32_16x16x32_bf16 v[116:119], v[96:99], v[136:139], v[116:119]
	v_mfma_f32_16x16x32_bf16 v[132:135], v[84:87], v[172:175], v[132:135]
	v_mfma_f32_16x16x32_bf16 v[136:139], v[88:91], v[152:155], v[140:143]
	v_mfma_f32_16x16x32_bf16 v[112:115], v[84:87], v[180:183], v[112:115]
	v_mfma_f32_16x16x32_bf16 v[120:123], v[96:99], v[180:183], v[120:123]
	v_mfma_f32_16x16x32_bf16 v[92:95], v[84:87], v[220:223], v[92:95]
	v_mfma_f32_16x16x32_bf16 v[100:103], v[96:99], v[220:223], v[100:103]
	v_mfma_f32_16x16x32_bf16 v[136:139], v[96:99], v[172:175], v[136:139]
	s_setprio 0
	s_barrier
	s_add_i32 s82, s70, s33
	v_lshl_add_u64 v[228:229], s[80:81], 0, v[186:187]
	s_mov_b32 m0, s82
	ds_read_b128 v[140:143], v211 offset:16384
	ds_read_b128 v[152:155], v211 offset:17408
	ds_read_b128 v[160:163], v211 offset:18432
	ds_read_b128 v[172:175], v211 offset:19456
	ds_read_b128 v[176:179], v211 offset:20480
	ds_read_b128 v[180:183], v211 offset:21504
	ds_read_b128 v[214:217], v211 offset:22528
	ds_read_b128 v[220:223], v211 offset:23552
	global_load_lds_dwordx4 v[228:229], off
	s_add_i32 m0, s82, 0x2000
	v_lshl_add_u64 v[230:231], s[80:81], 0, v[190:191]
	s_add_u32 s80, s80, s12
	s_addc_u32 s81, s81, s13
	s_add_i32 s82, s71, s33
	global_load_lds_dwordx4 v[230:231], off
	v_lshl_add_u64 v[232:233], s[80:81], 0, v[186:187]
	s_mov_b32 m0, s82
	v_lshl_add_u64 v[234:235], s[80:81], 0, v[190:191]
	global_load_lds_dwordx4 v[232:233], off
	s_add_i32 m0, s82, 0x2000
	v_lshl_add_u64 v[236:237], s[54:55], 0, v[184:185]
	global_load_lds_dwordx4 v[234:235], off
	s_mov_b32 m0, s51
	v_lshl_add_u64 v[238:239], s[54:55], 0, v[188:189]
	global_load_lds_dwordx4 v[236:237], off
	s_mov_b32 m0, s58
	s_nop 0
	global_load_lds_dwordx4 v[238:239], off
	s_waitcnt vmcnt(8)
	s_waitcnt lgkmcnt(0)
	s_barrier
; #define PG8_STAGE(bufoff, gbase, voff) do { _Pragma("unroll") for (int _i = 0; _i < 2; ++_i) \
;         __builtin_amdgcn_global_load_lds((const unsigned*)((const char*)(gbase) + (voff)[_i]), (LAS unsigned*)(lds + (bufoff) + ldsw + _i * 8192), 16, 0, 0); } while (0)
; #define PG8_LDA(dst, b, h) do { _Pragma("unroll") for (int m = 0; m < 4; ++m) _Pragma("unroll") for (int k = 0; k < 2; ++k) dst[m][k] = *(const LAS bf16x8*)(lds + PG8_SA(b, h) + aoff + m * 2048 + k * 1024); } while (0)
; #define PG8_LDB(dst, b, h) do { _Pragma("unroll") for (int n = 0; n < 2; ++n) _Pragma("unroll") for (int k = 0; k < 2; ++k) dst[n][k] = *(const LAS bf16x8*)(lds + PG8_SB(b, h) + boff + n * 2048 + k * 1024); } while (0)
; #define PG8_MMA(ai, bj, At, Bt) do { __builtin_amdgcn_s_setprio(1); _Pragma("unroll") for (int m = 0; m < 4; ++m) _Pragma("unroll") for (int n = 0; n < 2; ++n) _Pragma("unroll") for (int k = 0; k < 2; ++k) \
;         acc[ai][bj][m][n] = __builtin_amdgcn_mfma_f32_16x16x32_bf16(Bt[n][k], At[m][k], acc[ai][bj][m][n], 0, 0, 0); __builtin_amdgcn_s_setprio(0); } while (0)
; #define PG8_WAIT_V(n) asm volatile("s_waitcnt vmcnt(" #n ")" ::: "memory")
; #define PG8_WAIT_L(n) asm volatile("s_waitcnt lgkmcnt(" #n ")" ::: "memory")
; #define PG8_BAR __builtin_amdgcn_s_barrier()
; #define PG8_SCHED __builtin_amdgcn_sched_barrier(0)
; template <class Epi, class Sched, bool ALIGN_EPI>
; __device__ __forceinline__ void gemm_phase(LAS unsigned char* lds, const Gemm g, const Sched& S, const Epi& E) {
;     ...
;             PG8_WAIT_V(8); PG8_WAIT_L(0); PG8_BAR; PG8_MMA(1, 0, At, B0); PG8_MMA(1, 1, At, B1); PG8_BAR; PG8_SCHED;
;             PG8_LDB(B0, 1, 0); PG8_LDB(B1, 1, 1); PG8_SCHED; PG8_LDA(At, 1, 0); PG8_STAGE(PG8_SA(0, 1), a2 + hstepA, voffA);
;             PG8_WAIT_V(8); PG8_WAIT_L(0); PG8_BAR; PG8_MMA(0, 0, At, B0); PG8_MMA(0, 1, At, B1); PG8_BAR; PG8_SCHED;
	s_setprio 1
	v_mfma_f32_16x16x32_bf16 v[80:83], v[52:55], v[140:143], v[80:83]
	v_mfma_f32_16x16x32_bf16 v[68:71], v[64:67], v[140:143], v[68:71]
	v_mfma_f32_16x16x32_bf16 v[44:47], v[52:55], v[160:163], v[44:47]
	v_mfma_f32_16x16x32_bf16 v[40:43], v[64:67], v[160:163], v[40:43]
	v_mfma_f32_16x16x32_bf16 v[28:31], v[52:55], v[176:179], v[28:31]
	v_mfma_f32_16x16x32_bf16 v[24:27], v[64:67], v[176:179], v[24:27]
	v_mfma_f32_16x16x32_bf16 v[12:15], v[52:55], v[214:217], v[12:15]
	v_mfma_f32_16x16x32_bf16 v[8:11], v[64:67], v[214:217], v[8:11]
	v_mfma_f32_16x16x32_bf16 v[80:83], v[56:59], v[152:155], v[80:83]
	v_mfma_f32_16x16x32_bf16 v[68:71], v[72:75], v[152:155], v[68:71]
	v_mfma_f32_16x16x32_bf16 v[44:47], v[56:59], v[172:175], v[44:47]
	v_mfma_f32_16x16x32_bf16 v[40:43], v[72:75], v[172:175], v[40:43]
	v_mfma_f32_16x16x32_bf16 v[28:31], v[56:59], v[180:183], v[28:31]
	v_mfma_f32_16x16x32_bf16 v[24:27], v[72:75], v[180:183], v[24:27]
	v_mfma_f32_16x16x32_bf16 v[12:15], v[56:59], v[220:223], v[12:15]
	v_mfma_f32_16x16x32_bf16 v[8:11], v[72:75], v[220:223], v[8:11]
	s_setprio 0
	s_setprio 1
	v_mfma_f32_16x16x32_bf16 v[48:51], v[76:79], v[140:143], v[48:51]
	v_mfma_f32_16x16x32_bf16 v[32:35], v[76:79], v[160:163], v[32:35]
	v_mfma_f32_16x16x32_bf16 v[36:39], v[88:91], v[160:163], v[36:39]
	v_mfma_f32_16x16x32_bf16 v[16:19], v[76:79], v[176:179], v[16:19]
	v_mfma_f32_16x16x32_bf16 v[20:23], v[88:91], v[176:179], v[20:23]
	v_mfma_f32_16x16x32_bf16 v[4:7], v[76:79], v[214:217], v[4:7]
	v_mfma_f32_16x16x32_bf16 v[0:3], v[88:91], v[214:217], v[0:3]
	v_mfma_f32_16x16x32_bf16 v[48:51], v[84:87], v[152:155], v[48:51]
	v_mfma_f32_16x16x32_bf16 v[52:55], v[88:91], v[140:143], v[60:63]
	v_mfma_f32_16x16x32_bf16 v[32:35], v[84:87], v[172:175], v[32:35]
	v_mfma_f32_16x16x32_bf16 v[36:39], v[96:99], v[172:175], v[36:39]
	v_mfma_f32_16x16x32_bf16 v[16:19], v[84:87], v[180:183], v[16:19]
	v_mfma_f32_16x16x32_bf16 v[20:23], v[96:99], v[180:183], v[20:23]
	v_mfma_f32_16x16x32_bf16 v[4:7], v[84:87], v[220:223], v[4:7]
	v_mfma_f32_16x16x32_bf16 v[0:3], v[96:99], v[220:223], v[0:3]
	v_mfma_f32_16x16x32_bf16 v[52:55], v[96:99], v[152:155], v[52:55]
	s_setprio 0
	s_barrier
	s_add_i32 s80, 0, 0x18000
	s_add_i32 s81, 0, 0x1c000
	v_add_u32_e32 v72, s80, v208
	v_add_u32_e32 v96, s81, v208
	ds_read_b128 v[56:59], v72
	ds_read_b128 v[60:63], v72 offset:1024
	ds_read_b128 v[64:67], v72 offset:2048
	ds_read_b128 v[72:75], v72 offset:3072
	ds_read_b128 v[76:79], v96
	ds_read_b128 v[84:87], v96 offset:1024
	ds_read_b128 v[88:91], v96 offset:2048
	ds_read_b128 v[96:99], v96 offset:3072
	s_add_u32 s54, s54, s10
	s_addc_u32 s55, s55, s11
	s_mov_b32 m0, s59
	v_lshl_add_u64 v[160:161], s[54:55], 0, v[184:185]
	ds_read_b128 v[140:143], v211 offset:32768
	ds_read_b128 v[152:155], v211 offset:33792
	ds_read_b128 v[172:175], v211 offset:34816
	ds_read_b128 v[176:179], v211 offset:35840
	ds_read_b128 v[180:183], v211 offset:36864
	ds_read_b128 v[214:217], v211 offset:37888
	ds_read_b128 v[220:223], v211 offset:38912
	ds_read_b128 v[224:227], v211 offset:39936
	global_load_lds_dwordx4 v[160:161], off
	v_lshl_add_u64 v[160:161], s[54:55], 0, v[188:189]
	s_mov_b32 m0, s62
	s_nop 0
	global_load_lds_dwordx4 v[160:161], off
	s_waitcnt vmcnt(8)
	s_waitcnt lgkmcnt(0)
	s_barrier
	s_setprio 1
	v_mfma_f32_16x16x32_bf16 v[160:163], v[56:59], v[140:143], v[168:171]
	v_mfma_f32_16x16x32_bf16 v[168:171], v[60:63], v[152:155], v[160:163]
	v_mfma_f32_16x16x32_bf16 v[160:163], v[64:67], v[140:143], v[164:167]
	v_mfma_f32_16x16x32_bf16 v[148:151], v[56:59], v[172:175], v[148:151]
	v_mfma_f32_16x16x32_bf16 v[144:147], v[64:67], v[172:175], v[144:147]
	v_mfma_f32_16x16x32_bf16 v[128:131], v[56:59], v[180:183], v[128:131]
	v_mfma_f32_16x16x32_bf16 v[124:127], v[64:67], v[180:183], v[124:127]
	v_mfma_f32_16x16x32_bf16 v[108:111], v[56:59], v[220:223], v[108:111]
	v_mfma_f32_16x16x32_bf16 v[104:107], v[64:67], v[220:223], v[104:107]
	v_mfma_f32_16x16x32_bf16 v[164:167], v[72:75], v[152:155], v[160:163]
	v_mfma_f32_16x16x32_bf16 v[148:151], v[60:63], v[176:179], v[148:151]
	v_mfma_f32_16x16x32_bf16 v[144:147], v[72:75], v[176:179], v[144:147]
	v_mfma_f32_16x16x32_bf16 v[128:131], v[60:63], v[214:217], v[128:131]
	v_mfma_f32_16x16x32_bf16 v[124:127], v[72:75], v[214:217], v[124:127]
	v_mfma_f32_16x16x32_bf16 v[108:111], v[60:63], v[224:227], v[108:111]
	v_mfma_f32_16x16x32_bf16 v[104:107], v[72:75], v[224:227], v[104:107]
	s_setprio 0
	s_setprio 1
	v_mfma_f32_16x16x32_bf16 v[116:119], v[88:91], v[140:143], v[116:119]
	v_mfma_f32_16x16x32_bf16 v[160:163], v[96:99], v[152:155], v[116:119]
	v_mfma_f32_16x16x32_bf16 v[116:119], v[76:79], v[172:175], v[132:135]
	v_mfma_f32_16x16x32_bf16 v[132:135], v[84:87], v[176:179], v[116:119]
	v_mfma_f32_16x16x32_bf16 v[116:119], v[88:91], v[172:175], v[136:139]
	v_mfma_f32_16x16x32_bf16 v[156:159], v[76:79], v[140:143], v[156:159]
	v_mfma_f32_16x16x32_bf16 v[140:143], v[96:99], v[176:179], v[116:119]
	v_mfma_f32_16x16x32_bf16 v[112:115], v[76:79], v[180:183], v[112:115]
	v_mfma_f32_16x16x32_bf16 v[116:119], v[88:91], v[180:183], v[120:123]
	v_mfma_f32_16x16x32_bf16 v[92:95], v[76:79], v[220:223], v[92:95]
	v_mfma_f32_16x16x32_bf16 v[100:103], v[88:91], v[220:223], v[100:103]
	v_mfma_f32_16x16x32_bf16 v[156:159], v[84:87], v[152:155], v[156:159]
	v_mfma_f32_16x16x32_bf16 v[112:115], v[84:87], v[214:217], v[112:115]
	v_mfma_f32_16x16x32_bf16 v[120:123], v[96:99], v[214:217], v[116:119]
	v_mfma_f32_16x16x32_bf16 v[92:95], v[84:87], v[224:227], v[92:95]
	v_mfma_f32_16x16x32_bf16 v[100:103], v[96:99], v[224:227], v[100:103]
	s_setprio 0
	s_barrier
; #define PG8_STAGE(bufoff, gbase, voff) do { _Pragma("unroll") for (int _i = 0; _i < 2; ++_i) \
;         __builtin_amdgcn_global_load_lds((const unsigned*)((const char*)(gbase) + (voff)[_i]), (LAS unsigned*)(lds + (bufoff) + ldsw + _i * 8192), 16, 0, 0); } while (0)
; #define PG8_LDA(dst, b, h) do { _Pragma("unroll") for (int m = 0; m < 4; ++m) _Pragma("unroll") for (int k = 0; k < 2; ++k) dst[m][k] = *(const LAS bf16x8*)(lds + PG8_SA(b, h) + aoff + m * 2048 + k * 1024); } while (0)
; #define PG8_MMA(ai, bj, At, Bt) do { __builtin_amdgcn_s_setprio(1); _Pragma("unroll") for (int m = 0; m < 4; ++m) _Pragma("unroll") for (int n = 0; n < 2; ++n) _Pragma("unroll") for (int k = 0; k < 2; ++k) \
;         acc[ai][bj][m][n] = __builtin_amdgcn_mfma_f32_16x16x32_bf16(Bt[n][k], At[m][k], acc[ai][bj][m][n], 0, 0, 0); __builtin_amdgcn_s_setprio(0); } while (0)
; #define PG8_WAIT_V(n) asm volatile("s_waitcnt vmcnt(" #n ")" ::: "memory")
; #define PG8_WAIT_L(n) asm volatile("s_waitcnt lgkmcnt(" #n ")" ::: "memory")
; #define PG8_BAR __builtin_amdgcn_s_barrier()
; #define PG8_SCHED __builtin_amdgcn_sched_barrier(0)
; template <class Epi, class Sched, bool ALIGN_EPI>
; __device__ __forceinline__ void gemm_phase(LAS unsigned char* lds, const Gemm g, const Sched& S, const Epi& E) {
;     ...
;             PG8_LDA(At, 1, 1); PG8_STAGE(PG8_SB(1, 0), b3, voffB); PG8_STAGE(PG8_SB(1, 1), b3 + hstepB, voffB); PG8_STAGE(PG8_SA(1, 0), a3, voffA);
;             PG8_WAIT_V(8); PG8_WAIT_L(0); PG8_BAR; PG8_MMA(1, 0, At, B0); PG8_MMA(1, 1, At, B1); PG8_BAR; PG8_SCHED;
;         }
	s_add_i32 s54, s80, s33
	v_lshl_add_u64 v[224:225], v[228:229], 0, s[30:31]
	s_mov_b32 m0, s54
	ds_read_b128 v[116:119], v211 offset:49152
	ds_read_b128 v[136:139], v211 offset:50176
	ds_read_b128 v[152:155], v211 offset:51200
	ds_read_b128 v[172:175], v211 offset:52224
	ds_read_b128 v[176:179], v211 offset:53248
	ds_read_b128 v[180:183], v211 offset:54272
	ds_read_b128 v[214:217], v211 offset:55296
	ds_read_b128 v[220:223], v211 offset:56320
	global_load_lds_dwordx4 v[224:225], off
	v_lshl_add_u64 v[224:225], v[230:231], 0, s[30:31]
	s_add_i32 m0, s54, 0x2000
	s_add_i32 s54, s81, s33
	global_load_lds_dwordx4 v[224:225], off
	v_lshl_add_u64 v[224:225], v[232:233], 0, s[30:31]
	s_mov_b32 m0, s54
	s_nop 0
	global_load_lds_dwordx4 v[224:225], off
	v_lshl_add_u64 v[224:225], v[234:235], 0, s[30:31]
	s_add_i32 m0, s54, 0x2000
	s_nop 0
	global_load_lds_dwordx4 v[224:225], off
	v_lshl_add_u64 v[224:225], v[236:237], 0, s[30:31]
	s_mov_b32 m0, s64
	s_nop 0
	global_load_lds_dwordx4 v[224:225], off
	v_lshl_add_u64 v[224:225], v[238:239], 0, s[30:31]
	s_mov_b32 m0, s65
	s_nop 0
	global_load_lds_dwordx4 v[224:225], off
	s_waitcnt vmcnt(8)
	s_waitcnt lgkmcnt(0)
	s_barrier
	s_setprio 1
	v_mfma_f32_16x16x32_bf16 v[80:83], v[56:59], v[116:119], v[80:83]
	v_mfma_f32_16x16x32_bf16 v[68:71], v[64:67], v[116:119], v[68:71]
	v_mfma_f32_16x16x32_bf16 v[44:47], v[56:59], v[152:155], v[44:47]
	v_mfma_f32_16x16x32_bf16 v[40:43], v[64:67], v[152:155], v[40:43]
	v_mfma_f32_16x16x32_bf16 v[28:31], v[56:59], v[176:179], v[28:31]
	v_mfma_f32_16x16x32_bf16 v[24:27], v[64:67], v[176:179], v[24:27]
	v_mfma_f32_16x16x32_bf16 v[12:15], v[56:59], v[214:217], v[12:15]
	v_mfma_f32_16x16x32_bf16 v[8:11], v[64:67], v[214:217], v[8:11]
	v_mfma_f32_16x16x32_bf16 v[80:83], v[60:63], v[136:139], v[80:83]
	v_mfma_f32_16x16x32_bf16 v[68:71], v[72:75], v[136:139], v[68:71]
	v_mfma_f32_16x16x32_bf16 v[44:47], v[60:63], v[172:175], v[44:47]
	v_mfma_f32_16x16x32_bf16 v[40:43], v[72:75], v[172:175], v[40:43]
	v_mfma_f32_16x16x32_bf16 v[28:31], v[60:63], v[180:183], v[28:31]
	v_mfma_f32_16x16x32_bf16 v[24:27], v[72:75], v[180:183], v[24:27]
	v_mfma_f32_16x16x32_bf16 v[12:15], v[60:63], v[220:223], v[12:15]
	v_mfma_f32_16x16x32_bf16 v[8:11], v[72:75], v[220:223], v[8:11]
	s_setprio 0
	s_setprio 1
	v_mfma_f32_16x16x32_bf16 v[48:51], v[76:79], v[116:119], v[48:51]
	v_mfma_f32_16x16x32_bf16 v[52:55], v[88:91], v[116:119], v[52:55]
	v_mfma_f32_16x16x32_bf16 v[32:35], v[76:79], v[152:155], v[32:35]
	v_mfma_f32_16x16x32_bf16 v[36:39], v[88:91], v[152:155], v[36:39]
	v_mfma_f32_16x16x32_bf16 v[16:19], v[76:79], v[176:179], v[16:19]
	v_mfma_f32_16x16x32_bf16 v[20:23], v[88:91], v[176:179], v[20:23]
	v_mfma_f32_16x16x32_bf16 v[4:7], v[76:79], v[214:217], v[4:7]
	v_mfma_f32_16x16x32_bf16 v[0:3], v[88:91], v[214:217], v[0:3]
	v_mfma_f32_16x16x32_bf16 v[48:51], v[84:87], v[136:139], v[48:51]
	v_mfma_f32_16x16x32_bf16 v[60:63], v[96:99], v[136:139], v[52:55]
	v_mfma_f32_16x16x32_bf16 v[32:35], v[84:87], v[172:175], v[32:35]
	v_mfma_f32_16x16x32_bf16 v[36:39], v[96:99], v[172:175], v[36:39]
	v_mfma_f32_16x16x32_bf16 v[16:19], v[84:87], v[180:183], v[16:19]
	v_mfma_f32_16x16x32_bf16 v[20:23], v[96:99], v[180:183], v[20:23]
	v_mfma_f32_16x16x32_bf16 v[4:7], v[84:87], v[220:223], v[4:7]
	v_mfma_f32_16x16x32_bf16 v[0:3], v[96:99], v[220:223], v[0:3]
	s_setprio 0
	s_barrier
	s_add_u32 s75, s75, 0x100
	s_addc_u32 s76, s76, 0
	s_add_u32 s52, s52, 0x100
	s_addc_u32 s53, s53, 0
	s_cmp_ge_i32 s77, s66
	s_mov_b32 s54, s77
	s_cbranch_scc0 .LBB0_540
	v_readlane_b32 s68, v252, 34
	v_readlane_b32 s69, v252, 35

; #define PG8_STAGE(bufoff, gbase, voff) do { _Pragma("unroll") for (int _i = 0; _i < 2; ++_i) \
;         __builtin_amdgcn_global_load_lds((const unsigned*)((const char*)(gbase) + (voff)[_i]), (LAS unsigned*)(lds + (bufoff) + ldsw + _i * 8192), 16, 0, 0); } while (0)
; #define PG8_LDA(dst, b, h) do { _Pragma("unroll") for (int m = 0; m < 4; ++m) _Pragma("unroll") for (int k = 0; k < 2; ++k) dst[m][k] = *(const LAS bf16x8*)(lds + PG8_SA(b, h) + aoff + m * 2048 + k * 1024); } while (0)
; #define PG8_LDB(dst, b, h) do { _Pragma("unroll") for (int n = 0; n < 2; ++n) _Pragma("unroll") for (int k = 0; k < 2; ++k) dst[n][k] = *(const LAS bf16x8*)(lds + PG8_SB(b, h) + boff + n * 2048 + k * 1024); } while (0)
; #define PG8_MMA(ai, bj, At, Bt) do { __builtin_amdgcn_s_setprio(1); _Pragma("unroll") for (int m = 0; m < 4; ++m) _Pragma("unroll") for (int n = 0; n < 2; ++n) _Pragma("unroll") for (int k = 0; k < 2; ++k) \
;         acc[ai][bj][m][n] = __builtin_amdgcn_mfma_f32_16x16x32_bf16(Bt[n][k], At[m][k], acc[ai][bj][m][n], 0, 0, 0); __builtin_amdgcn_s_setprio(0); } while (0)
; #define PG8_WAIT_V(n) asm volatile("s_waitcnt vmcnt(" #n ")" ::: "memory")
; #define PG8_WAIT_L(n) asm volatile("s_waitcnt lgkmcnt(" #n ")" ::: "memory")
; #define PG8_BAR __builtin_amdgcn_s_barrier()
; #define PG8_SCHED __builtin_amdgcn_sched_barrier(0)
; template <class Epi, class Sched, bool ALIGN_EPI>
; __device__ __forceinline__ void gemm_phase(LAS unsigned char* lds, const Gemm g, const Sched& S, const Epi& E) {
;     ...
;         for (int t = 0; t < nt; t += 2) {
;             const bool last = (t == nt - 2);
;             const char* a1 = cA + (size_t)(t + 1) * kstep;
;             const char* a2 = last ? nA : cA + (size_t)(t + 2) * kstep; const char* b2 = last ? nB : cB + (size_t)(t + 2) * kstep;
;             const char* a3 = a2 + kstep; const char* b3 = b2 + kstep;
;             PG8_LDB(B0, 0, 0); PG8_LDB(B1, 0, 1); PG8_SCHED; PG8_LDA(At, 0, 0); PG8_STAGE(PG8_SA(1, 1), a1 + hstepA, voffA);
;             PG8_WAIT_V(8); PG8_WAIT_L(0); PG8_BAR; PG8_MMA(0, 0, At, B0); PG8_MMA(0, 1, At, B1); PG8_BAR; PG8_SCHED;
;             PG8_LDA(At, 0, 1); PG8_STAGE(PG8_SB(0, 0), b2, voffB); PG8_STAGE(PG8_SB(0, 1), b2 + hstepB, voffB); PG8_STAGE(PG8_SA(0, 0), a2, voffA);
;             PG8_WAIT_V(8); PG8_WAIT_L(0); PG8_BAR; PG8_MMA(1, 0, At, B0); PG8_MMA(1, 1, At, B1); PG8_BAR; PG8_SCHED;
.LBB0_889:
	v_add_u32_e32 v0, s65, v219
	ds_read_b128 v[132:135], v0
	ds_read_b128 v[136:139], v0 offset:1024
	ds_read_b128 v[140:143], v0 offset:2048
	ds_read_b128 v[144:147], v0 offset:3072
	v_add_u32_e32 v0, s66, v219
	ds_read_b128 v[148:151], v0
	ds_read_b128 v[152:155], v0 offset:1024
	ds_read_b128 v[156:159], v0 offset:2048
	ds_read_b128 v[160:163], v0 offset:3072
	s_add_i32 s72, s52, 2
	s_add_u32 s73, s50, 0x80
	s_addc_u32 s53, s51, 0
	s_cmp_eq_u32 s63, s52
	s_cselect_b32 s52, s43, s73
	s_cselect_b32 s53, s7, s53
	s_cselect_b32 s75, s45, s71
	s_cselect_b32 s74, s69, s70
	v_lshl_add_u64 v[2:3], s[50:51], 0, v[204:205]
	s_add_i32 m0, s54, 0xc000
	ds_read_b128 v[164:167], v222
	ds_read_b128 v[168:171], v222 offset:1024
	ds_read_b128 v[172:175], v222 offset:2048
	ds_read_b128 v[176:179], v222 offset:3072
	ds_read_b128 v[180:183], v222 offset:4096
	ds_read_b128 v[184:187], v222 offset:5120
	ds_read_b128 v[188:191], v222 offset:6144
	ds_read_b128 v[192:195], v222 offset:7168
	global_load_lds_dwordx4 v[2:3], off
	v_lshl_add_u64 v[2:3], s[50:51], 0, v[206:207]
	s_add_i32 m0, s54, 0xe000
	s_nop 0
	global_load_lds_dwordx4 v[2:3], off
	s_waitcnt vmcnt(8)
	s_waitcnt lgkmcnt(0)
	s_barrier
	s_setprio 1
	v_mfma_f32_16x16x32_bf16 v[128:131], v[132:135], v[164:167], v[128:131]
	v_mfma_f32_16x16x32_bf16 v[124:127], v[140:143], v[164:167], v[124:127]
	v_mfma_f32_16x16x32_bf16 v[120:123], v[132:135], v[172:175], v[120:123]
	v_mfma_f32_16x16x32_bf16 v[116:119], v[140:143], v[172:175], v[116:119]
	v_mfma_f32_16x16x32_bf16 v[112:115], v[132:135], v[180:183], v[112:115]
	v_mfma_f32_16x16x32_bf16 v[108:111], v[140:143], v[180:183], v[108:111]
	v_mfma_f32_16x16x32_bf16 v[104:107], v[132:135], v[188:191], v[104:107]
	v_mfma_f32_16x16x32_bf16 v[100:103], v[140:143], v[188:191], v[100:103]
	v_mfma_f32_16x16x32_bf16 v[128:131], v[136:139], v[168:171], v[128:131]
	v_mfma_f32_16x16x32_bf16 v[124:127], v[144:147], v[168:171], v[124:127]
	v_mfma_f32_16x16x32_bf16 v[120:123], v[136:139], v[176:179], v[120:123]
	v_mfma_f32_16x16x32_bf16 v[116:119], v[144:147], v[176:179], v[116:119]
	v_mfma_f32_16x16x32_bf16 v[112:115], v[136:139], v[184:187], v[112:115]
	v_mfma_f32_16x16x32_bf16 v[108:111], v[144:147], v[184:187], v[108:111]
	v_mfma_f32_16x16x32_bf16 v[104:107], v[136:139], v[192:195], v[104:107]
	v_mfma_f32_16x16x32_bf16 v[100:103], v[144:147], v[192:195], v[100:103]
	s_setprio 0
	s_setprio 1
	v_mfma_f32_16x16x32_bf16 v[96:99], v[148:151], v[164:167], v[96:99]
	v_mfma_f32_16x16x32_bf16 v[92:95], v[156:159], v[164:167], v[92:95]
	v_mfma_f32_16x16x32_bf16 v[88:91], v[148:151], v[172:175], v[88:91]
	v_mfma_f32_16x16x32_bf16 v[84:87], v[156:159], v[172:175], v[84:87]
	v_mfma_f32_16x16x32_bf16 v[80:83], v[148:151], v[180:183], v[80:83]
	v_mfma_f32_16x16x32_bf16 v[76:79], v[156:159], v[180:183], v[76:79]
	v_mfma_f32_16x16x32_bf16 v[72:75], v[148:151], v[188:191], v[72:75]
	v_mfma_f32_16x16x32_bf16 v[68:71], v[156:159], v[188:191], v[68:71]
	v_mfma_f32_16x16x32_bf16 v[96:99], v[152:155], v[168:171], v[96:99]
	v_mfma_f32_16x16x32_bf16 v[92:95], v[160:163], v[168:171], v[92:95]
	v_mfma_f32_16x16x32_bf16 v[88:91], v[152:155], v[176:179], v[88:91]
	v_mfma_f32_16x16x32_bf16 v[84:87], v[160:163], v[176:179], v[84:87]
	v_mfma_f32_16x16x32_bf16 v[80:83], v[152:155], v[184:187], v[80:83]
	v_mfma_f32_16x16x32_bf16 v[76:79], v[160:163], v[184:187], v[76:79]
	v_mfma_f32_16x16x32_bf16 v[72:75], v[152:155], v[192:195], v[72:75]
	v_mfma_f32_16x16x32_bf16 v[68:71], v[160:163], v[192:195], v[68:71]
	s_setprio 0
	s_barrier
	s_add_i32 s73, s65, s33
	v_lshl_add_u64 v[212:213], s[74:75], 0, v[198:199]
	s_mov_b32 m0, s73
	ds_read_b128 v[164:167], v222 offset:16384
	ds_read_b128 v[168:171], v222 offset:17408
	ds_read_b128 v[172:175], v222 offset:18432
	ds_read_b128 v[176:179], v222 offset:19456
	ds_read_b128 v[180:183], v222 offset:20480
	ds_read_b128 v[184:187], v222 offset:21504
	ds_read_b128 v[188:191], v222 offset:22528
	ds_read_b128 v[192:195], v222 offset:23552
	global_load_lds_dwordx4 v[212:213], off
	s_add_i32 m0, s73, 0x2000
	v_lshl_add_u64 v[214:215], s[74:75], 0, v[202:203]
	s_add_u32 s74, s74, s26
	s_addc_u32 s75, s75, s27
	s_add_i32 s73, s66, s33
	global_load_lds_dwordx4 v[214:215], off
	v_lshl_add_u64 v[216:217], s[74:75], 0, v[198:199]
	s_mov_b32 m0, s73
	v_lshl_add_u64 v[224:225], s[74:75], 0, v[202:203]
	global_load_lds_dwordx4 v[216:217], off
	s_add_i32 m0, s73, 0x2000
	v_lshl_add_u64 v[226:227], s[52:53], 0, v[196:197]
	global_load_lds_dwordx4 v[224:225], off
	s_mov_b32 m0, s54
	v_lshl_add_u64 v[228:229], s[52:53], 0, v[200:201]
	global_load_lds_dwordx4 v[226:227], off
	s_mov_b32 m0, s55
	s_nop 0
	global_load_lds_dwordx4 v[228:229], off
	s_waitcnt vmcnt(8)
	s_waitcnt lgkmcnt(0)
	s_barrier
; #define PG8_STAGE(bufoff, gbase, voff) do { _Pragma("unroll") for (int _i = 0; _i < 2; ++_i) \
;         __builtin_amdgcn_global_load_lds((const unsigned*)((const char*)(gbase) + (voff)[_i]), (LAS unsigned*)(lds + (bufoff) + ldsw + _i * 8192), 16, 0, 0); } while (0)
; #define PG8_LDA(dst, b, h) do { _Pragma("unroll") for (int m = 0; m < 4; ++m) _Pragma("unroll") for (int k = 0; k < 2; ++k) dst[m][k] = *(const LAS bf16x8*)(lds + PG8_SA(b, h) + aoff + m * 2048 + k * 1024); } while (0)
; #define PG8_LDB(dst, b, h) do { _Pragma("unroll") for (int n = 0; n < 2; ++n) _Pragma("unroll") for (int k = 0; k < 2; ++k) dst[n][k] = *(const LAS bf16x8*)(lds + PG8_SB(b, h) + boff + n * 2048 + k * 1024); } while (0)
; #define PG8_MMA(ai, bj, At, Bt) do { __builtin_amdgcn_s_setprio(1); _Pragma("unroll") for (int m = 0; m < 4; ++m) _Pragma("unroll") for (int n = 0; n < 2; ++n) _Pragma("unroll") for (int k = 0; k < 2; ++k) \
;         acc[ai][bj][m][n] = __builtin_amdgcn_mfma_f32_16x16x32_bf16(Bt[n][k], At[m][k], acc[ai][bj][m][n], 0, 0, 0); __builtin_amdgcn_s_setprio(0); } while (0)
; #define PG8_WAIT_V(n) asm volatile("s_waitcnt vmcnt(" #n ")" ::: "memory")
; #define PG8_WAIT_L(n) asm volatile("s_waitcnt lgkmcnt(" #n ")" ::: "memory")
; #define PG8_BAR __builtin_amdgcn_s_barrier()
; #define PG8_SCHED __builtin_amdgcn_sched_barrier(0)
; template <class Epi, class Sched, bool ALIGN_EPI>
; __device__ __forceinline__ void gemm_phase(LAS unsigned char* lds, const Gemm g, const Sched& S, const Epi& E) {
;     ...
;             PG8_WAIT_V(8); PG8_WAIT_L(0); PG8_BAR; PG8_MMA(1, 0, At, B0); PG8_MMA(1, 1, At, B1); PG8_BAR; PG8_SCHED;
;             PG8_LDB(B0, 1, 0); PG8_LDB(B1, 1, 1); PG8_SCHED; PG8_LDA(At, 1, 0); PG8_STAGE(PG8_SA(0, 1), a2 + hstepA, voffA);
;             PG8_WAIT_V(8); PG8_WAIT_L(0); PG8_BAR; PG8_MMA(0, 0, At, B0); PG8_MMA(0, 1, At, B1); PG8_BAR; PG8_SCHED;
	s_setprio 1
	v_mfma_f32_16x16x32_bf16 v[64:67], v[132:135], v[164:167], v[64:67]
	v_mfma_f32_16x16x32_bf16 v[60:63], v[140:143], v[164:167], v[60:63]
	v_mfma_f32_16x16x32_bf16 v[56:59], v[132:135], v[172:175], v[56:59]
	v_mfma_f32_16x16x32_bf16 v[52:55], v[140:143], v[172:175], v[52:55]
	v_mfma_f32_16x16x32_bf16 v[48:51], v[132:135], v[180:183], v[48:51]
	v_mfma_f32_16x16x32_bf16 v[44:47], v[140:143], v[180:183], v[44:47]
	v_mfma_f32_16x16x32_bf16 v[40:43], v[132:135], v[188:191], v[40:43]
	v_mfma_f32_16x16x32_bf16 v[36:39], v[140:143], v[188:191], v[36:39]
	v_mfma_f32_16x16x32_bf16 v[64:67], v[136:139], v[168:171], v[64:67]
	v_mfma_f32_16x16x32_bf16 v[60:63], v[144:147], v[168:171], v[60:63]
	v_mfma_f32_16x16x32_bf16 v[56:59], v[136:139], v[176:179], v[56:59]
	v_mfma_f32_16x16x32_bf16 v[52:55], v[144:147], v[176:179], v[52:55]
	v_mfma_f32_16x16x32_bf16 v[48:51], v[136:139], v[184:187], v[48:51]
	v_mfma_f32_16x16x32_bf16 v[44:47], v[144:147], v[184:187], v[44:47]
	v_mfma_f32_16x16x32_bf16 v[40:43], v[136:139], v[192:195], v[40:43]
	v_mfma_f32_16x16x32_bf16 v[36:39], v[144:147], v[192:195], v[36:39]
	s_setprio 0
	s_setprio 1
	v_mfma_f32_16x16x32_bf16 v[32:35], v[148:151], v[164:167], v[32:35]
	v_mfma_f32_16x16x32_bf16 v[28:31], v[156:159], v[164:167], v[28:31]
	v_mfma_f32_16x16x32_bf16 v[24:27], v[148:151], v[172:175], v[24:27]
	v_mfma_f32_16x16x32_bf16 v[20:23], v[156:159], v[172:175], v[20:23]
	v_mfma_f32_16x16x32_bf16 v[16:19], v[148:151], v[180:183], v[16:19]
	v_mfma_f32_16x16x32_bf16 v[12:15], v[156:159], v[180:183], v[12:15]
	v_mfma_f32_16x16x32_bf16 v[8:11], v[148:151], v[188:191], v[8:11]
	v_mfma_f32_16x16x32_bf16 v[2:5], v[156:159], v[188:191], v[4:7]
	v_mfma_f32_16x16x32_bf16 v[32:35], v[152:155], v[168:171], v[32:35]
	v_mfma_f32_16x16x32_bf16 v[28:31], v[160:163], v[168:171], v[28:31]
	v_mfma_f32_16x16x32_bf16 v[24:27], v[152:155], v[176:179], v[24:27]
	v_mfma_f32_16x16x32_bf16 v[20:23], v[160:163], v[176:179], v[20:23]
	v_mfma_f32_16x16x32_bf16 v[16:19], v[152:155], v[184:187], v[16:19]
	v_mfma_f32_16x16x32_bf16 v[12:15], v[160:163], v[184:187], v[12:15]
	v_mfma_f32_16x16x32_bf16 v[8:11], v[152:155], v[192:195], v[8:11]
	v_mfma_f32_16x16x32_bf16 v[2:5], v[160:163], v[192:195], v[2:5]
	s_setprio 0
	s_barrier
	s_add_i32 s73, 0, 0x18000
	v_add_u32_e32 v0, s73, v219
	s_add_i32 s74, 0, 0x1c000
	ds_read_b128 v[132:135], v0
	ds_read_b128 v[136:139], v0 offset:1024
	ds_read_b128 v[140:143], v0 offset:2048
	ds_read_b128 v[144:147], v0 offset:3072
	v_add_u32_e32 v0, s74, v219
	ds_read_b128 v[148:151], v0
	ds_read_b128 v[152:155], v0 offset:1024
	ds_read_b128 v[156:159], v0 offset:2048
	ds_read_b128 v[160:163], v0 offset:3072
	s_add_u32 s52, s52, s24
	s_addc_u32 s53, s53, s25
	s_mov_b32 m0, s58
	v_lshl_add_u64 v[6:7], s[52:53], 0, v[196:197]
	ds_read_b128 v[164:167], v222 offset:32768
	ds_read_b128 v[168:171], v222 offset:33792
	ds_read_b128 v[172:175], v222 offset:34816
	ds_read_b128 v[176:179], v222 offset:35840
	ds_read_b128 v[180:183], v222 offset:36864
	ds_read_b128 v[184:187], v222 offset:37888
	ds_read_b128 v[188:191], v222 offset:38912
	ds_read_b128 v[192:195], v222 offset:39936
	global_load_lds_dwordx4 v[6:7], off
	v_lshl_add_u64 v[6:7], s[52:53], 0, v[200:201]
	s_mov_b32 m0, s59
	s_nop 0
	global_load_lds_dwordx4 v[6:7], off
	s_waitcnt vmcnt(8)
	s_waitcnt lgkmcnt(0)
	s_barrier
	s_setprio 1
	v_mfma_f32_16x16x32_bf16 v[128:131], v[132:135], v[164:167], v[128:131]
	v_mfma_f32_16x16x32_bf16 v[124:127], v[140:143], v[164:167], v[124:127]
	v_mfma_f32_16x16x32_bf16 v[120:123], v[132:135], v[172:175], v[120:123]
	v_mfma_f32_16x16x32_bf16 v[116:119], v[140:143], v[172:175], v[116:119]
	v_mfma_f32_16x16x32_bf16 v[112:115], v[132:135], v[180:183], v[112:115]
	v_mfma_f32_16x16x32_bf16 v[108:111], v[140:143], v[180:183], v[108:111]
	v_mfma_f32_16x16x32_bf16 v[104:107], v[132:135], v[188:191], v[104:107]
	v_mfma_f32_16x16x32_bf16 v[100:103], v[140:143], v[188:191], v[100:103]
	v_mfma_f32_16x16x32_bf16 v[128:131], v[136:139], v[168:171], v[128:131]
	v_mfma_f32_16x16x32_bf16 v[124:127], v[144:147], v[168:171], v[124:127]
	v_mfma_f32_16x16x32_bf16 v[120:123], v[136:139], v[176:179], v[120:123]
	v_mfma_f32_16x16x32_bf16 v[116:119], v[144:147], v[176:179], v[116:119]
	v_mfma_f32_16x16x32_bf16 v[112:115], v[136:139], v[184:187], v[112:115]
	v_mfma_f32_16x16x32_bf16 v[108:111], v[144:147], v[184:187], v[108:111]
	v_mfma_f32_16x16x32_bf16 v[104:107], v[136:139], v[192:195], v[104:107]
	v_mfma_f32_16x16x32_bf16 v[100:103], v[144:147], v[192:195], v[100:103]
	s_setprio 0
	s_setprio 1
	v_mfma_f32_16x16x32_bf16 v[96:99], v[148:151], v[164:167], v[96:99]
	v_mfma_f32_16x16x32_bf16 v[92:95], v[156:159], v[164:167], v[92:95]
	v_mfma_f32_16x16x32_bf16 v[88:91], v[148:151], v[172:175], v[88:91]
	v_mfma_f32_16x16x32_bf16 v[84:87], v[156:159], v[172:175], v[84:87]
	v_mfma_f32_16x16x32_bf16 v[80:83], v[148:151], v[180:183], v[80:83]
	v_mfma_f32_16x16x32_bf16 v[76:79], v[156:159], v[180:183], v[76:79]
	v_mfma_f32_16x16x32_bf16 v[72:75], v[148:151], v[188:191], v[72:75]
	v_mfma_f32_16x16x32_bf16 v[68:71], v[156:159], v[188:191], v[68:71]
	v_mfma_f32_16x16x32_bf16 v[96:99], v[152:155], v[168:171], v[96:99]
	v_mfma_f32_16x16x32_bf16 v[92:95], v[160:163], v[168:171], v[92:95]
	v_mfma_f32_16x16x32_bf16 v[88:91], v[152:155], v[176:179], v[88:91]
	v_mfma_f32_16x16x32_bf16 v[84:87], v[160:163], v[176:179], v[84:87]
	v_mfma_f32_16x16x32_bf16 v[80:83], v[152:155], v[184:187], v[80:83]
	v_mfma_f32_16x16x32_bf16 v[76:79], v[160:163], v[184:187], v[76:79]
	v_mfma_f32_16x16x32_bf16 v[72:75], v[152:155], v[192:195], v[72:75]
	v_mfma_f32_16x16x32_bf16 v[68:71], v[160:163], v[192:195], v[68:71]
	s_setprio 0
	s_barrier
; #define PG8_STAGE(bufoff, gbase, voff) do { _Pragma("unroll") for (int _i = 0; _i < 2; ++_i) \
;         __builtin_amdgcn_global_load_lds((const unsigned*)((const char*)(gbase) + (voff)[_i]), (LAS unsigned*)(lds + (bufoff) + ldsw + _i * 8192), 16, 0, 0); } while (0)
; #define PG8_LDA(dst, b, h) do { _Pragma("unroll") for (int m = 0; m < 4; ++m) _Pragma("unroll") for (int k = 0; k < 2; ++k) dst[m][k] = *(const LAS bf16x8*)(lds + PG8_SA(b, h) + aoff + m * 2048 + k * 1024); } while (0)
; #define PG8_MMA(ai, bj, At, Bt) do { __builtin_amdgcn_s_setprio(1); _Pragma("unroll") for (int m = 0; m < 4; ++m) _Pragma("unroll") for (int n = 0; n < 2; ++n) _Pragma("unroll") for (int k = 0; k < 2; ++k) \
;         acc[ai][bj][m][n] = __builtin_amdgcn_mfma_f32_16x16x32_bf16(Bt[n][k], At[m][k], acc[ai][bj][m][n], 0, 0, 0); __builtin_amdgcn_s_setprio(0); } while (0)
; #define PG8_WAIT_V(n) asm volatile("s_waitcnt vmcnt(" #n ")" ::: "memory")
; #define PG8_WAIT_L(n) asm volatile("s_waitcnt lgkmcnt(" #n ")" ::: "memory")
; #define PG8_BAR __builtin_amdgcn_s_barrier()
; #define PG8_SCHED __builtin_amdgcn_sched_barrier(0)
; template <class Epi, class Sched, bool ALIGN_EPI>
; __device__ __forceinline__ void gemm_phase(LAS unsigned char* lds, const Gemm g, const Sched& S, const Epi& E) {
;     ...
;             PG8_LDA(At, 1, 1); PG8_STAGE(PG8_SB(1, 0), b3, voffB); PG8_STAGE(PG8_SB(1, 1), b3 + hstepB, voffB); PG8_STAGE(PG8_SA(1, 0), a3, voffA);
;             PG8_WAIT_V(8); PG8_WAIT_L(0); PG8_BAR; PG8_MMA(1, 0, At, B0); PG8_MMA(1, 1, At, B1); PG8_BAR; PG8_SCHED;
;         }
	s_add_i32 s52, s73, s33
	v_lshl_add_u64 v[6:7], v[212:213], 0, s[30:31]
	s_mov_b32 m0, s52
	ds_read_b128 v[164:167], v222 offset:49152
	ds_read_b128 v[168:171], v222 offset:50176
	ds_read_b128 v[172:175], v222 offset:51200
	ds_read_b128 v[176:179], v222 offset:52224
	ds_read_b128 v[180:183], v222 offset:53248
	ds_read_b128 v[184:187], v222 offset:54272
	ds_read_b128 v[188:191], v222 offset:55296
	ds_read_b128 v[192:195], v222 offset:56320
	global_load_lds_dwordx4 v[6:7], off
	v_lshl_add_u64 v[6:7], v[214:215], 0, s[30:31]
	s_add_i32 m0, s52, 0x2000
	s_add_i32 s52, s74, s33
	global_load_lds_dwordx4 v[6:7], off
	v_lshl_add_u64 v[6:7], v[216:217], 0, s[30:31]
	s_mov_b32 m0, s52
	s_nop 0
	global_load_lds_dwordx4 v[6:7], off
	v_lshl_add_u64 v[6:7], v[224:225], 0, s[30:31]
	s_add_i32 m0, s52, 0x2000
	s_nop 0
	global_load_lds_dwordx4 v[6:7], off
	v_lshl_add_u64 v[6:7], v[226:227], 0, s[30:31]
	s_mov_b32 m0, s60
	s_nop 0
	global_load_lds_dwordx4 v[6:7], off
	v_lshl_add_u64 v[6:7], v[228:229], 0, s[30:31]
	s_mov_b32 m0, s61
	s_nop 0
	global_load_lds_dwordx4 v[6:7], off
	s_waitcnt vmcnt(8)
	s_waitcnt lgkmcnt(0)
	s_barrier
	s_setprio 1
	v_mfma_f32_16x16x32_bf16 v[64:67], v[132:135], v[164:167], v[64:67]
	v_mfma_f32_16x16x32_bf16 v[60:63], v[140:143], v[164:167], v[60:63]
	v_mfma_f32_16x16x32_bf16 v[56:59], v[132:135], v[172:175], v[56:59]
	v_mfma_f32_16x16x32_bf16 v[52:55], v[140:143], v[172:175], v[52:55]
	v_mfma_f32_16x16x32_bf16 v[48:51], v[132:135], v[180:183], v[48:51]
	v_mfma_f32_16x16x32_bf16 v[44:47], v[140:143], v[180:183], v[44:47]
	v_mfma_f32_16x16x32_bf16 v[40:43], v[132:135], v[188:191], v[40:43]
	v_mfma_f32_16x16x32_bf16 v[36:39], v[140:143], v[188:191], v[36:39]
	v_mfma_f32_16x16x32_bf16 v[64:67], v[136:139], v[168:171], v[64:67]
	v_mfma_f32_16x16x32_bf16 v[60:63], v[144:147], v[168:171], v[60:63]
	v_mfma_f32_16x16x32_bf16 v[56:59], v[136:139], v[176:179], v[56:59]
	v_mfma_f32_16x16x32_bf16 v[52:55], v[144:147], v[176:179], v[52:55]
	v_mfma_f32_16x16x32_bf16 v[48:51], v[136:139], v[184:187], v[48:51]
	v_mfma_f32_16x16x32_bf16 v[44:47], v[144:147], v[184:187], v[44:47]
	v_mfma_f32_16x16x32_bf16 v[40:43], v[136:139], v[192:195], v[40:43]
	v_mfma_f32_16x16x32_bf16 v[36:39], v[144:147], v[192:195], v[36:39]
	s_setprio 0
	s_setprio 1
	v_mfma_f32_16x16x32_bf16 v[32:35], v[148:151], v[164:167], v[32:35]
	v_mfma_f32_16x16x32_bf16 v[28:31], v[156:159], v[164:167], v[28:31]
	v_mfma_f32_16x16x32_bf16 v[24:27], v[148:151], v[172:175], v[24:27]
	v_mfma_f32_16x16x32_bf16 v[20:23], v[156:159], v[172:175], v[20:23]
	v_mfma_f32_16x16x32_bf16 v[16:19], v[148:151], v[180:183], v[16:19]
	v_mfma_f32_16x16x32_bf16 v[12:15], v[156:159], v[180:183], v[12:15]
	v_mfma_f32_16x16x32_bf16 v[6:9], v[148:151], v[188:191], v[8:11]
	v_mfma_f32_16x16x32_bf16 v[2:5], v[156:159], v[188:191], v[2:5]
	v_mfma_f32_16x16x32_bf16 v[32:35], v[152:155], v[168:171], v[32:35]
	v_mfma_f32_16x16x32_bf16 v[28:31], v[160:163], v[168:171], v[28:31]
	v_mfma_f32_16x16x32_bf16 v[24:27], v[152:155], v[176:179], v[24:27]
	v_mfma_f32_16x16x32_bf16 v[20:23], v[160:163], v[176:179], v[20:23]
	v_mfma_f32_16x16x32_bf16 v[16:19], v[152:155], v[184:187], v[16:19]
	v_mfma_f32_16x16x32_bf16 v[12:15], v[160:163], v[184:187], v[12:15]
	v_mfma_f32_16x16x32_bf16 v[8:11], v[152:155], v[192:195], v[6:9]
	v_mfma_f32_16x16x32_bf16 v[4:7], v[160:163], v[192:195], v[2:5]
	s_setprio 0
	s_barrier
	s_add_u32 s70, s70, 0x100
	s_addc_u32 s71, s71, 0
	s_add_u32 s50, s50, 0x100
	s_addc_u32 s51, s51, 0
	s_cmp_ge_i32 s72, s62
	s_mov_b32 s52, s72
	s_cbranch_scc0 .LBB0_889

; #define PG8_STAGE(bufoff, gbase, voff) do { _Pragma("unroll") for (int _i = 0; _i < 2; ++_i) \
;         __builtin_amdgcn_global_load_lds((const unsigned*)((const char*)(gbase) + (voff)[_i]), (LAS unsigned*)(lds + (bufoff) + ldsw + _i * 8192), 16, 0, 0); } while (0)
; #define PG8_LDA(dst, b, h) do { _Pragma("unroll") for (int m = 0; m < 4; ++m) _Pragma("unroll") for (int k = 0; k < 2; ++k) dst[m][k] = *(const LAS bf16x8*)(lds + PG8_SA(b, h) + aoff + m * 2048 + k * 1024); } while (0)
; #define PG8_LDB(dst, b, h) do { _Pragma("unroll") for (int n = 0; n < 2; ++n) _Pragma("unroll") for (int k = 0; k < 2; ++k) dst[n][k] = *(const LAS bf16x8*)(lds + PG8_SB(b, h) + boff + n * 2048 + k * 1024); } while (0)
; #define PG8_MMA(ai, bj, At, Bt) do { __builtin_amdgcn_s_setprio(1); _Pragma("unroll") for (int m = 0; m < 4; ++m) _Pragma("unroll") for (int n = 0; n < 2; ++n) _Pragma("unroll") for (int k = 0; k < 2; ++k) \
;         acc[ai][bj][m][n] = __builtin_amdgcn_mfma_f32_16x16x32_bf16(Bt[n][k], At[m][k], acc[ai][bj][m][n], 0, 0, 0); __builtin_amdgcn_s_setprio(0); } while (0)
; #define PG8_WAIT_V(n) asm volatile("s_waitcnt vmcnt(" #n ")" ::: "memory")
; #define PG8_WAIT_L(n) asm volatile("s_waitcnt lgkmcnt(" #n ")" ::: "memory")
; #define PG8_BAR __builtin_amdgcn_s_barrier()
; #define PG8_SCHED __builtin_amdgcn_sched_barrier(0)
; template <class Epi, class Sched, bool ALIGN_EPI>
; __device__ __forceinline__ void gemm_phase(LAS unsigned char* lds, const Gemm g, const Sched& S, const Epi& E) {
;     ...
;         for (int t = 0; t < nt; t += 2) {
;             const bool last = (t == nt - 2);
;             const char* a1 = cA + (size_t)(t + 1) * kstep;
;             const char* a2 = last ? nA : cA + (size_t)(t + 2) * kstep; const char* b2 = last ? nB : cB + (size_t)(t + 2) * kstep;
;             const char* a3 = a2 + kstep; const char* b3 = b2 + kstep;
;             PG8_LDB(B0, 0, 0); PG8_LDB(B1, 0, 1); PG8_SCHED; PG8_LDA(At, 0, 0); PG8_STAGE(PG8_SA(1, 1), a1 + hstepA, voffA);
;             PG8_WAIT_V(8); PG8_WAIT_L(0); PG8_BAR; PG8_MMA(0, 0, At, B0); PG8_MMA(0, 1, At, B1); PG8_BAR; PG8_SCHED;
;             PG8_LDA(At, 0, 1); PG8_STAGE(PG8_SB(0, 0), b2, voffB); PG8_STAGE(PG8_SB(0, 1), b2 + hstepB, voffB); PG8_STAGE(PG8_SA(0, 0), a2, voffA);
;             PG8_WAIT_V(8); PG8_WAIT_L(0); PG8_BAR; PG8_MMA(1, 0, At, B0); PG8_MMA(1, 1, At, B1); PG8_BAR; PG8_SCHED;
.LBB0_1065:
	ds_read_b128 v[128:131], v199
	ds_read_b128 v[132:135], v199 offset:1024
	ds_read_b128 v[136:139], v199 offset:2048
	ds_read_b128 v[140:143], v199 offset:3072
	ds_read_b128 v[144:147], v200
	ds_read_b128 v[148:151], v200 offset:1024
	ds_read_b128 v[152:155], v200 offset:2048
	ds_read_b128 v[156:159], v200 offset:3072
	s_add_i32 s71, s54, 2
	s_add_u32 s72, s52, 0x80
	s_addc_u32 s55, s53, 0
	s_cmp_eq_u32 s63, s54
	s_cselect_b32 s54, s43, s72
	s_cselect_b32 s55, s41, s55
	s_cselect_b32 s73, s49, s70
	s_cselect_b32 s72, s68, s69
	v_lshl_add_u64 v[194:195], s[52:53], 0, v[186:187]
	s_add_i32 m0, s51, 0xc000
	ds_read_b128 v[160:163], v201
	ds_read_b128 v[164:167], v201 offset:1024
	ds_read_b128 v[168:171], v201 offset:2048
	ds_read_b128 v[172:175], v201 offset:3072
	ds_read_b128 v[204:207], v201 offset:4096
	ds_read_b128 v[208:211], v201 offset:5120
	ds_read_b128 v[212:215], v201 offset:6144
	ds_read_b128 v[220:223], v201 offset:7168
	global_load_lds_dwordx4 v[194:195], off
	v_lshl_add_u64 v[194:195], s[52:53], 0, v[188:189]
	s_add_i32 m0, s51, 0xe000
	s_nop 0
	global_load_lds_dwordx4 v[194:195], off
	s_waitcnt vmcnt(8)
	s_waitcnt lgkmcnt(0)
	s_barrier
	s_setprio 1
	v_mfma_f32_16x16x32_bf16 v[120:123], v[128:131], v[160:163], v[120:123]
	v_mfma_f32_16x16x32_bf16 v[124:127], v[136:139], v[160:163], v[124:127]
	v_mfma_f32_16x16x32_bf16 v[108:111], v[128:131], v[168:171], v[108:111]
	v_mfma_f32_16x16x32_bf16 v[104:107], v[136:139], v[168:171], v[104:107]
	v_mfma_f32_16x16x32_bf16 v[92:95], v[128:131], v[204:207], v[92:95]
	v_mfma_f32_16x16x32_bf16 v[88:91], v[136:139], v[204:207], v[88:91]
	v_mfma_f32_16x16x32_bf16 v[76:79], v[128:131], v[212:215], v[76:79]
	v_mfma_f32_16x16x32_bf16 v[72:75], v[136:139], v[212:215], v[72:75]
	v_mfma_f32_16x16x32_bf16 v[120:123], v[132:135], v[164:167], v[120:123]
	v_mfma_f32_16x16x32_bf16 v[124:127], v[140:143], v[164:167], v[124:127]
	v_mfma_f32_16x16x32_bf16 v[108:111], v[132:135], v[172:175], v[108:111]
	v_mfma_f32_16x16x32_bf16 v[104:107], v[140:143], v[172:175], v[104:107]
	v_mfma_f32_16x16x32_bf16 v[92:95], v[132:135], v[208:211], v[92:95]
	v_mfma_f32_16x16x32_bf16 v[88:91], v[140:143], v[208:211], v[88:91]
	v_mfma_f32_16x16x32_bf16 v[76:79], v[132:135], v[220:223], v[76:79]
	v_mfma_f32_16x16x32_bf16 v[72:75], v[140:143], v[220:223], v[72:75]
	s_setprio 0
	s_setprio 1
	v_mfma_f32_16x16x32_bf16 v[116:119], v[144:147], v[160:163], v[116:119]
	v_mfma_f32_16x16x32_bf16 v[112:115], v[152:155], v[160:163], v[112:115]
	v_mfma_f32_16x16x32_bf16 v[100:103], v[144:147], v[168:171], v[100:103]
	v_mfma_f32_16x16x32_bf16 v[96:99], v[152:155], v[168:171], v[96:99]
	v_mfma_f32_16x16x32_bf16 v[84:87], v[144:147], v[204:207], v[84:87]
	v_mfma_f32_16x16x32_bf16 v[80:83], v[152:155], v[204:207], v[80:83]
	v_mfma_f32_16x16x32_bf16 v[68:71], v[144:147], v[212:215], v[68:71]
	v_mfma_f32_16x16x32_bf16 v[64:67], v[152:155], v[212:215], v[64:67]
	v_mfma_f32_16x16x32_bf16 v[116:119], v[148:151], v[164:167], v[116:119]
	v_mfma_f32_16x16x32_bf16 v[112:115], v[156:159], v[164:167], v[112:115]
	v_mfma_f32_16x16x32_bf16 v[100:103], v[148:151], v[172:175], v[100:103]
	v_mfma_f32_16x16x32_bf16 v[96:99], v[156:159], v[172:175], v[96:99]
	v_mfma_f32_16x16x32_bf16 v[84:87], v[148:151], v[208:211], v[84:87]
	v_mfma_f32_16x16x32_bf16 v[80:83], v[156:159], v[208:211], v[80:83]
	v_mfma_f32_16x16x32_bf16 v[68:71], v[148:151], v[220:223], v[68:71]
	v_mfma_f32_16x16x32_bf16 v[64:67], v[156:159], v[220:223], v[64:67]
	s_setprio 0
	s_barrier
	s_add_i32 s74, s66, s33
	v_lshl_add_u64 v[194:195], s[72:73], 0, v[178:179]
	s_mov_b32 m0, s74
	ds_read_b128 v[160:163], v201 offset:16384
	ds_read_b128 v[164:167], v201 offset:17408
	ds_read_b128 v[168:171], v201 offset:18432
	ds_read_b128 v[172:175], v201 offset:19456
	ds_read_b128 v[204:207], v201 offset:20480
	ds_read_b128 v[208:211], v201 offset:21504
	ds_read_b128 v[212:215], v201 offset:22528
	ds_read_b128 v[220:223], v201 offset:23552
	global_load_lds_dwordx4 v[194:195], off
	s_add_i32 m0, s74, 0x2000
	v_lshl_add_u64 v[216:217], s[72:73], 0, v[182:183]
	s_add_u32 s72, s72, s26
	s_addc_u32 s73, s73, s27
	s_add_i32 s74, s67, s33
	global_load_lds_dwordx4 v[216:217], off
	v_lshl_add_u64 v[224:225], s[72:73], 0, v[178:179]
	s_mov_b32 m0, s74
	v_lshl_add_u64 v[226:227], s[72:73], 0, v[182:183]
	global_load_lds_dwordx4 v[224:225], off
	s_add_i32 m0, s74, 0x2000
	v_lshl_add_u64 v[228:229], s[54:55], 0, v[176:177]
	global_load_lds_dwordx4 v[226:227], off
	s_mov_b32 m0, s51
	v_lshl_add_u64 v[230:231], s[54:55], 0, v[180:181]
	global_load_lds_dwordx4 v[228:229], off
	s_mov_b32 m0, s56
	s_nop 0
	global_load_lds_dwordx4 v[230:231], off
	s_waitcnt vmcnt(8)
	s_waitcnt lgkmcnt(0)
	s_barrier
; #define PG8_STAGE(bufoff, gbase, voff) do { _Pragma("unroll") for (int _i = 0; _i < 2; ++_i) \
;         __builtin_amdgcn_global_load_lds((const unsigned*)((const char*)(gbase) + (voff)[_i]), (LAS unsigned*)(lds + (bufoff) + ldsw + _i * 8192), 16, 0, 0); } while (0)
; #define PG8_LDA(dst, b, h) do { _Pragma("unroll") for (int m = 0; m < 4; ++m) _Pragma("unroll") for (int k = 0; k < 2; ++k) dst[m][k] = *(const LAS bf16x8*)(lds + PG8_SA(b, h) + aoff + m * 2048 + k * 1024); } while (0)
; #define PG8_LDB(dst, b, h) do { _Pragma("unroll") for (int n = 0; n < 2; ++n) _Pragma("unroll") for (int k = 0; k < 2; ++k) dst[n][k] = *(const LAS bf16x8*)(lds + PG8_SB(b, h) + boff + n * 2048 + k * 1024); } while (0)
; #define PG8_MMA(ai, bj, At, Bt) do { __builtin_amdgcn_s_setprio(1); _Pragma("unroll") for (int m = 0; m < 4; ++m) _Pragma("unroll") for (int n = 0; n < 2; ++n) _Pragma("unroll") for (int k = 0; k < 2; ++k) \
;         acc[ai][bj][m][n] = __builtin_amdgcn_mfma_f32_16x16x32_bf16(Bt[n][k], At[m][k], acc[ai][bj][m][n], 0, 0, 0); __builtin_amdgcn_s_setprio(0); } while (0)
; #define PG8_WAIT_V(n) asm volatile("s_waitcnt vmcnt(" #n ")" ::: "memory")
; #define PG8_WAIT_L(n) asm volatile("s_waitcnt lgkmcnt(" #n ")" ::: "memory")
; #define PG8_BAR __builtin_amdgcn_s_barrier()
; #define PG8_SCHED __builtin_amdgcn_sched_barrier(0)
; template <class Epi, class Sched, bool ALIGN_EPI>
; __device__ __forceinline__ void gemm_phase(LAS unsigned char* lds, const Gemm g, const Sched& S, const Epi& E) {
;     ...
;             PG8_WAIT_V(8); PG8_WAIT_L(0); PG8_BAR; PG8_MMA(1, 0, At, B0); PG8_MMA(1, 1, At, B1); PG8_BAR; PG8_SCHED;
;             PG8_LDB(B0, 1, 0); PG8_LDB(B1, 1, 1); PG8_SCHED; PG8_LDA(At, 1, 0); PG8_STAGE(PG8_SA(0, 1), a2 + hstepA, voffA);
;             PG8_WAIT_V(8); PG8_WAIT_L(0); PG8_BAR; PG8_MMA(0, 0, At, B0); PG8_MMA(0, 1, At, B1); PG8_BAR; PG8_SCHED;
	s_setprio 1
	v_mfma_f32_16x16x32_bf16 v[60:63], v[128:131], v[160:163], v[60:63]
	v_mfma_f32_16x16x32_bf16 v[56:59], v[136:139], v[160:163], v[56:59]
	v_mfma_f32_16x16x32_bf16 v[44:47], v[128:131], v[168:171], v[44:47]
	v_mfma_f32_16x16x32_bf16 v[40:43], v[136:139], v[168:171], v[40:43]
	v_mfma_f32_16x16x32_bf16 v[28:31], v[128:131], v[204:207], v[28:31]
	v_mfma_f32_16x16x32_bf16 v[24:27], v[136:139], v[204:207], v[24:27]
	v_mfma_f32_16x16x32_bf16 v[12:15], v[128:131], v[212:215], v[12:15]
	v_mfma_f32_16x16x32_bf16 v[8:11], v[136:139], v[212:215], v[8:11]
	v_mfma_f32_16x16x32_bf16 v[60:63], v[132:135], v[164:167], v[60:63]
	v_mfma_f32_16x16x32_bf16 v[56:59], v[140:143], v[164:167], v[56:59]
	v_mfma_f32_16x16x32_bf16 v[44:47], v[132:135], v[172:175], v[44:47]
	v_mfma_f32_16x16x32_bf16 v[40:43], v[140:143], v[172:175], v[40:43]
	v_mfma_f32_16x16x32_bf16 v[28:31], v[132:135], v[208:211], v[28:31]
	v_mfma_f32_16x16x32_bf16 v[24:27], v[140:143], v[208:211], v[24:27]
	v_mfma_f32_16x16x32_bf16 v[12:15], v[132:135], v[220:223], v[12:15]
	v_mfma_f32_16x16x32_bf16 v[8:11], v[140:143], v[220:223], v[8:11]
	s_setprio 0
	s_setprio 1
	v_mfma_f32_16x16x32_bf16 v[52:55], v[144:147], v[160:163], v[52:55]
	v_mfma_f32_16x16x32_bf16 v[48:51], v[152:155], v[160:163], v[48:51]
	v_mfma_f32_16x16x32_bf16 v[36:39], v[144:147], v[168:171], v[36:39]
	v_mfma_f32_16x16x32_bf16 v[32:35], v[152:155], v[168:171], v[32:35]
	v_mfma_f32_16x16x32_bf16 v[20:23], v[144:147], v[204:207], v[20:23]
	v_mfma_f32_16x16x32_bf16 v[16:19], v[152:155], v[204:207], v[16:19]
	v_mfma_f32_16x16x32_bf16 v[4:7], v[144:147], v[212:215], v[4:7]
	v_mfma_f32_16x16x32_bf16 v[0:3], v[152:155], v[212:215], v[0:3]
	v_mfma_f32_16x16x32_bf16 v[52:55], v[148:151], v[164:167], v[52:55]
	v_mfma_f32_16x16x32_bf16 v[48:51], v[156:159], v[164:167], v[48:51]
	v_mfma_f32_16x16x32_bf16 v[36:39], v[148:151], v[172:175], v[36:39]
	v_mfma_f32_16x16x32_bf16 v[32:35], v[156:159], v[172:175], v[32:35]
	v_mfma_f32_16x16x32_bf16 v[20:23], v[148:151], v[208:211], v[20:23]
	v_mfma_f32_16x16x32_bf16 v[16:19], v[156:159], v[208:211], v[16:19]
	v_mfma_f32_16x16x32_bf16 v[4:7], v[148:151], v[220:223], v[4:7]
	v_mfma_f32_16x16x32_bf16 v[0:3], v[156:159], v[220:223], v[0:3]
	s_setprio 0
	s_barrier
	s_add_i32 s72, 0, 0x18000
	s_add_i32 s73, 0, 0x1c000
	v_add_u32_e32 v140, s72, v197
	v_add_u32_e32 v156, s73, v197
	ds_read_b128 v[128:131], v140
	ds_read_b128 v[132:135], v140 offset:1024
	ds_read_b128 v[136:139], v140 offset:2048
	ds_read_b128 v[140:143], v140 offset:3072
	ds_read_b128 v[144:147], v156
	ds_read_b128 v[148:151], v156 offset:1024
	ds_read_b128 v[152:155], v156 offset:2048
	ds_read_b128 v[156:159], v156 offset:3072
	s_add_u32 s54, s54, s24
	s_addc_u32 s55, s55, s25
	s_mov_b32 m0, s57
	v_lshl_add_u64 v[232:233], s[54:55], 0, v[176:177]
	ds_read_b128 v[160:163], v201 offset:32768
	ds_read_b128 v[164:167], v201 offset:33792
	ds_read_b128 v[168:171], v201 offset:34816
	ds_read_b128 v[172:175], v201 offset:35840
	ds_read_b128 v[204:207], v201 offset:36864
	ds_read_b128 v[208:211], v201 offset:37888
	ds_read_b128 v[212:215], v201 offset:38912
	ds_read_b128 v[220:223], v201 offset:39936
	global_load_lds_dwordx4 v[232:233], off
	v_lshl_add_u64 v[232:233], s[54:55], 0, v[180:181]
	s_mov_b32 m0, s58
	s_nop 0
	global_load_lds_dwordx4 v[232:233], off
	s_waitcnt vmcnt(8)
	s_waitcnt lgkmcnt(0)
	s_barrier
	s_setprio 1
	v_mfma_f32_16x16x32_bf16 v[120:123], v[128:131], v[160:163], v[120:123]
	v_mfma_f32_16x16x32_bf16 v[124:127], v[136:139], v[160:163], v[124:127]
	v_mfma_f32_16x16x32_bf16 v[108:111], v[128:131], v[168:171], v[108:111]
	v_mfma_f32_16x16x32_bf16 v[104:107], v[136:139], v[168:171], v[104:107]
	v_mfma_f32_16x16x32_bf16 v[92:95], v[128:131], v[204:207], v[92:95]
	v_mfma_f32_16x16x32_bf16 v[88:91], v[136:139], v[204:207], v[88:91]
	v_mfma_f32_16x16x32_bf16 v[76:79], v[128:131], v[212:215], v[76:79]
	v_mfma_f32_16x16x32_bf16 v[72:75], v[136:139], v[212:215], v[72:75]
	v_mfma_f32_16x16x32_bf16 v[120:123], v[132:135], v[164:167], v[120:123]
	v_mfma_f32_16x16x32_bf16 v[124:127], v[140:143], v[164:167], v[124:127]
	v_mfma_f32_16x16x32_bf16 v[108:111], v[132:135], v[172:175], v[108:111]
	v_mfma_f32_16x16x32_bf16 v[104:107], v[140:143], v[172:175], v[104:107]
	v_mfma_f32_16x16x32_bf16 v[92:95], v[132:135], v[208:211], v[92:95]
	v_mfma_f32_16x16x32_bf16 v[88:91], v[140:143], v[208:211], v[88:91]
	v_mfma_f32_16x16x32_bf16 v[76:79], v[132:135], v[220:223], v[76:79]
	v_mfma_f32_16x16x32_bf16 v[72:75], v[140:143], v[220:223], v[72:75]
	s_setprio 0
	s_setprio 1
	v_mfma_f32_16x16x32_bf16 v[116:119], v[144:147], v[160:163], v[116:119]
	v_mfma_f32_16x16x32_bf16 v[112:115], v[152:155], v[160:163], v[112:115]
	v_mfma_f32_16x16x32_bf16 v[100:103], v[144:147], v[168:171], v[100:103]
	v_mfma_f32_16x16x32_bf16 v[96:99], v[152:155], v[168:171], v[96:99]
	v_mfma_f32_16x16x32_bf16 v[84:87], v[144:147], v[204:207], v[84:87]
	v_mfma_f32_16x16x32_bf16 v[80:83], v[152:155], v[204:207], v[80:83]
	v_mfma_f32_16x16x32_bf16 v[68:71], v[144:147], v[212:215], v[68:71]
	v_mfma_f32_16x16x32_bf16 v[64:67], v[152:155], v[212:215], v[64:67]
	v_mfma_f32_16x16x32_bf16 v[116:119], v[148:151], v[164:167], v[116:119]
	v_mfma_f32_16x16x32_bf16 v[112:115], v[156:159], v[164:167], v[112:115]
	v_mfma_f32_16x16x32_bf16 v[100:103], v[148:151], v[172:175], v[100:103]
	v_mfma_f32_16x16x32_bf16 v[96:99], v[156:159], v[172:175], v[96:99]
	v_mfma_f32_16x16x32_bf16 v[84:87], v[148:151], v[208:211], v[84:87]
	v_mfma_f32_16x16x32_bf16 v[80:83], v[156:159], v[208:211], v[80:83]
	v_mfma_f32_16x16x32_bf16 v[68:71], v[148:151], v[220:223], v[68:71]
	v_mfma_f32_16x16x32_bf16 v[64:67], v[156:159], v[220:223], v[64:67]
	s_setprio 0
	s_barrier
; #define PG8_STAGE(bufoff, gbase, voff) do { _Pragma("unroll") for (int _i = 0; _i < 2; ++_i) \
;         __builtin_amdgcn_global_load_lds((const unsigned*)((const char*)(gbase) + (voff)[_i]), (LAS unsigned*)(lds + (bufoff) + ldsw + _i * 8192), 16, 0, 0); } while (0)
; #define PG8_LDA(dst, b, h) do { _Pragma("unroll") for (int m = 0; m < 4; ++m) _Pragma("unroll") for (int k = 0; k < 2; ++k) dst[m][k] = *(const LAS bf16x8*)(lds + PG8_SA(b, h) + aoff + m * 2048 + k * 1024); } while (0)
; #define PG8_MMA(ai, bj, At, Bt) do { __builtin_amdgcn_s_setprio(1); _Pragma("unroll") for (int m = 0; m < 4; ++m) _Pragma("unroll") for (int n = 0; n < 2; ++n) _Pragma("unroll") for (int k = 0; k < 2; ++k) \
;         acc[ai][bj][m][n] = __builtin_amdgcn_mfma_f32_16x16x32_bf16(Bt[n][k], At[m][k], acc[ai][bj][m][n], 0, 0, 0); __builtin_amdgcn_s_setprio(0); } while (0)
; #define PG8_WAIT_V(n) asm volatile("s_waitcnt vmcnt(" #n ")" ::: "memory")
; #define PG8_WAIT_L(n) asm volatile("s_waitcnt lgkmcnt(" #n ")" ::: "memory")
; #define PG8_BAR __builtin_amdgcn_s_barrier()
; #define PG8_SCHED __builtin_amdgcn_sched_barrier(0)
; template <class Epi, class Sched, bool ALIGN_EPI>
; __device__ __forceinline__ void gemm_phase(LAS unsigned char* lds, const Gemm g, const Sched& S, const Epi& E) {
;     ...
;             PG8_LDA(At, 1, 1); PG8_STAGE(PG8_SB(1, 0), b3, voffB); PG8_STAGE(PG8_SB(1, 1), b3 + hstepB, voffB); PG8_STAGE(PG8_SA(1, 0), a3, voffA);
;             PG8_WAIT_V(8); PG8_WAIT_L(0); PG8_BAR; PG8_MMA(1, 0, At, B0); PG8_MMA(1, 1, At, B1); PG8_BAR; PG8_SCHED;
;         }
	s_add_i32 s54, s72, s33
	v_lshl_add_u64 v[194:195], v[194:195], 0, s[30:31]
	s_mov_b32 m0, s54
	ds_read_b128 v[160:163], v201 offset:49152
	ds_read_b128 v[164:167], v201 offset:50176
	ds_read_b128 v[168:171], v201 offset:51200
	ds_read_b128 v[172:175], v201 offset:52224
	ds_read_b128 v[204:207], v201 offset:53248
	ds_read_b128 v[208:211], v201 offset:54272
	ds_read_b128 v[212:215], v201 offset:55296
	ds_read_b128 v[220:223], v201 offset:56320
	global_load_lds_dwordx4 v[194:195], off
	v_lshl_add_u64 v[194:195], v[216:217], 0, s[30:31]
	s_add_i32 m0, s54, 0x2000
	s_add_i32 s54, s73, s33
	global_load_lds_dwordx4 v[194:195], off
	v_lshl_add_u64 v[194:195], v[224:225], 0, s[30:31]
	s_mov_b32 m0, s54
	s_nop 0
	global_load_lds_dwordx4 v[194:195], off
	v_lshl_add_u64 v[194:195], v[226:227], 0, s[30:31]
	s_add_i32 m0, s54, 0x2000
	s_nop 0
	global_load_lds_dwordx4 v[194:195], off
	v_lshl_add_u64 v[194:195], v[228:229], 0, s[30:31]
	s_mov_b32 m0, s60
	s_nop 0
	global_load_lds_dwordx4 v[194:195], off
	v_lshl_add_u64 v[194:195], v[230:231], 0, s[30:31]
	s_mov_b32 m0, s61
	s_nop 0
	global_load_lds_dwordx4 v[194:195], off
	s_waitcnt vmcnt(8)
	s_waitcnt lgkmcnt(0)
	s_barrier
	s_setprio 1
	v_mfma_f32_16x16x32_bf16 v[60:63], v[128:131], v[160:163], v[60:63]
	v_mfma_f32_16x16x32_bf16 v[56:59], v[136:139], v[160:163], v[56:59]
	v_mfma_f32_16x16x32_bf16 v[44:47], v[128:131], v[168:171], v[44:47]
	v_mfma_f32_16x16x32_bf16 v[40:43], v[136:139], v[168:171], v[40:43]
	v_mfma_f32_16x16x32_bf16 v[28:31], v[128:131], v[204:207], v[28:31]
	v_mfma_f32_16x16x32_bf16 v[24:27], v[136:139], v[204:207], v[24:27]
	v_mfma_f32_16x16x32_bf16 v[12:15], v[128:131], v[212:215], v[12:15]
	v_mfma_f32_16x16x32_bf16 v[8:11], v[136:139], v[212:215], v[8:11]
	v_mfma_f32_16x16x32_bf16 v[60:63], v[132:135], v[164:167], v[60:63]
	v_mfma_f32_16x16x32_bf16 v[56:59], v[140:143], v[164:167], v[56:59]
	v_mfma_f32_16x16x32_bf16 v[44:47], v[132:135], v[172:175], v[44:47]
	v_mfma_f32_16x16x32_bf16 v[40:43], v[140:143], v[172:175], v[40:43]
	v_mfma_f32_16x16x32_bf16 v[28:31], v[132:135], v[208:211], v[28:31]
	v_mfma_f32_16x16x32_bf16 v[24:27], v[140:143], v[208:211], v[24:27]
	v_mfma_f32_16x16x32_bf16 v[12:15], v[132:135], v[220:223], v[12:15]
	v_mfma_f32_16x16x32_bf16 v[8:11], v[140:143], v[220:223], v[8:11]
	s_setprio 0
	s_setprio 1
	v_mfma_f32_16x16x32_bf16 v[52:55], v[144:147], v[160:163], v[52:55]
	v_mfma_f32_16x16x32_bf16 v[48:51], v[152:155], v[160:163], v[48:51]
	v_mfma_f32_16x16x32_bf16 v[36:39], v[144:147], v[168:171], v[36:39]
	v_mfma_f32_16x16x32_bf16 v[32:35], v[152:155], v[168:171], v[32:35]
	v_mfma_f32_16x16x32_bf16 v[20:23], v[144:147], v[204:207], v[20:23]
	v_mfma_f32_16x16x32_bf16 v[16:19], v[152:155], v[204:207], v[16:19]
	v_mfma_f32_16x16x32_bf16 v[4:7], v[144:147], v[212:215], v[4:7]
	v_mfma_f32_16x16x32_bf16 v[0:3], v[152:155], v[212:215], v[0:3]
	v_mfma_f32_16x16x32_bf16 v[52:55], v[148:151], v[164:167], v[52:55]
	v_mfma_f32_16x16x32_bf16 v[48:51], v[156:159], v[164:167], v[48:51]
	v_mfma_f32_16x16x32_bf16 v[36:39], v[148:151], v[172:175], v[36:39]
	v_mfma_f32_16x16x32_bf16 v[32:35], v[156:159], v[172:175], v[32:35]
	v_mfma_f32_16x16x32_bf16 v[20:23], v[148:151], v[208:211], v[20:23]
	v_mfma_f32_16x16x32_bf16 v[16:19], v[156:159], v[208:211], v[16:19]
	v_mfma_f32_16x16x32_bf16 v[4:7], v[148:151], v[220:223], v[4:7]
	v_mfma_f32_16x16x32_bf16 v[0:3], v[156:159], v[220:223], v[0:3]
	s_setprio 0
	s_barrier
	s_add_u32 s69, s69, 0x100
	s_addc_u32 s70, s70, 0
	s_add_u32 s52, s52, 0x100
	s_addc_u32 s53, s53, 0
	s_cmp_ge_i32 s71, s62
	s_mov_b32 s54, s71
	s_cbranch_scc0 .LBB0_1065

; #define PG8_STAGE(bufoff, gbase, voff) do { _Pragma("unroll") for (int _i = 0; _i < 2; ++_i) \
;         __builtin_amdgcn_global_load_lds((const unsigned*)((const char*)(gbase) + (voff)[_i]), (LAS unsigned*)(lds + (bufoff) + ldsw + _i * 8192), 16, 0, 0); } while (0)
; #define PG8_LDA(dst, b, h) do { _Pragma("unroll") for (int m = 0; m < 4; ++m) _Pragma("unroll") for (int k = 0; k < 2; ++k) dst[m][k] = *(const LAS bf16x8*)(lds + PG8_SA(b, h) + aoff + m * 2048 + k * 1024); } while (0)
; #define PG8_LDB(dst, b, h) do { _Pragma("unroll") for (int n = 0; n < 2; ++n) _Pragma("unroll") for (int k = 0; k < 2; ++k) dst[n][k] = *(const LAS bf16x8*)(lds + PG8_SB(b, h) + boff + n * 2048 + k * 1024); } while (0)
; #define PG8_MMA(ai, bj, At, Bt) do { __builtin_amdgcn_s_setprio(1); _Pragma("unroll") for (int m = 0; m < 4; ++m) _Pragma("unroll") for (int n = 0; n < 2; ++n) _Pragma("unroll") for (int k = 0; k < 2; ++k) \
;         acc[ai][bj][m][n] = __builtin_amdgcn_mfma_f32_16x16x32_bf16(Bt[n][k], At[m][k], acc[ai][bj][m][n], 0, 0, 0); __builtin_amdgcn_s_setprio(0); } while (0)
; #define PG8_WAIT_V(n) asm volatile("s_waitcnt vmcnt(" #n ")" ::: "memory")
; #define PG8_WAIT_L(n) asm volatile("s_waitcnt lgkmcnt(" #n ")" ::: "memory")
; #define PG8_BAR __builtin_amdgcn_s_barrier()
; #define PG8_SCHED __builtin_amdgcn_sched_barrier(0)
; template <class Epi, class Sched, bool ALIGN_EPI>
; __device__ __forceinline__ void gemm_phase(LAS unsigned char* lds, const Gemm g, const Sched& S, const Epi& E) {
;     ...
;         for (int t = 0; t < nt; t += 2) {
;             const bool last = (t == nt - 2);
;             const char* a1 = cA + (size_t)(t + 1) * kstep;
;             const char* a2 = last ? nA : cA + (size_t)(t + 2) * kstep; const char* b2 = last ? nB : cB + (size_t)(t + 2) * kstep;
;             const char* a3 = a2 + kstep; const char* b3 = b2 + kstep;
;             PG8_LDB(B0, 0, 0); PG8_LDB(B1, 0, 1); PG8_SCHED; PG8_LDA(At, 0, 0); PG8_STAGE(PG8_SA(1, 1), a1 + hstepA, voffA);
;             PG8_WAIT_V(8); PG8_WAIT_L(0); PG8_BAR; PG8_MMA(0, 0, At, B0); PG8_MMA(0, 1, At, B1); PG8_BAR; PG8_SCHED;
;             PG8_LDA(At, 0, 1); PG8_STAGE(PG8_SB(0, 0), b2, voffB); PG8_STAGE(PG8_SB(0, 1), b2 + hstepB, voffB); PG8_STAGE(PG8_SA(0, 0), a2, voffA);
;             PG8_WAIT_V(8); PG8_WAIT_L(0); PG8_BAR; PG8_MMA(1, 0, At, B0); PG8_MMA(1, 1, At, B1); PG8_BAR; PG8_SCHED;
.LBB0_1149:
	ds_read_b128 v[154:157], v149
	ds_read_b128 v[158:161], v149 offset:1024
	ds_read_b128 v[162:165], v149 offset:2048
	ds_read_b128 v[166:169], v149 offset:3072
	ds_read_b128 v[170:173], v150
	ds_read_b128 v[174:177], v150 offset:1024
	ds_read_b128 v[178:181], v150 offset:2048
	ds_read_b128 v[182:185], v150 offset:3072
	s_add_i32 s70, s48, 2
	s_add_u32 s71, s46, 0x80
	s_addc_u32 s49, s47, 0
	s_cmp_eq_u32 s59, s48
	s_cselect_b32 s48, s39, s71
	s_cselect_b32 s49, s37, s49
	s_cselect_b32 s73, s66, s69
	s_cselect_b32 s72, s67, s68
	v_lshl_add_u64 v[220:221], s[46:47], 0, v[138:139]
	s_add_i32 m0, s52, 0xc000
	ds_read_b128 v[186:189], v151
	ds_read_b128 v[190:193], v151 offset:1024
	ds_read_b128 v[194:197], v151 offset:2048
	ds_read_b128 v[198:201], v151 offset:3072
	ds_read_b128 v[202:205], v151 offset:4096
	ds_read_b128 v[206:209], v151 offset:5120
	ds_read_b128 v[210:213], v151 offset:6144
	ds_read_b128 v[214:217], v151 offset:7168
	global_load_lds_dwordx4 v[220:221], off
	v_lshl_add_u64 v[220:221], s[46:47], 0, v[140:141]
	s_add_i32 m0, s52, 0xe000
	s_nop 0
	global_load_lds_dwordx4 v[220:221], off
	s_waitcnt vmcnt(8)
	s_waitcnt lgkmcnt(0)
	s_barrier
	s_setprio 1
	v_mfma_f32_16x16x32_bf16 v[116:119], v[154:157], v[186:189], v[116:119]
	v_mfma_f32_16x16x32_bf16 v[112:115], v[162:165], v[186:189], v[112:115]
	v_mfma_f32_16x16x32_bf16 v[104:107], v[154:157], v[194:197], v[104:107]
	v_mfma_f32_16x16x32_bf16 v[96:99], v[162:165], v[194:197], v[96:99]
	v_mfma_f32_16x16x32_bf16 v[88:91], v[154:157], v[202:205], v[88:91]
	v_mfma_f32_16x16x32_bf16 v[80:83], v[162:165], v[202:205], v[80:83]
	v_mfma_f32_16x16x32_bf16 v[72:75], v[154:157], v[210:213], v[72:75]
	v_mfma_f32_16x16x32_bf16 v[64:67], v[162:165], v[210:213], v[64:67]
	v_mfma_f32_16x16x32_bf16 v[116:119], v[158:161], v[190:193], v[116:119]
	v_mfma_f32_16x16x32_bf16 v[112:115], v[166:169], v[190:193], v[112:115]
	v_mfma_f32_16x16x32_bf16 v[104:107], v[158:161], v[198:201], v[104:107]
	v_mfma_f32_16x16x32_bf16 v[96:99], v[166:169], v[198:201], v[96:99]
	v_mfma_f32_16x16x32_bf16 v[88:91], v[158:161], v[206:209], v[88:91]
	v_mfma_f32_16x16x32_bf16 v[80:83], v[166:169], v[206:209], v[80:83]
	v_mfma_f32_16x16x32_bf16 v[72:75], v[158:161], v[214:217], v[72:75]
	v_mfma_f32_16x16x32_bf16 v[64:67], v[166:169], v[214:217], v[64:67]
	s_setprio 0
	s_setprio 1
	v_mfma_f32_16x16x32_bf16 v[124:127], v[170:173], v[186:189], v[124:127]
	v_mfma_f32_16x16x32_bf16 v[120:123], v[178:181], v[186:189], v[120:123]
	v_mfma_f32_16x16x32_bf16 v[108:111], v[170:173], v[194:197], v[108:111]
	v_mfma_f32_16x16x32_bf16 v[100:103], v[178:181], v[194:197], v[100:103]
	v_mfma_f32_16x16x32_bf16 v[92:95], v[170:173], v[202:205], v[92:95]
	v_mfma_f32_16x16x32_bf16 v[84:87], v[178:181], v[202:205], v[84:87]
	v_mfma_f32_16x16x32_bf16 v[76:79], v[170:173], v[210:213], v[76:79]
	v_mfma_f32_16x16x32_bf16 v[68:71], v[178:181], v[210:213], v[68:71]
	v_mfma_f32_16x16x32_bf16 v[124:127], v[174:177], v[190:193], v[124:127]
	v_mfma_f32_16x16x32_bf16 v[120:123], v[182:185], v[190:193], v[120:123]
	v_mfma_f32_16x16x32_bf16 v[108:111], v[174:177], v[198:201], v[108:111]
	v_mfma_f32_16x16x32_bf16 v[100:103], v[182:185], v[198:201], v[100:103]
	v_mfma_f32_16x16x32_bf16 v[92:95], v[174:177], v[206:209], v[92:95]
	v_mfma_f32_16x16x32_bf16 v[84:87], v[182:185], v[206:209], v[84:87]
	v_mfma_f32_16x16x32_bf16 v[76:79], v[174:177], v[214:217], v[76:79]
	v_mfma_f32_16x16x32_bf16 v[68:71], v[182:185], v[214:217], v[68:71]
	s_setprio 0
	s_barrier
	s_add_i32 s71, s61, s33
	v_lshl_add_u64 v[220:221], s[72:73], 0, v[132:133]
	s_mov_b32 m0, s71
	ds_read_b128 v[186:189], v151 offset:16384
	ds_read_b128 v[190:193], v151 offset:17408
	ds_read_b128 v[194:197], v151 offset:18432
	ds_read_b128 v[198:201], v151 offset:19456
	ds_read_b128 v[202:205], v151 offset:20480
	ds_read_b128 v[206:209], v151 offset:21504
	ds_read_b128 v[210:213], v151 offset:22528
	ds_read_b128 v[214:217], v151 offset:23552
	global_load_lds_dwordx4 v[220:221], off
	s_add_i32 m0, s71, 0x2000
	v_lshl_add_u64 v[222:223], s[72:73], 0, v[128:129]
	s_add_u32 s72, s72, s26
	s_addc_u32 s73, s73, s27
	s_add_i32 s71, s62, s33
	global_load_lds_dwordx4 v[222:223], off
	v_lshl_add_u64 v[224:225], s[72:73], 0, v[132:133]
	s_mov_b32 m0, s71
	v_lshl_add_u64 v[226:227], s[72:73], 0, v[128:129]
	global_load_lds_dwordx4 v[224:225], off
	s_add_i32 m0, s71, 0x2000
	v_lshl_add_u64 v[228:229], s[48:49], 0, v[134:135]
	global_load_lds_dwordx4 v[226:227], off
	s_mov_b32 m0, s52
	v_lshl_add_u64 v[230:231], s[48:49], 0, v[130:131]
	global_load_lds_dwordx4 v[228:229], off
	s_mov_b32 m0, s45
	s_nop 0
	global_load_lds_dwordx4 v[230:231], off
	s_waitcnt vmcnt(8)
	s_waitcnt lgkmcnt(0)
	s_barrier
; #define PG8_STAGE(bufoff, gbase, voff) do { _Pragma("unroll") for (int _i = 0; _i < 2; ++_i) \
;         __builtin_amdgcn_global_load_lds((const unsigned*)((const char*)(gbase) + (voff)[_i]), (LAS unsigned*)(lds + (bufoff) + ldsw + _i * 8192), 16, 0, 0); } while (0)
; #define PG8_LDA(dst, b, h) do { _Pragma("unroll") for (int m = 0; m < 4; ++m) _Pragma("unroll") for (int k = 0; k < 2; ++k) dst[m][k] = *(const LAS bf16x8*)(lds + PG8_SA(b, h) + aoff + m * 2048 + k * 1024); } while (0)
; #define PG8_LDB(dst, b, h) do { _Pragma("unroll") for (int n = 0; n < 2; ++n) _Pragma("unroll") for (int k = 0; k < 2; ++k) dst[n][k] = *(const LAS bf16x8*)(lds + PG8_SB(b, h) + boff + n * 2048 + k * 1024); } while (0)
; #define PG8_MMA(ai, bj, At, Bt) do { __builtin_amdgcn_s_setprio(1); _Pragma("unroll") for (int m = 0; m < 4; ++m) _Pragma("unroll") for (int n = 0; n < 2; ++n) _Pragma("unroll") for (int k = 0; k < 2; ++k) \
;         acc[ai][bj][m][n] = __builtin_amdgcn_mfma_f32_16x16x32_bf16(Bt[n][k], At[m][k], acc[ai][bj][m][n], 0, 0, 0); __builtin_amdgcn_s_setprio(0); } while (0)
; #define PG8_WAIT_V(n) asm volatile("s_waitcnt vmcnt(" #n ")" ::: "memory")
; #define PG8_WAIT_L(n) asm volatile("s_waitcnt lgkmcnt(" #n ")" ::: "memory")
; #define PG8_BAR __builtin_amdgcn_s_barrier()
; #define PG8_SCHED __builtin_amdgcn_sched_barrier(0)
; template <class Epi, class Sched, bool ALIGN_EPI>
; __device__ __forceinline__ void gemm_phase(LAS unsigned char* lds, const Gemm g, const Sched& S, const Epi& E) {
;     ...
;             PG8_WAIT_V(8); PG8_WAIT_L(0); PG8_BAR; PG8_MMA(1, 0, At, B0); PG8_MMA(1, 1, At, B1); PG8_BAR; PG8_SCHED;
;             PG8_LDB(B0, 1, 0); PG8_LDB(B1, 1, 1); PG8_SCHED; PG8_LDA(At, 1, 0); PG8_STAGE(PG8_SA(0, 1), a2 + hstepA, voffA);
;             PG8_WAIT_V(8); PG8_WAIT_L(0); PG8_BAR; PG8_MMA(0, 0, At, B0); PG8_MMA(0, 1, At, B1); PG8_BAR; PG8_SCHED;
	s_setprio 1
	v_mfma_f32_16x16x32_bf16 v[56:59], v[154:157], v[186:189], v[56:59]
	v_mfma_f32_16x16x32_bf16 v[48:51], v[162:165], v[186:189], v[48:51]
	v_mfma_f32_16x16x32_bf16 v[40:43], v[154:157], v[194:197], v[40:43]
	v_mfma_f32_16x16x32_bf16 v[32:35], v[162:165], v[194:197], v[32:35]
	v_mfma_f32_16x16x32_bf16 v[24:27], v[154:157], v[202:205], v[24:27]
	v_mfma_f32_16x16x32_bf16 v[16:19], v[162:165], v[202:205], v[16:19]
	v_mfma_f32_16x16x32_bf16 v[8:11], v[154:157], v[210:213], v[8:11]
	v_mfma_f32_16x16x32_bf16 v[4:7], v[162:165], v[210:213], v[4:7]
	v_mfma_f32_16x16x32_bf16 v[56:59], v[158:161], v[190:193], v[56:59]
	v_mfma_f32_16x16x32_bf16 v[48:51], v[166:169], v[190:193], v[48:51]
	v_mfma_f32_16x16x32_bf16 v[40:43], v[158:161], v[198:201], v[40:43]
	v_mfma_f32_16x16x32_bf16 v[32:35], v[166:169], v[198:201], v[32:35]
	v_mfma_f32_16x16x32_bf16 v[24:27], v[158:161], v[206:209], v[24:27]
	v_mfma_f32_16x16x32_bf16 v[16:19], v[166:169], v[206:209], v[16:19]
	v_mfma_f32_16x16x32_bf16 v[8:11], v[158:161], v[214:217], v[8:11]
	v_mfma_f32_16x16x32_bf16 v[4:7], v[166:169], v[214:217], v[4:7]
	s_setprio 0
	s_setprio 1
	v_mfma_f32_16x16x32_bf16 v[60:63], v[170:173], v[186:189], v[60:63]
	v_mfma_f32_16x16x32_bf16 v[52:55], v[178:181], v[186:189], v[52:55]
	v_mfma_f32_16x16x32_bf16 v[44:47], v[170:173], v[194:197], v[44:47]
	v_mfma_f32_16x16x32_bf16 v[36:39], v[178:181], v[194:197], v[36:39]
	v_mfma_f32_16x16x32_bf16 v[28:31], v[170:173], v[202:205], v[28:31]
	v_mfma_f32_16x16x32_bf16 v[20:23], v[178:181], v[202:205], v[20:23]
	v_mfma_f32_16x16x32_bf16 v[12:15], v[170:173], v[210:213], v[12:15]
	v_mfma_f32_16x16x32_bf16 v[0:3], v[178:181], v[210:213], v[0:3]
	v_mfma_f32_16x16x32_bf16 v[60:63], v[174:177], v[190:193], v[60:63]
	v_mfma_f32_16x16x32_bf16 v[52:55], v[182:185], v[190:193], v[52:55]
	v_mfma_f32_16x16x32_bf16 v[44:47], v[174:177], v[198:201], v[44:47]
	v_mfma_f32_16x16x32_bf16 v[36:39], v[182:185], v[198:201], v[36:39]
	v_mfma_f32_16x16x32_bf16 v[28:31], v[174:177], v[206:209], v[28:31]
	v_mfma_f32_16x16x32_bf16 v[20:23], v[182:185], v[206:209], v[20:23]
	v_mfma_f32_16x16x32_bf16 v[12:15], v[174:177], v[214:217], v[12:15]
	v_mfma_f32_16x16x32_bf16 v[0:3], v[182:185], v[214:217], v[0:3]
	s_setprio 0
	s_barrier
	s_add_i32 s71, 0, 0x18000
	v_add_u32_e32 v136, s71, v147
	s_add_i32 s72, 0, 0x1c000
	ds_read_b128 v[154:157], v136
	ds_read_b128 v[158:161], v136 offset:1024
	ds_read_b128 v[162:165], v136 offset:2048
	ds_read_b128 v[166:169], v136 offset:3072
	v_add_u32_e32 v136, s72, v147
	ds_read_b128 v[170:173], v136
	ds_read_b128 v[174:177], v136 offset:1024
	ds_read_b128 v[178:181], v136 offset:2048
	ds_read_b128 v[182:185], v136 offset:3072
	s_add_u32 s48, s48, s24
	s_addc_u32 s49, s49, s25
	s_mov_b32 m0, s53
	v_lshl_add_u64 v[232:233], s[48:49], 0, v[134:135]
	ds_read_b128 v[186:189], v151 offset:32768
	ds_read_b128 v[190:193], v151 offset:33792
	ds_read_b128 v[194:197], v151 offset:34816
	ds_read_b128 v[198:201], v151 offset:35840
	ds_read_b128 v[202:205], v151 offset:36864
	ds_read_b128 v[206:209], v151 offset:37888
	ds_read_b128 v[210:213], v151 offset:38912
	ds_read_b128 v[214:217], v151 offset:39936
	global_load_lds_dwordx4 v[232:233], off
	v_lshl_add_u64 v[232:233], s[48:49], 0, v[130:131]
	s_mov_b32 m0, s54
	s_nop 0
	global_load_lds_dwordx4 v[232:233], off
	s_waitcnt vmcnt(8)
	s_waitcnt lgkmcnt(0)
	s_barrier
	s_setprio 1
	v_mfma_f32_16x16x32_bf16 v[116:119], v[154:157], v[186:189], v[116:119]
	v_mfma_f32_16x16x32_bf16 v[112:115], v[162:165], v[186:189], v[112:115]
	v_mfma_f32_16x16x32_bf16 v[104:107], v[154:157], v[194:197], v[104:107]
	v_mfma_f32_16x16x32_bf16 v[96:99], v[162:165], v[194:197], v[96:99]
	v_mfma_f32_16x16x32_bf16 v[88:91], v[154:157], v[202:205], v[88:91]
	v_mfma_f32_16x16x32_bf16 v[80:83], v[162:165], v[202:205], v[80:83]
	v_mfma_f32_16x16x32_bf16 v[72:75], v[154:157], v[210:213], v[72:75]
	v_mfma_f32_16x16x32_bf16 v[64:67], v[162:165], v[210:213], v[64:67]
	v_mfma_f32_16x16x32_bf16 v[116:119], v[158:161], v[190:193], v[116:119]
	v_mfma_f32_16x16x32_bf16 v[112:115], v[166:169], v[190:193], v[112:115]
	v_mfma_f32_16x16x32_bf16 v[104:107], v[158:161], v[198:201], v[104:107]
	v_mfma_f32_16x16x32_bf16 v[96:99], v[166:169], v[198:201], v[96:99]
	v_mfma_f32_16x16x32_bf16 v[88:91], v[158:161], v[206:209], v[88:91]
	v_mfma_f32_16x16x32_bf16 v[80:83], v[166:169], v[206:209], v[80:83]
	v_mfma_f32_16x16x32_bf16 v[72:75], v[158:161], v[214:217], v[72:75]
	v_mfma_f32_16x16x32_bf16 v[64:67], v[166:169], v[214:217], v[64:67]
	s_setprio 0
	s_setprio 1
	v_mfma_f32_16x16x32_bf16 v[124:127], v[170:173], v[186:189], v[124:127]
	v_mfma_f32_16x16x32_bf16 v[120:123], v[178:181], v[186:189], v[120:123]
	v_mfma_f32_16x16x32_bf16 v[108:111], v[170:173], v[194:197], v[108:111]
	v_mfma_f32_16x16x32_bf16 v[100:103], v[178:181], v[194:197], v[100:103]
	v_mfma_f32_16x16x32_bf16 v[92:95], v[170:173], v[202:205], v[92:95]
	v_mfma_f32_16x16x32_bf16 v[84:87], v[178:181], v[202:205], v[84:87]
	v_mfma_f32_16x16x32_bf16 v[76:79], v[170:173], v[210:213], v[76:79]
	v_mfma_f32_16x16x32_bf16 v[68:71], v[178:181], v[210:213], v[68:71]
	v_mfma_f32_16x16x32_bf16 v[124:127], v[174:177], v[190:193], v[124:127]
	v_mfma_f32_16x16x32_bf16 v[120:123], v[182:185], v[190:193], v[120:123]
	v_mfma_f32_16x16x32_bf16 v[108:111], v[174:177], v[198:201], v[108:111]
	v_mfma_f32_16x16x32_bf16 v[100:103], v[182:185], v[198:201], v[100:103]
	v_mfma_f32_16x16x32_bf16 v[92:95], v[174:177], v[206:209], v[92:95]
	v_mfma_f32_16x16x32_bf16 v[84:87], v[182:185], v[206:209], v[84:87]
	v_mfma_f32_16x16x32_bf16 v[76:79], v[174:177], v[214:217], v[76:79]
	v_mfma_f32_16x16x32_bf16 v[68:71], v[182:185], v[214:217], v[68:71]
	s_setprio 0
	s_barrier
; #define PG8_STAGE(bufoff, gbase, voff) do { _Pragma("unroll") for (int _i = 0; _i < 2; ++_i) \
;         __builtin_amdgcn_global_load_lds((const unsigned*)((const char*)(gbase) + (voff)[_i]), (LAS unsigned*)(lds + (bufoff) + ldsw + _i * 8192), 16, 0, 0); } while (0)
; #define PG8_LDA(dst, b, h) do { _Pragma("unroll") for (int m = 0; m < 4; ++m) _Pragma("unroll") for (int k = 0; k < 2; ++k) dst[m][k] = *(const LAS bf16x8*)(lds + PG8_SA(b, h) + aoff + m * 2048 + k * 1024); } while (0)
; #define PG8_MMA(ai, bj, At, Bt) do { __builtin_amdgcn_s_setprio(1); _Pragma("unroll") for (int m = 0; m < 4; ++m) _Pragma("unroll") for (int n = 0; n < 2; ++n) _Pragma("unroll") for (int k = 0; k < 2; ++k) \
;         acc[ai][bj][m][n] = __builtin_amdgcn_mfma_f32_16x16x32_bf16(Bt[n][k], At[m][k], acc[ai][bj][m][n], 0, 0, 0); __builtin_amdgcn_s_setprio(0); } while (0)
; #define PG8_WAIT_V(n) asm volatile("s_waitcnt vmcnt(" #n ")" ::: "memory")
; #define PG8_WAIT_L(n) asm volatile("s_waitcnt lgkmcnt(" #n ")" ::: "memory")
; #define PG8_BAR __builtin_amdgcn_s_barrier()
; #define PG8_SCHED __builtin_amdgcn_sched_barrier(0)
; template <class Epi, class Sched, bool ALIGN_EPI>
; __device__ __forceinline__ void gemm_phase(LAS unsigned char* lds, const Gemm g, const Sched& S, const Epi& E) {
;     ...
;             PG8_LDA(At, 1, 1); PG8_STAGE(PG8_SB(1, 0), b3, voffB); PG8_STAGE(PG8_SB(1, 1), b3 + hstepB, voffB); PG8_STAGE(PG8_SA(1, 0), a3, voffA);
;             PG8_WAIT_V(8); PG8_WAIT_L(0); PG8_BAR; PG8_MMA(1, 0, At, B0); PG8_MMA(1, 1, At, B1); PG8_BAR; PG8_SCHED;
;         }
	s_add_i32 s48, s71, s33
	v_lshl_add_u64 v[220:221], v[220:221], 0, s[30:31]
	s_mov_b32 m0, s48
	ds_read_b128 v[186:189], v151 offset:49152
	ds_read_b128 v[190:193], v151 offset:50176
	ds_read_b128 v[194:197], v151 offset:51200
	ds_read_b128 v[198:201], v151 offset:52224
	ds_read_b128 v[202:205], v151 offset:53248
	ds_read_b128 v[206:209], v151 offset:54272
	ds_read_b128 v[210:213], v151 offset:55296
	ds_read_b128 v[214:217], v151 offset:56320
	global_load_lds_dwordx4 v[220:221], off
	v_lshl_add_u64 v[220:221], v[222:223], 0, s[30:31]
	s_add_i32 m0, s48, 0x2000
	s_add_i32 s48, s72, s33
	global_load_lds_dwordx4 v[220:221], off
	v_lshl_add_u64 v[220:221], v[224:225], 0, s[30:31]
	s_mov_b32 m0, s48
	s_nop 0
	global_load_lds_dwordx4 v[220:221], off
	v_lshl_add_u64 v[220:221], v[226:227], 0, s[30:31]
	s_add_i32 m0, s48, 0x2000
	s_nop 0
	global_load_lds_dwordx4 v[220:221], off
	v_lshl_add_u64 v[220:221], v[228:229], 0, s[30:31]
	s_mov_b32 m0, s56
	s_nop 0
	global_load_lds_dwordx4 v[220:221], off
	v_lshl_add_u64 v[220:221], v[230:231], 0, s[30:31]
	s_mov_b32 m0, s57
	s_nop 0
	global_load_lds_dwordx4 v[220:221], off
	s_waitcnt vmcnt(8)
	s_waitcnt lgkmcnt(0)
	s_barrier
	s_setprio 1
	v_mfma_f32_16x16x32_bf16 v[56:59], v[154:157], v[186:189], v[56:59]
	v_mfma_f32_16x16x32_bf16 v[48:51], v[162:165], v[186:189], v[48:51]
	v_mfma_f32_16x16x32_bf16 v[40:43], v[154:157], v[194:197], v[40:43]
	v_mfma_f32_16x16x32_bf16 v[32:35], v[162:165], v[194:197], v[32:35]
	v_mfma_f32_16x16x32_bf16 v[24:27], v[154:157], v[202:205], v[24:27]
	v_mfma_f32_16x16x32_bf16 v[16:19], v[162:165], v[202:205], v[16:19]
	v_mfma_f32_16x16x32_bf16 v[8:11], v[154:157], v[210:213], v[8:11]
	v_mfma_f32_16x16x32_bf16 v[4:7], v[162:165], v[210:213], v[4:7]
	v_mfma_f32_16x16x32_bf16 v[56:59], v[158:161], v[190:193], v[56:59]
	v_mfma_f32_16x16x32_bf16 v[48:51], v[166:169], v[190:193], v[48:51]
	v_mfma_f32_16x16x32_bf16 v[40:43], v[158:161], v[198:201], v[40:43]
	v_mfma_f32_16x16x32_bf16 v[32:35], v[166:169], v[198:201], v[32:35]
	v_mfma_f32_16x16x32_bf16 v[24:27], v[158:161], v[206:209], v[24:27]
	v_mfma_f32_16x16x32_bf16 v[16:19], v[166:169], v[206:209], v[16:19]
	v_mfma_f32_16x16x32_bf16 v[8:11], v[158:161], v[214:217], v[8:11]
	v_mfma_f32_16x16x32_bf16 v[4:7], v[166:169], v[214:217], v[4:7]
	s_setprio 0
	s_setprio 1
	v_mfma_f32_16x16x32_bf16 v[60:63], v[170:173], v[186:189], v[60:63]
	v_mfma_f32_16x16x32_bf16 v[52:55], v[178:181], v[186:189], v[52:55]
	v_mfma_f32_16x16x32_bf16 v[44:47], v[170:173], v[194:197], v[44:47]
	v_mfma_f32_16x16x32_bf16 v[36:39], v[178:181], v[194:197], v[36:39]
	v_mfma_f32_16x16x32_bf16 v[28:31], v[170:173], v[202:205], v[28:31]
	v_mfma_f32_16x16x32_bf16 v[20:23], v[178:181], v[202:205], v[20:23]
	v_mfma_f32_16x16x32_bf16 v[12:15], v[170:173], v[210:213], v[12:15]
	v_mfma_f32_16x16x32_bf16 v[0:3], v[178:181], v[210:213], v[0:3]
	v_mfma_f32_16x16x32_bf16 v[60:63], v[174:177], v[190:193], v[60:63]
	v_mfma_f32_16x16x32_bf16 v[52:55], v[182:185], v[190:193], v[52:55]
	v_mfma_f32_16x16x32_bf16 v[44:47], v[174:177], v[198:201], v[44:47]
	v_mfma_f32_16x16x32_bf16 v[36:39], v[182:185], v[198:201], v[36:39]
	v_mfma_f32_16x16x32_bf16 v[28:31], v[174:177], v[206:209], v[28:31]
	v_mfma_f32_16x16x32_bf16 v[20:23], v[182:185], v[206:209], v[20:23]
	v_mfma_f32_16x16x32_bf16 v[12:15], v[174:177], v[214:217], v[12:15]
	v_mfma_f32_16x16x32_bf16 v[0:3], v[182:185], v[214:217], v[0:3]
	s_setprio 0
	s_barrier
	s_add_u32 s68, s68, 0x100
	s_addc_u32 s69, s69, 0
	s_add_u32 s46, s46, 0x100
	s_addc_u32 s47, s47, 0
	s_cmp_ge_i32 s70, s58
	s_mov_b32 s48, s70
	s_cbranch_scc0 .LBB0_1149

; #define PG8_STAGE(bufoff, gbase, voff) do { _Pragma("unroll") for (int _i = 0; _i < 2; ++_i) \
;         __builtin_amdgcn_global_load_lds((const unsigned*)((const char*)(gbase) + (voff)[_i]), (LAS unsigned*)(lds + (bufoff) + ldsw + _i * 8192), 16, 0, 0); } while (0)
; #define PG8_LDA(dst, b, h) do { _Pragma("unroll") for (int m = 0; m < 4; ++m) _Pragma("unroll") for (int k = 0; k < 2; ++k) dst[m][k] = *(const LAS bf16x8*)(lds + PG8_SA(b, h) + aoff + m * 2048 + k * 1024); } while (0)
; #define PG8_LDB(dst, b, h) do { _Pragma("unroll") for (int n = 0; n < 2; ++n) _Pragma("unroll") for (int k = 0; k < 2; ++k) dst[n][k] = *(const LAS bf16x8*)(lds + PG8_SB(b, h) + boff + n * 2048 + k * 1024); } while (0)
; #define PG8_MMA(ai, bj, At, Bt) do { __builtin_amdgcn_s_setprio(1); _Pragma("unroll") for (int m = 0; m < 4; ++m) _Pragma("unroll") for (int n = 0; n < 2; ++n) _Pragma("unroll") for (int k = 0; k < 2; ++k) \
;         acc[ai][bj][m][n] = __builtin_amdgcn_mfma_f32_16x16x32_bf16(Bt[n][k], At[m][k], acc[ai][bj][m][n], 0, 0, 0); __builtin_amdgcn_s_setprio(0); } while (0)
; #define PG8_WAIT_V(n) asm volatile("s_waitcnt vmcnt(" #n ")" ::: "memory")
; #define PG8_WAIT_L(n) asm volatile("s_waitcnt lgkmcnt(" #n ")" ::: "memory")
; #define PG8_BAR __builtin_amdgcn_s_barrier()
; #define PG8_SCHED __builtin_amdgcn_sched_barrier(0)
; template <class Epi, class Sched, bool ALIGN_EPI>
; __device__ __forceinline__ void gemm_phase(LAS unsigned char* lds, const Gemm g, const Sched& S, const Epi& E) {
;     ...
;         for (int t = 0; t < nt; t += 2) {
;             const bool last = (t == nt - 2);
;             const char* a1 = cA + (size_t)(t + 1) * kstep;
;             const char* a2 = last ? nA : cA + (size_t)(t + 2) * kstep; const char* b2 = last ? nB : cB + (size_t)(t + 2) * kstep;
;             const char* a3 = a2 + kstep; const char* b3 = b2 + kstep;
;             PG8_LDB(B0, 0, 0); PG8_LDB(B1, 0, 1); PG8_SCHED; PG8_LDA(At, 0, 0); PG8_STAGE(PG8_SA(1, 1), a1 + hstepA, voffA);
;             PG8_WAIT_V(8); PG8_WAIT_L(0); PG8_BAR; PG8_MMA(0, 0, At, B0); PG8_MMA(0, 1, At, B1); PG8_BAR; PG8_SCHED;
;             PG8_LDA(At, 0, 1); PG8_STAGE(PG8_SB(0, 0), b2, voffB); PG8_STAGE(PG8_SB(0, 1), b2 + hstepB, voffB); PG8_STAGE(PG8_SA(0, 0), a2, voffA);
;             PG8_WAIT_V(8); PG8_WAIT_L(0); PG8_BAR; PG8_MMA(1, 0, At, B0); PG8_MMA(1, 1, At, B1); PG8_BAR; PG8_SCHED;
.LBB0_1231:
	ds_read_b128 v[128:131], v209
	ds_read_b128 v[132:135], v209 offset:1024
	ds_read_b128 v[136:139], v209 offset:2048
	ds_read_b128 v[140:143], v209 offset:3072
	ds_read_b128 v[144:147], v210
	ds_read_b128 v[148:151], v210 offset:1024
	ds_read_b128 v[152:155], v210 offset:2048
	ds_read_b128 v[156:159], v210 offset:3072
	s_add_i32 s65, s44, 2
	s_add_u32 s66, s42, 0x80
	s_addc_u32 s45, s43, 0
	s_cmp_eq_u32 s54, s44
	s_cselect_b32 s44, s4, s66
	s_cselect_b32 s45, s5, s45
	s_cselect_b32 s67, s41, s64
	s_cselect_b32 s66, s40, s63
	v_lshl_add_u64 v[220:221], s[42:43], 0, v[194:195]
	s_add_i32 m0, s46, 0xc000
	ds_read_b128 v[160:163], v211
	ds_read_b128 v[164:167], v211 offset:1024
	ds_read_b128 v[168:171], v211 offset:2048
	ds_read_b128 v[172:175], v211 offset:3072
	ds_read_b128 v[176:179], v211 offset:4096
	ds_read_b128 v[180:183], v211 offset:5120
	ds_read_b128 v[202:205], v211 offset:6144
	ds_read_b128 v[214:217], v211 offset:7168
	global_load_lds_dwordx4 v[220:221], off
	v_lshl_add_u64 v[220:221], s[42:43], 0, v[196:197]
	s_add_i32 m0, s46, 0xe000
	s_nop 0
	global_load_lds_dwordx4 v[220:221], off
	s_waitcnt vmcnt(8)
	s_waitcnt lgkmcnt(0)
	s_barrier
	s_setprio 1
	v_mfma_f32_16x16x32_bf16 v[124:127], v[128:131], v[160:163], v[124:127]
	v_mfma_f32_16x16x32_bf16 v[120:123], v[136:139], v[160:163], v[120:123]
	v_mfma_f32_16x16x32_bf16 v[108:111], v[128:131], v[168:171], v[108:111]
	v_mfma_f32_16x16x32_bf16 v[104:107], v[136:139], v[168:171], v[104:107]
	v_mfma_f32_16x16x32_bf16 v[92:95], v[128:131], v[176:179], v[92:95]
	v_mfma_f32_16x16x32_bf16 v[88:91], v[136:139], v[176:179], v[88:91]
	v_mfma_f32_16x16x32_bf16 v[76:79], v[128:131], v[202:205], v[76:79]
	v_mfma_f32_16x16x32_bf16 v[72:75], v[136:139], v[202:205], v[72:75]
	v_mfma_f32_16x16x32_bf16 v[124:127], v[132:135], v[164:167], v[124:127]
	v_mfma_f32_16x16x32_bf16 v[120:123], v[140:143], v[164:167], v[120:123]
	v_mfma_f32_16x16x32_bf16 v[108:111], v[132:135], v[172:175], v[108:111]
	v_mfma_f32_16x16x32_bf16 v[104:107], v[140:143], v[172:175], v[104:107]
	v_mfma_f32_16x16x32_bf16 v[92:95], v[132:135], v[180:183], v[92:95]
	v_mfma_f32_16x16x32_bf16 v[88:91], v[140:143], v[180:183], v[88:91]
	v_mfma_f32_16x16x32_bf16 v[76:79], v[132:135], v[214:217], v[76:79]
	v_mfma_f32_16x16x32_bf16 v[72:75], v[140:143], v[214:217], v[72:75]
	s_setprio 0
	s_setprio 1
	v_mfma_f32_16x16x32_bf16 v[116:119], v[144:147], v[160:163], v[116:119]
	v_mfma_f32_16x16x32_bf16 v[112:115], v[152:155], v[160:163], v[112:115]
	v_mfma_f32_16x16x32_bf16 v[100:103], v[144:147], v[168:171], v[100:103]
	v_mfma_f32_16x16x32_bf16 v[96:99], v[152:155], v[168:171], v[96:99]
	v_mfma_f32_16x16x32_bf16 v[84:87], v[144:147], v[176:179], v[84:87]
	v_mfma_f32_16x16x32_bf16 v[80:83], v[152:155], v[176:179], v[80:83]
	v_mfma_f32_16x16x32_bf16 v[68:71], v[144:147], v[202:205], v[68:71]
	v_mfma_f32_16x16x32_bf16 v[64:67], v[152:155], v[202:205], v[64:67]
	v_mfma_f32_16x16x32_bf16 v[116:119], v[148:151], v[164:167], v[116:119]
	v_mfma_f32_16x16x32_bf16 v[112:115], v[156:159], v[164:167], v[112:115]
	v_mfma_f32_16x16x32_bf16 v[100:103], v[148:151], v[172:175], v[100:103]
	v_mfma_f32_16x16x32_bf16 v[96:99], v[156:159], v[172:175], v[96:99]
	v_mfma_f32_16x16x32_bf16 v[84:87], v[148:151], v[180:183], v[84:87]
	v_mfma_f32_16x16x32_bf16 v[80:83], v[156:159], v[180:183], v[80:83]
	v_mfma_f32_16x16x32_bf16 v[68:71], v[148:151], v[214:217], v[68:71]
	v_mfma_f32_16x16x32_bf16 v[64:67], v[156:159], v[214:217], v[64:67]
	s_setprio 0
	s_barrier
	s_add_i32 s68, s57, s33
	v_lshl_add_u64 v[220:221], s[66:67], 0, v[186:187]
	s_mov_b32 m0, s68
	ds_read_b128 v[160:163], v211 offset:16384
	ds_read_b128 v[164:167], v211 offset:17408
	ds_read_b128 v[168:171], v211 offset:18432
	ds_read_b128 v[172:175], v211 offset:19456
	ds_read_b128 v[176:179], v211 offset:20480
	ds_read_b128 v[180:183], v211 offset:21504
	ds_read_b128 v[202:205], v211 offset:22528
	ds_read_b128 v[214:217], v211 offset:23552
	global_load_lds_dwordx4 v[220:221], off
	s_add_i32 m0, s68, 0x2000
	v_lshl_add_u64 v[222:223], s[66:67], 0, v[190:191]
	s_add_u32 s66, s66, s26
	s_addc_u32 s67, s67, s27
	s_add_i32 s68, s58, s33
	global_load_lds_dwordx4 v[222:223], off
	v_lshl_add_u64 v[224:225], s[66:67], 0, v[186:187]
	s_mov_b32 m0, s68
	v_lshl_add_u64 v[226:227], s[66:67], 0, v[190:191]
	global_load_lds_dwordx4 v[224:225], off
	s_add_i32 m0, s68, 0x2000
	v_lshl_add_u64 v[228:229], s[44:45], 0, v[184:185]
	global_load_lds_dwordx4 v[226:227], off
	s_mov_b32 m0, s46
	v_lshl_add_u64 v[230:231], s[44:45], 0, v[188:189]
	global_load_lds_dwordx4 v[228:229], off
	s_mov_b32 m0, s47
	s_nop 0
	global_load_lds_dwordx4 v[230:231], off
	s_waitcnt vmcnt(8)
	s_waitcnt lgkmcnt(0)
	s_barrier
; #define PG8_STAGE(bufoff, gbase, voff) do { _Pragma("unroll") for (int _i = 0; _i < 2; ++_i) \
;         __builtin_amdgcn_global_load_lds((const unsigned*)((const char*)(gbase) + (voff)[_i]), (LAS unsigned*)(lds + (bufoff) + ldsw + _i * 8192), 16, 0, 0); } while (0)
; #define PG8_LDA(dst, b, h) do { _Pragma("unroll") for (int m = 0; m < 4; ++m) _Pragma("unroll") for (int k = 0; k < 2; ++k) dst[m][k] = *(const LAS bf16x8*)(lds + PG8_SA(b, h) + aoff + m * 2048 + k * 1024); } while (0)
; #define PG8_LDB(dst, b, h) do { _Pragma("unroll") for (int n = 0; n < 2; ++n) _Pragma("unroll") for (int k = 0; k < 2; ++k) dst[n][k] = *(const LAS bf16x8*)(lds + PG8_SB(b, h) + boff + n * 2048 + k * 1024); } while (0)
; #define PG8_MMA(ai, bj, At, Bt) do { __builtin_amdgcn_s_setprio(1); _Pragma("unroll") for (int m = 0; m < 4; ++m) _Pragma("unroll") for (int n = 0; n < 2; ++n) _Pragma("unroll") for (int k = 0; k < 2; ++k) \
;         acc[ai][bj][m][n] = __builtin_amdgcn_mfma_f32_16x16x32_bf16(Bt[n][k], At[m][k], acc[ai][bj][m][n], 0, 0, 0); __builtin_amdgcn_s_setprio(0); } while (0)
; #define PG8_WAIT_V(n) asm volatile("s_waitcnt vmcnt(" #n ")" ::: "memory")
; #define PG8_WAIT_L(n) asm volatile("s_waitcnt lgkmcnt(" #n ")" ::: "memory")
; #define PG8_BAR __builtin_amdgcn_s_barrier()
; #define PG8_SCHED __builtin_amdgcn_sched_barrier(0)
; template <class Epi, class Sched, bool ALIGN_EPI>
; __device__ __forceinline__ void gemm_phase(LAS unsigned char* lds, const Gemm g, const Sched& S, const Epi& E) {
;     ...
;             PG8_WAIT_V(8); PG8_WAIT_L(0); PG8_BAR; PG8_MMA(1, 0, At, B0); PG8_MMA(1, 1, At, B1); PG8_BAR; PG8_SCHED;
;             PG8_LDB(B0, 1, 0); PG8_LDB(B1, 1, 1); PG8_SCHED; PG8_LDA(At, 1, 0); PG8_STAGE(PG8_SA(0, 1), a2 + hstepA, voffA);
;             PG8_WAIT_V(8); PG8_WAIT_L(0); PG8_BAR; PG8_MMA(0, 0, At, B0); PG8_MMA(0, 1, At, B1); PG8_BAR; PG8_SCHED;
	s_setprio 1
	v_mfma_f32_16x16x32_bf16 v[60:63], v[128:131], v[160:163], v[60:63]
	v_mfma_f32_16x16x32_bf16 v[56:59], v[136:139], v[160:163], v[56:59]
	v_mfma_f32_16x16x32_bf16 v[44:47], v[128:131], v[168:171], v[44:47]
	v_mfma_f32_16x16x32_bf16 v[40:43], v[136:139], v[168:171], v[40:43]
	v_mfma_f32_16x16x32_bf16 v[28:31], v[128:131], v[176:179], v[28:31]
	v_mfma_f32_16x16x32_bf16 v[24:27], v[136:139], v[176:179], v[24:27]
	v_mfma_f32_16x16x32_bf16 v[12:15], v[128:131], v[202:205], v[12:15]
	v_mfma_f32_16x16x32_bf16 v[8:11], v[136:139], v[202:205], v[8:11]
	v_mfma_f32_16x16x32_bf16 v[60:63], v[132:135], v[164:167], v[60:63]
	v_mfma_f32_16x16x32_bf16 v[56:59], v[140:143], v[164:167], v[56:59]
	v_mfma_f32_16x16x32_bf16 v[44:47], v[132:135], v[172:175], v[44:47]
	v_mfma_f32_16x16x32_bf16 v[40:43], v[140:143], v[172:175], v[40:43]
	v_mfma_f32_16x16x32_bf16 v[28:31], v[132:135], v[180:183], v[28:31]
	v_mfma_f32_16x16x32_bf16 v[24:27], v[140:143], v[180:183], v[24:27]
	v_mfma_f32_16x16x32_bf16 v[12:15], v[132:135], v[214:217], v[12:15]
	v_mfma_f32_16x16x32_bf16 v[8:11], v[140:143], v[214:217], v[8:11]
	s_setprio 0
	s_setprio 1
	v_mfma_f32_16x16x32_bf16 v[52:55], v[144:147], v[160:163], v[52:55]
	v_mfma_f32_16x16x32_bf16 v[48:51], v[152:155], v[160:163], v[48:51]
	v_mfma_f32_16x16x32_bf16 v[36:39], v[144:147], v[168:171], v[36:39]
	v_mfma_f32_16x16x32_bf16 v[32:35], v[152:155], v[168:171], v[32:35]
	v_mfma_f32_16x16x32_bf16 v[20:23], v[144:147], v[176:179], v[20:23]
	v_mfma_f32_16x16x32_bf16 v[16:19], v[152:155], v[176:179], v[16:19]
	v_mfma_f32_16x16x32_bf16 v[4:7], v[144:147], v[202:205], v[4:7]
	v_mfma_f32_16x16x32_bf16 v[0:3], v[152:155], v[202:205], v[0:3]
	v_mfma_f32_16x16x32_bf16 v[52:55], v[148:151], v[164:167], v[52:55]
	v_mfma_f32_16x16x32_bf16 v[48:51], v[156:159], v[164:167], v[48:51]
	v_mfma_f32_16x16x32_bf16 v[36:39], v[148:151], v[172:175], v[36:39]
	v_mfma_f32_16x16x32_bf16 v[32:35], v[156:159], v[172:175], v[32:35]
	v_mfma_f32_16x16x32_bf16 v[20:23], v[148:151], v[180:183], v[20:23]
	v_mfma_f32_16x16x32_bf16 v[16:19], v[156:159], v[180:183], v[16:19]
	v_mfma_f32_16x16x32_bf16 v[4:7], v[148:151], v[214:217], v[4:7]
	v_mfma_f32_16x16x32_bf16 v[0:3], v[156:159], v[214:217], v[0:3]
	s_setprio 0
	s_barrier
	s_add_i32 s66, 0, 0x18000
	s_add_i32 s67, 0, 0x1c000
	v_add_u32_e32 v140, s66, v207
	v_add_u32_e32 v156, s67, v207
	ds_read_b128 v[128:131], v140
	ds_read_b128 v[132:135], v140 offset:1024
	ds_read_b128 v[136:139], v140 offset:2048
	ds_read_b128 v[140:143], v140 offset:3072
	ds_read_b128 v[144:147], v156
	ds_read_b128 v[148:151], v156 offset:1024
	ds_read_b128 v[152:155], v156 offset:2048
	ds_read_b128 v[156:159], v156 offset:3072
	s_add_u32 s44, s44, s24
	s_addc_u32 s45, s45, s25
	s_mov_b32 m0, s48
	v_lshl_add_u64 v[232:233], s[44:45], 0, v[184:185]
	ds_read_b128 v[160:163], v211 offset:32768
	ds_read_b128 v[164:167], v211 offset:33792
	ds_read_b128 v[168:171], v211 offset:34816
	ds_read_b128 v[172:175], v211 offset:35840
	ds_read_b128 v[176:179], v211 offset:36864
	ds_read_b128 v[180:183], v211 offset:37888
	ds_read_b128 v[202:205], v211 offset:38912
	ds_read_b128 v[214:217], v211 offset:39936
	global_load_lds_dwordx4 v[232:233], off
	v_lshl_add_u64 v[232:233], s[44:45], 0, v[188:189]
	s_mov_b32 m0, s49
	s_nop 0
	global_load_lds_dwordx4 v[232:233], off
	s_waitcnt vmcnt(8)
	s_waitcnt lgkmcnt(0)
	s_barrier
	s_setprio 1
	v_mfma_f32_16x16x32_bf16 v[124:127], v[128:131], v[160:163], v[124:127]
	v_mfma_f32_16x16x32_bf16 v[120:123], v[136:139], v[160:163], v[120:123]
	v_mfma_f32_16x16x32_bf16 v[108:111], v[128:131], v[168:171], v[108:111]
	v_mfma_f32_16x16x32_bf16 v[104:107], v[136:139], v[168:171], v[104:107]
	v_mfma_f32_16x16x32_bf16 v[92:95], v[128:131], v[176:179], v[92:95]
	v_mfma_f32_16x16x32_bf16 v[88:91], v[136:139], v[176:179], v[88:91]
	v_mfma_f32_16x16x32_bf16 v[76:79], v[128:131], v[202:205], v[76:79]
	v_mfma_f32_16x16x32_bf16 v[72:75], v[136:139], v[202:205], v[72:75]
	v_mfma_f32_16x16x32_bf16 v[124:127], v[132:135], v[164:167], v[124:127]
	v_mfma_f32_16x16x32_bf16 v[120:123], v[140:143], v[164:167], v[120:123]
	v_mfma_f32_16x16x32_bf16 v[108:111], v[132:135], v[172:175], v[108:111]
	v_mfma_f32_16x16x32_bf16 v[104:107], v[140:143], v[172:175], v[104:107]
	v_mfma_f32_16x16x32_bf16 v[92:95], v[132:135], v[180:183], v[92:95]
	v_mfma_f32_16x16x32_bf16 v[88:91], v[140:143], v[180:183], v[88:91]
	v_mfma_f32_16x16x32_bf16 v[76:79], v[132:135], v[214:217], v[76:79]
	v_mfma_f32_16x16x32_bf16 v[72:75], v[140:143], v[214:217], v[72:75]
	s_setprio 0
	s_setprio 1
	v_mfma_f32_16x16x32_bf16 v[116:119], v[144:147], v[160:163], v[116:119]
	v_mfma_f32_16x16x32_bf16 v[112:115], v[152:155], v[160:163], v[112:115]
	v_mfma_f32_16x16x32_bf16 v[100:103], v[144:147], v[168:171], v[100:103]
	v_mfma_f32_16x16x32_bf16 v[96:99], v[152:155], v[168:171], v[96:99]
	v_mfma_f32_16x16x32_bf16 v[84:87], v[144:147], v[176:179], v[84:87]
	v_mfma_f32_16x16x32_bf16 v[80:83], v[152:155], v[176:179], v[80:83]
	v_mfma_f32_16x16x32_bf16 v[68:71], v[144:147], v[202:205], v[68:71]
	v_mfma_f32_16x16x32_bf16 v[64:67], v[152:155], v[202:205], v[64:67]
	v_mfma_f32_16x16x32_bf16 v[116:119], v[148:151], v[164:167], v[116:119]
	v_mfma_f32_16x16x32_bf16 v[112:115], v[156:159], v[164:167], v[112:115]
	v_mfma_f32_16x16x32_bf16 v[100:103], v[148:151], v[172:175], v[100:103]
	v_mfma_f32_16x16x32_bf16 v[96:99], v[156:159], v[172:175], v[96:99]
	v_mfma_f32_16x16x32_bf16 v[84:87], v[148:151], v[180:183], v[84:87]
	v_mfma_f32_16x16x32_bf16 v[80:83], v[156:159], v[180:183], v[80:83]
	v_mfma_f32_16x16x32_bf16 v[68:71], v[148:151], v[214:217], v[68:71]
	v_mfma_f32_16x16x32_bf16 v[64:67], v[156:159], v[214:217], v[64:67]
	s_setprio 0
	s_barrier
; #define PG8_STAGE(bufoff, gbase, voff) do { _Pragma("unroll") for (int _i = 0; _i < 2; ++_i) \
;         __builtin_amdgcn_global_load_lds((const unsigned*)((const char*)(gbase) + (voff)[_i]), (LAS unsigned*)(lds + (bufoff) + ldsw + _i * 8192), 16, 0, 0); } while (0)
; #define PG8_LDA(dst, b, h) do { _Pragma("unroll") for (int m = 0; m < 4; ++m) _Pragma("unroll") for (int k = 0; k < 2; ++k) dst[m][k] = *(const LAS bf16x8*)(lds + PG8_SA(b, h) + aoff + m * 2048 + k * 1024); } while (0)
; #define PG8_MMA(ai, bj, At, Bt) do { __builtin_amdgcn_s_setprio(1); _Pragma("unroll") for (int m = 0; m < 4; ++m) _Pragma("unroll") for (int n = 0; n < 2; ++n) _Pragma("unroll") for (int k = 0; k < 2; ++k) \
;         acc[ai][bj][m][n] = __builtin_amdgcn_mfma_f32_16x16x32_bf16(Bt[n][k], At[m][k], acc[ai][bj][m][n], 0, 0, 0); __builtin_amdgcn_s_setprio(0); } while (0)
; #define PG8_WAIT_V(n) asm volatile("s_waitcnt vmcnt(" #n ")" ::: "memory")
; #define PG8_WAIT_L(n) asm volatile("s_waitcnt lgkmcnt(" #n ")" ::: "memory")
; #define PG8_BAR __builtin_amdgcn_s_barrier()
; #define PG8_SCHED __builtin_amdgcn_sched_barrier(0)
; template <class Epi, class Sched, bool ALIGN_EPI>
; __device__ __forceinline__ void gemm_phase(LAS unsigned char* lds, const Gemm g, const Sched& S, const Epi& E) {
;     ...
;             PG8_LDA(At, 1, 1); PG8_STAGE(PG8_SB(1, 0), b3, voffB); PG8_STAGE(PG8_SB(1, 1), b3 + hstepB, voffB); PG8_STAGE(PG8_SA(1, 0), a3, voffA);
;             PG8_WAIT_V(8); PG8_WAIT_L(0); PG8_BAR; PG8_MMA(1, 0, At, B0); PG8_MMA(1, 1, At, B1); PG8_BAR; PG8_SCHED;
;         }
	s_add_i32 s44, s66, s33
	v_lshl_add_u64 v[220:221], v[220:221], 0, s[34:35]
	s_mov_b32 m0, s44
	ds_read_b128 v[160:163], v211 offset:49152
	ds_read_b128 v[164:167], v211 offset:50176
	ds_read_b128 v[168:171], v211 offset:51200
	ds_read_b128 v[172:175], v211 offset:52224
	ds_read_b128 v[176:179], v211 offset:53248
	ds_read_b128 v[180:183], v211 offset:54272
	ds_read_b128 v[202:205], v211 offset:55296
	ds_read_b128 v[214:217], v211 offset:56320
	global_load_lds_dwordx4 v[220:221], off
	v_lshl_add_u64 v[220:221], v[222:223], 0, s[34:35]
	s_add_i32 m0, s44, 0x2000
	s_add_i32 s44, s67, s33
	global_load_lds_dwordx4 v[220:221], off
	v_lshl_add_u64 v[220:221], v[224:225], 0, s[34:35]
	s_mov_b32 m0, s44
	s_nop 0
	global_load_lds_dwordx4 v[220:221], off
	v_lshl_add_u64 v[220:221], v[226:227], 0, s[34:35]
	s_add_i32 m0, s44, 0x2000
	s_nop 0
	global_load_lds_dwordx4 v[220:221], off
	v_lshl_add_u64 v[220:221], v[228:229], 0, s[34:35]
	s_mov_b32 m0, s52
	s_nop 0
	global_load_lds_dwordx4 v[220:221], off
	v_lshl_add_u64 v[220:221], v[230:231], 0, s[34:35]
	s_mov_b32 m0, s53
	s_nop 0
	global_load_lds_dwordx4 v[220:221], off
	s_waitcnt vmcnt(8)
	s_waitcnt lgkmcnt(0)
	s_barrier
	s_setprio 1
	v_mfma_f32_16x16x32_bf16 v[60:63], v[128:131], v[160:163], v[60:63]
	v_mfma_f32_16x16x32_bf16 v[56:59], v[136:139], v[160:163], v[56:59]
	v_mfma_f32_16x16x32_bf16 v[44:47], v[128:131], v[168:171], v[44:47]
	v_mfma_f32_16x16x32_bf16 v[40:43], v[136:139], v[168:171], v[40:43]
	v_mfma_f32_16x16x32_bf16 v[28:31], v[128:131], v[176:179], v[28:31]
	v_mfma_f32_16x16x32_bf16 v[24:27], v[136:139], v[176:179], v[24:27]
	v_mfma_f32_16x16x32_bf16 v[12:15], v[128:131], v[202:205], v[12:15]
	v_mfma_f32_16x16x32_bf16 v[8:11], v[136:139], v[202:205], v[8:11]
	v_mfma_f32_16x16x32_bf16 v[60:63], v[132:135], v[164:167], v[60:63]
	v_mfma_f32_16x16x32_bf16 v[56:59], v[140:143], v[164:167], v[56:59]
	v_mfma_f32_16x16x32_bf16 v[44:47], v[132:135], v[172:175], v[44:47]
	v_mfma_f32_16x16x32_bf16 v[40:43], v[140:143], v[172:175], v[40:43]
	v_mfma_f32_16x16x32_bf16 v[28:31], v[132:135], v[180:183], v[28:31]
	v_mfma_f32_16x16x32_bf16 v[24:27], v[140:143], v[180:183], v[24:27]
	v_mfma_f32_16x16x32_bf16 v[12:15], v[132:135], v[214:217], v[12:15]
	v_mfma_f32_16x16x32_bf16 v[8:11], v[140:143], v[214:217], v[8:11]
	s_setprio 0
	s_setprio 1
	v_mfma_f32_16x16x32_bf16 v[52:55], v[144:147], v[160:163], v[52:55]
	v_mfma_f32_16x16x32_bf16 v[48:51], v[152:155], v[160:163], v[48:51]
	v_mfma_f32_16x16x32_bf16 v[36:39], v[144:147], v[168:171], v[36:39]
	v_mfma_f32_16x16x32_bf16 v[32:35], v[152:155], v[168:171], v[32:35]
	v_mfma_f32_16x16x32_bf16 v[20:23], v[144:147], v[176:179], v[20:23]
	v_mfma_f32_16x16x32_bf16 v[16:19], v[152:155], v[176:179], v[16:19]
	v_mfma_f32_16x16x32_bf16 v[4:7], v[144:147], v[202:205], v[4:7]
	v_mfma_f32_16x16x32_bf16 v[0:3], v[152:155], v[202:205], v[0:3]
	v_mfma_f32_16x16x32_bf16 v[52:55], v[148:151], v[164:167], v[52:55]
	v_mfma_f32_16x16x32_bf16 v[48:51], v[156:159], v[164:167], v[48:51]
	v_mfma_f32_16x16x32_bf16 v[36:39], v[148:151], v[172:175], v[36:39]
	v_mfma_f32_16x16x32_bf16 v[32:35], v[156:159], v[172:175], v[32:35]
	v_mfma_f32_16x16x32_bf16 v[20:23], v[148:151], v[180:183], v[20:23]
	v_mfma_f32_16x16x32_bf16 v[16:19], v[156:159], v[180:183], v[16:19]
	v_mfma_f32_16x16x32_bf16 v[4:7], v[148:151], v[214:217], v[4:7]
	v_mfma_f32_16x16x32_bf16 v[0:3], v[156:159], v[214:217], v[0:3]
	s_setprio 0
	s_barrier
	s_add_u32 s63, s63, 0x100
	s_addc_u32 s64, s64, 0
	s_add_u32 s42, s42, 0x100
	s_addc_u32 s43, s43, 0
	s_cmp_ge_i32 s65, s51
	s_mov_b32 s44, s65
	s_cbranch_scc0 .LBB0_1231
